# v78 + K-loop load segments issue their LDS-DMA pieces (and feeding SALU) before the ds_reads (more lead before the closing vmcnt wait)
# speedup vs baseline: 1.0238x; 1.0047x over previous
.Lbal_first_21:
	s_add_u32 s26, s24, 0xfffc0080
	s_addc_u32 s27, s25, -1
	s_cmp_eq_u32 s55, 12
	s_cselect_b32 s29, s19, s27
	s_cselect_b32 s28, s51, s26
	s_cselect_b32 s27, s17, s54
	s_cselect_b32 s26, s52, s53
	s_add_i32 m0, s38, 0xc000
	s_nop 0
	global_load_lds_dwordx4 v138, s[24:25]
	s_add_i32 m0, s38, 0xe000
	s_nop 0
	global_load_lds_dwordx4 v136, s[24:25]
	ds_read_b128 v[144:147], v151
	ds_read_b128 v[156:159], v151 offset:1024
	ds_read_b128 v[160:163], v151 offset:2048
	ds_read_b128 v[164:167], v151 offset:3072
	ds_read_b128 v[168:171], v152
	ds_read_b128 v[172:175], v152 offset:1024
	ds_read_b128 v[176:179], v152 offset:2048
	ds_read_b128 v[180:183], v152 offset:3072
	ds_read_b128 v[184:187], v153
	ds_read_b128 v[188:191], v153 offset:1024
	ds_read_b128 v[192:195], v153 offset:2048
	ds_read_b128 v[196:199], v153 offset:3072
	ds_read_b128 v[200:203], v153 offset:4096
	ds_read_b128 v[208:211], v153 offset:5120
	ds_read_b128 v[212:215], v153 offset:6144
	ds_read_b128 v[216:219], v153 offset:7168
	s_waitcnt vmcnt(8)
	s_waitcnt lgkmcnt(0)
	s_barrier
	s_waitcnt lgkmcnt(0)
	v_mfma_f32_16x16x32_bf16 v[124:127], v[144:147], v[184:187], v[124:127]
	v_mfma_f32_16x16x32_bf16 v[120:123], v[160:163], v[184:187], v[120:123]
	v_mfma_f32_16x16x32_bf16 v[108:111], v[144:147], v[192:195], v[108:111]
	v_mfma_f32_16x16x32_bf16 v[104:107], v[160:163], v[192:195], v[104:107]
	v_mfma_f32_16x16x32_bf16 v[92:95], v[144:147], v[200:203], v[92:95]
	v_mfma_f32_16x16x32_bf16 v[88:91], v[160:163], v[200:203], v[88:91]
	v_mfma_f32_16x16x32_bf16 v[76:79], v[144:147], v[212:215], v[76:79]
	v_mfma_f32_16x16x32_bf16 v[72:75], v[160:163], v[212:215], v[72:75]
	v_mfma_f32_16x16x32_bf16 v[124:127], v[156:159], v[188:191], v[124:127]
	v_mfma_f32_16x16x32_bf16 v[120:123], v[164:167], v[188:191], v[120:123]
	v_mfma_f32_16x16x32_bf16 v[108:111], v[156:159], v[196:199], v[108:111]
	v_mfma_f32_16x16x32_bf16 v[104:107], v[164:167], v[196:199], v[104:107]
	v_mfma_f32_16x16x32_bf16 v[92:95], v[156:159], v[208:211], v[92:95]
	v_mfma_f32_16x16x32_bf16 v[88:91], v[164:167], v[208:211], v[88:91]
	v_mfma_f32_16x16x32_bf16 v[76:79], v[156:159], v[216:219], v[76:79]
	v_mfma_f32_16x16x32_bf16 v[72:75], v[164:167], v[216:219], v[72:75]
	v_mfma_f32_16x16x32_bf16 v[116:119], v[168:171], v[184:187], v[116:119]
	v_mfma_f32_16x16x32_bf16 v[112:115], v[176:179], v[184:187], v[112:115]
	v_mfma_f32_16x16x32_bf16 v[100:103], v[168:171], v[192:195], v[100:103]
	v_mfma_f32_16x16x32_bf16 v[96:99], v[176:179], v[192:195], v[96:99]
	v_mfma_f32_16x16x32_bf16 v[84:87], v[168:171], v[200:203], v[84:87]
	v_mfma_f32_16x16x32_bf16 v[80:83], v[176:179], v[200:203], v[80:83]
	v_mfma_f32_16x16x32_bf16 v[68:71], v[168:171], v[212:215], v[68:71]
	v_mfma_f32_16x16x32_bf16 v[64:67], v[176:179], v[212:215], v[64:67]
	v_mfma_f32_16x16x32_bf16 v[116:119], v[172:175], v[188:191], v[116:119]
	v_mfma_f32_16x16x32_bf16 v[112:115], v[180:183], v[188:191], v[112:115]
	v_mfma_f32_16x16x32_bf16 v[100:103], v[172:175], v[196:199], v[100:103]
	v_mfma_f32_16x16x32_bf16 v[96:99], v[180:183], v[196:199], v[96:99]
	v_mfma_f32_16x16x32_bf16 v[84:87], v[172:175], v[208:211], v[84:87]
	v_mfma_f32_16x16x32_bf16 v[80:83], v[180:183], v[208:211], v[80:83]
	v_mfma_f32_16x16x32_bf16 v[68:71], v[172:175], v[216:219], v[68:71]
	v_mfma_f32_16x16x32_bf16 v[64:67], v[180:183], v[216:219], v[64:67]
	s_barrier
	s_add_i32 s56, s48, s35
	s_mov_b32 m0, s56
	s_nop 0
	global_load_lds_dwordx4 v132, s[26:27]
	s_add_i32 m0, s56, 0x2000
	s_add_u32 s56, s26, 0x40000
	s_mov_b64 s[98:99], s[26:27]
	s_addc_u32 s57, s27, 0
	s_add_i32 s58, s49, s35
	global_load_lds_dwordx4 v128, s[26:27]
	s_mov_b32 m0, s58
	s_mov_b64 s[100:101], s[28:29]
	global_load_lds_dwordx4 v132, s[56:57]
	s_add_i32 m0, s58, 0x2000
	s_nop 0
	global_load_lds_dwordx4 v128, s[56:57]
	ds_read_b128 v[184:187], v153 offset:16384
	ds_read_b128 v[188:191], v153 offset:17408
	ds_read_b128 v[192:195], v153 offset:18432
	ds_read_b128 v[196:199], v153 offset:19456
	ds_read_b128 v[200:203], v153 offset:20480
	ds_read_b128 v[208:211], v153 offset:21504
	ds_read_b128 v[212:215], v153 offset:22528
	ds_read_b128 v[216:219], v153 offset:23552
	s_waitcnt vmcnt(6)
	s_waitcnt lgkmcnt(0)
	s_barrier
	s_waitcnt lgkmcnt(0)
	v_mfma_f32_16x16x32_bf16 v[60:63], v[144:147], v[184:187], v[60:63]
	v_mfma_f32_16x16x32_bf16 v[56:59], v[160:163], v[184:187], v[56:59]
	v_mfma_f32_16x16x32_bf16 v[44:47], v[144:147], v[192:195], v[44:47]
	v_mfma_f32_16x16x32_bf16 v[40:43], v[160:163], v[192:195], v[40:43]
	v_mfma_f32_16x16x32_bf16 v[28:31], v[144:147], v[200:203], v[28:31]
	v_mfma_f32_16x16x32_bf16 v[24:27], v[160:163], v[200:203], v[24:27]
	v_mfma_f32_16x16x32_bf16 v[12:15], v[144:147], v[212:215], v[12:15]
	v_mfma_f32_16x16x32_bf16 v[8:11], v[160:163], v[212:215], v[8:11]
	v_mfma_f32_16x16x32_bf16 v[60:63], v[156:159], v[188:191], v[60:63]
	v_mfma_f32_16x16x32_bf16 v[56:59], v[164:167], v[188:191], v[56:59]
	v_mfma_f32_16x16x32_bf16 v[44:47], v[156:159], v[196:199], v[44:47]
	v_mfma_f32_16x16x32_bf16 v[40:43], v[164:167], v[196:199], v[40:43]
	v_mfma_f32_16x16x32_bf16 v[28:31], v[156:159], v[208:211], v[28:31]
	v_mfma_f32_16x16x32_bf16 v[24:27], v[164:167], v[208:211], v[24:27]
	v_mfma_f32_16x16x32_bf16 v[12:15], v[156:159], v[216:219], v[12:15]
	v_mfma_f32_16x16x32_bf16 v[8:11], v[164:167], v[216:219], v[8:11]
	v_mfma_f32_16x16x32_bf16 v[52:55], v[168:171], v[184:187], v[52:55]
	v_mfma_f32_16x16x32_bf16 v[48:51], v[176:179], v[184:187], v[48:51]
	v_mfma_f32_16x16x32_bf16 v[36:39], v[168:171], v[192:195], v[36:39]
	v_mfma_f32_16x16x32_bf16 v[32:35], v[176:179], v[192:195], v[32:35]
	v_mfma_f32_16x16x32_bf16 v[20:23], v[168:171], v[200:203], v[20:23]
	v_mfma_f32_16x16x32_bf16 v[16:19], v[176:179], v[200:203], v[16:19]
	v_mfma_f32_16x16x32_bf16 v[4:7], v[168:171], v[212:215], v[4:7]
	v_mfma_f32_16x16x32_bf16 v[0:3], v[176:179], v[212:215], v[0:3]
	v_mfma_f32_16x16x32_bf16 v[52:55], v[172:175], v[188:191], v[52:55]
	v_mfma_f32_16x16x32_bf16 v[48:51], v[180:183], v[188:191], v[48:51]
	v_mfma_f32_16x16x32_bf16 v[36:39], v[172:175], v[196:199], v[36:39]
	v_mfma_f32_16x16x32_bf16 v[32:35], v[180:183], v[196:199], v[32:35]
	v_mfma_f32_16x16x32_bf16 v[20:23], v[172:175], v[208:211], v[20:23]
	v_mfma_f32_16x16x32_bf16 v[16:19], v[180:183], v[208:211], v[16:19]
	v_mfma_f32_16x16x32_bf16 v[4:7], v[172:175], v[216:219], v[4:7]
	v_mfma_f32_16x16x32_bf16 v[0:3], v[180:183], v[216:219], v[0:3]
	s_barrier
	s_mov_b32 m0, s38
	s_nop 0
	global_load_lds_dwordx4 v134, s[28:29]
	s_mov_b32 m0, s39
	s_nop 0
	global_load_lds_dwordx4 v130, s[28:29]
	s_add_i32 s56, 0, 0x18000
	s_add_i32 s57, 0, 0x1c000
	s_add_u32 s28, s28, 0x40000
	s_addc_u32 s29, s29, 0
	s_mov_b32 m0, s40
	s_nop 0
	global_load_lds_dwordx4 v134, s[28:29]
	s_mov_b32 m0, s41
	s_nop 0
	global_load_lds_dwordx4 v130, s[28:29]
	v_add_u32_e32 v164, s56, v149
	v_add_u32_e32 v180, s57, v149
	ds_read_b128 v[144:147], v164
	ds_read_b128 v[156:159], v164 offset:1024
	ds_read_b128 v[160:163], v164 offset:2048
	ds_read_b128 v[164:167], v164 offset:3072
	ds_read_b128 v[168:171], v180
	ds_read_b128 v[172:175], v180 offset:1024
	ds_read_b128 v[176:179], v180 offset:2048
	ds_read_b128 v[180:183], v180 offset:3072
	ds_read_b128 v[184:187], v153 offset:32768
	ds_read_b128 v[188:191], v153 offset:33792
	ds_read_b128 v[192:195], v153 offset:34816
	ds_read_b128 v[196:199], v153 offset:35840
	ds_read_b128 v[200:203], v153 offset:36864
	ds_read_b128 v[208:211], v153 offset:37888
	ds_read_b128 v[212:215], v153 offset:38912
	ds_read_b128 v[216:219], v153 offset:39936
	s_waitcnt vmcnt(8)
	s_waitcnt lgkmcnt(0)
	s_barrier
	s_waitcnt lgkmcnt(0)
	v_mfma_f32_16x16x32_bf16 v[124:127], v[144:147], v[184:187], v[124:127]
	v_mfma_f32_16x16x32_bf16 v[120:123], v[160:163], v[184:187], v[120:123]
	v_mfma_f32_16x16x32_bf16 v[108:111], v[144:147], v[192:195], v[108:111]
	v_mfma_f32_16x16x32_bf16 v[104:107], v[160:163], v[192:195], v[104:107]
	v_mfma_f32_16x16x32_bf16 v[92:95], v[144:147], v[200:203], v[92:95]
	v_mfma_f32_16x16x32_bf16 v[88:91], v[160:163], v[200:203], v[88:91]
	v_mfma_f32_16x16x32_bf16 v[76:79], v[144:147], v[212:215], v[76:79]
	v_mfma_f32_16x16x32_bf16 v[72:75], v[160:163], v[212:215], v[72:75]
	v_mfma_f32_16x16x32_bf16 v[124:127], v[156:159], v[188:191], v[124:127]
	v_mfma_f32_16x16x32_bf16 v[120:123], v[164:167], v[188:191], v[120:123]
	v_mfma_f32_16x16x32_bf16 v[108:111], v[156:159], v[196:199], v[108:111]
	v_mfma_f32_16x16x32_bf16 v[104:107], v[164:167], v[196:199], v[104:107]
	v_mfma_f32_16x16x32_bf16 v[92:95], v[156:159], v[208:211], v[92:95]
	v_mfma_f32_16x16x32_bf16 v[88:91], v[164:167], v[208:211], v[88:91]
	v_mfma_f32_16x16x32_bf16 v[76:79], v[156:159], v[216:219], v[76:79]
	v_mfma_f32_16x16x32_bf16 v[72:75], v[164:167], v[216:219], v[72:75]
	v_mfma_f32_16x16x32_bf16 v[116:119], v[168:171], v[184:187], v[116:119]
	v_mfma_f32_16x16x32_bf16 v[112:115], v[176:179], v[184:187], v[112:115]
	v_mfma_f32_16x16x32_bf16 v[100:103], v[168:171], v[192:195], v[100:103]
	v_mfma_f32_16x16x32_bf16 v[96:99], v[176:179], v[192:195], v[96:99]
	v_mfma_f32_16x16x32_bf16 v[84:87], v[168:171], v[200:203], v[84:87]
	v_mfma_f32_16x16x32_bf16 v[80:83], v[176:179], v[200:203], v[80:83]
	v_mfma_f32_16x16x32_bf16 v[68:71], v[168:171], v[212:215], v[68:71]
	v_mfma_f32_16x16x32_bf16 v[64:67], v[176:179], v[212:215], v[64:67]
	v_mfma_f32_16x16x32_bf16 v[116:119], v[172:175], v[188:191], v[116:119]
	v_mfma_f32_16x16x32_bf16 v[112:115], v[180:183], v[188:191], v[112:115]
	v_mfma_f32_16x16x32_bf16 v[100:103], v[172:175], v[196:199], v[100:103]
	v_mfma_f32_16x16x32_bf16 v[96:99], v[180:183], v[196:199], v[96:99]
	v_mfma_f32_16x16x32_bf16 v[84:87], v[172:175], v[208:211], v[84:87]
	v_mfma_f32_16x16x32_bf16 v[80:83], v[180:183], v[208:211], v[80:83]
	v_mfma_f32_16x16x32_bf16 v[68:71], v[172:175], v[216:219], v[68:71]
	v_mfma_f32_16x16x32_bf16 v[64:67], v[180:183], v[216:219], v[64:67]
	s_barrier
	s_add_i32 s28, s56, s35
	s_mov_b32 m0, s28
	s_nop 0
	global_load_lds_dwordx4 v220, s[26:27]
	s_add_i32 m0, s28, 0x2000
	s_add_u32 s26, s26, 0x40080
	s_addc_u32 s27, s27, 0
	s_add_i32 s28, s57, s35
	global_load_lds_dwordx4 v204, s[98:99]
	s_mov_b32 m0, s28
	s_nop 0
	global_load_lds_dwordx4 v132, s[26:27]
	s_add_i32 m0, s28, 0x2000
	s_nop 0
	global_load_lds_dwordx4 v128, s[26:27]
	s_cmp_lg_u32 s55, 12
	s_cbranch_scc1 .Lbal_last_21
	s_mov_b32 m0, s45
	s_nop 0
	global_load_lds_dwordx4 v221, s[100:101]
	s_mov_b32 m0, s46
	s_nop 0
	global_load_lds_dwordx4 v205, s[100:101]
.Lbal_last_21:
	ds_read_b128 v[184:187], v153 offset:49152
	ds_read_b128 v[188:191], v153 offset:50176
	ds_read_b128 v[192:195], v153 offset:51200
	ds_read_b128 v[196:199], v153 offset:52224
	ds_read_b128 v[200:203], v153 offset:53248
	ds_read_b128 v[208:211], v153 offset:54272
	ds_read_b128 v[212:215], v153 offset:55296
	ds_read_b128 v[216:219], v153 offset:56320
	s_waitcnt vmcnt(6)
	s_waitcnt lgkmcnt(0)
	s_barrier
	s_waitcnt lgkmcnt(0)
	v_mfma_f32_16x16x32_bf16 v[60:63], v[144:147], v[184:187], v[60:63]
	v_mfma_f32_16x16x32_bf16 v[56:59], v[160:163], v[184:187], v[56:59]
	v_mfma_f32_16x16x32_bf16 v[44:47], v[144:147], v[192:195], v[44:47]
	v_mfma_f32_16x16x32_bf16 v[40:43], v[160:163], v[192:195], v[40:43]
	v_mfma_f32_16x16x32_bf16 v[28:31], v[144:147], v[200:203], v[28:31]
	v_mfma_f32_16x16x32_bf16 v[24:27], v[160:163], v[200:203], v[24:27]
	v_mfma_f32_16x16x32_bf16 v[12:15], v[144:147], v[212:215], v[12:15]
	v_mfma_f32_16x16x32_bf16 v[8:11], v[160:163], v[212:215], v[8:11]
	v_mfma_f32_16x16x32_bf16 v[60:63], v[156:159], v[188:191], v[60:63]
	v_mfma_f32_16x16x32_bf16 v[56:59], v[164:167], v[188:191], v[56:59]
	v_mfma_f32_16x16x32_bf16 v[44:47], v[156:159], v[196:199], v[44:47]
	v_mfma_f32_16x16x32_bf16 v[40:43], v[164:167], v[196:199], v[40:43]
	v_mfma_f32_16x16x32_bf16 v[28:31], v[156:159], v[208:211], v[28:31]
	v_mfma_f32_16x16x32_bf16 v[24:27], v[164:167], v[208:211], v[24:27]
	v_mfma_f32_16x16x32_bf16 v[12:15], v[156:159], v[216:219], v[12:15]
	v_mfma_f32_16x16x32_bf16 v[8:11], v[164:167], v[216:219], v[8:11]
	v_mfma_f32_16x16x32_bf16 v[52:55], v[168:171], v[184:187], v[52:55]
	v_mfma_f32_16x16x32_bf16 v[48:51], v[176:179], v[184:187], v[48:51]
	v_mfma_f32_16x16x32_bf16 v[36:39], v[168:171], v[192:195], v[36:39]
	v_mfma_f32_16x16x32_bf16 v[32:35], v[176:179], v[192:195], v[32:35]
	v_mfma_f32_16x16x32_bf16 v[20:23], v[168:171], v[200:203], v[20:23]
	v_mfma_f32_16x16x32_bf16 v[16:19], v[176:179], v[200:203], v[16:19]
	v_mfma_f32_16x16x32_bf16 v[4:7], v[168:171], v[212:215], v[4:7]
	v_mfma_f32_16x16x32_bf16 v[0:3], v[176:179], v[212:215], v[0:3]
	v_mfma_f32_16x16x32_bf16 v[52:55], v[172:175], v[188:191], v[52:55]
	v_mfma_f32_16x16x32_bf16 v[48:51], v[180:183], v[188:191], v[48:51]
	v_mfma_f32_16x16x32_bf16 v[36:39], v[172:175], v[196:199], v[36:39]
	v_mfma_f32_16x16x32_bf16 v[32:35], v[180:183], v[196:199], v[32:35]
	v_mfma_f32_16x16x32_bf16 v[20:23], v[172:175], v[208:211], v[20:23]
	v_mfma_f32_16x16x32_bf16 v[16:19], v[180:183], v[208:211], v[16:19]
	v_mfma_f32_16x16x32_bf16 v[4:7], v[172:175], v[216:219], v[4:7]
	v_mfma_f32_16x16x32_bf16 v[0:3], v[180:183], v[216:219], v[0:3]
	s_barrier
	s_add_i32 s55, s55, 2
	s_add_u32 s53, s53, 0x100
	s_addc_u32 s54, s54, 0
	s_add_u32 s24, s24, 0x100
	s_addc_u32 s25, s25, 0
	s_cmp_gt_u32 s55, 13
	s_cbranch_scc0 .LBB0_163
	s_setprio 0
	s_and_b64 vcc, exec, s[14:15]
	s_cbranch_vccz .LBB0_166
	s_barrier

.Lbal_first_20:
	s_add_u32 s30, s28, 0x100
	s_addc_u32 s31, s29, 0
	s_cmp_eq_u32 s58, 12
	s_cselect_b32 s37, s21, s31
	s_cselect_b32 s36, s27, s30
	s_cselect_b32 s35, s19, s57
	s_cselect_b32 s34, s55, s56
	s_add_i32 m0, s44, 0xc000
	s_nop 0
	global_load_lds_dwordx4 v134, s[28:29]
	s_add_i32 m0, s44, 0xe000
	s_nop 0
	global_load_lds_dwordx4 v132, s[28:29]
	ds_read_b128 v[140:143], v147
	ds_read_b128 v[150:153], v147 offset:1024
	ds_read_b128 v[154:157], v147 offset:2048
	ds_read_b128 v[158:161], v147 offset:3072
	ds_read_b128 v[162:165], v148
	ds_read_b128 v[166:169], v148 offset:1024
	ds_read_b128 v[170:173], v148 offset:2048
	ds_read_b128 v[174:177], v148 offset:3072
	ds_read_b128 v[178:181], v149
	ds_read_b128 v[182:185], v149 offset:1024
	ds_read_b128 v[186:189], v149 offset:2048
	ds_read_b128 v[190:193], v149 offset:3072
	ds_read_b128 v[194:197], v149 offset:4096
	ds_read_b128 v[198:201], v149 offset:5120
	ds_read_b128 v[202:205], v149 offset:6144
	ds_read_b128 v[208:211], v149 offset:7168
	s_waitcnt vmcnt(8)
	s_waitcnt lgkmcnt(0)
	s_barrier
	s_waitcnt lgkmcnt(0)
	v_mfma_f32_16x16x32_bf16 v[124:127], v[140:143], v[178:181], v[124:127]
	v_mfma_f32_16x16x32_bf16 v[120:123], v[154:157], v[178:181], v[120:123]
	v_mfma_f32_16x16x32_bf16 v[108:111], v[140:143], v[186:189], v[108:111]
	v_mfma_f32_16x16x32_bf16 v[104:107], v[154:157], v[186:189], v[104:107]
	v_mfma_f32_16x16x32_bf16 v[92:95], v[140:143], v[194:197], v[92:95]
	v_mfma_f32_16x16x32_bf16 v[88:91], v[154:157], v[194:197], v[88:91]
	v_mfma_f32_16x16x32_bf16 v[76:79], v[140:143], v[202:205], v[76:79]
	v_mfma_f32_16x16x32_bf16 v[72:75], v[154:157], v[202:205], v[72:75]
	v_mfma_f32_16x16x32_bf16 v[124:127], v[150:153], v[182:185], v[124:127]
	v_mfma_f32_16x16x32_bf16 v[120:123], v[158:161], v[182:185], v[120:123]
	v_mfma_f32_16x16x32_bf16 v[108:111], v[150:153], v[190:193], v[108:111]
	v_mfma_f32_16x16x32_bf16 v[104:107], v[158:161], v[190:193], v[104:107]
	v_mfma_f32_16x16x32_bf16 v[92:95], v[150:153], v[198:201], v[92:95]
	v_mfma_f32_16x16x32_bf16 v[88:91], v[158:161], v[198:201], v[88:91]
	v_mfma_f32_16x16x32_bf16 v[76:79], v[150:153], v[208:211], v[76:79]
	v_mfma_f32_16x16x32_bf16 v[72:75], v[158:161], v[208:211], v[72:75]
	v_mfma_f32_16x16x32_bf16 v[116:119], v[162:165], v[178:181], v[116:119]
	v_mfma_f32_16x16x32_bf16 v[112:115], v[170:173], v[178:181], v[112:115]
	v_mfma_f32_16x16x32_bf16 v[100:103], v[162:165], v[186:189], v[100:103]
	v_mfma_f32_16x16x32_bf16 v[96:99], v[170:173], v[186:189], v[96:99]
	v_mfma_f32_16x16x32_bf16 v[84:87], v[162:165], v[194:197], v[84:87]
	v_mfma_f32_16x16x32_bf16 v[80:83], v[170:173], v[194:197], v[80:83]
	v_mfma_f32_16x16x32_bf16 v[68:71], v[162:165], v[202:205], v[68:71]
	v_mfma_f32_16x16x32_bf16 v[64:67], v[170:173], v[202:205], v[64:67]
	v_mfma_f32_16x16x32_bf16 v[116:119], v[166:169], v[182:185], v[116:119]
	v_mfma_f32_16x16x32_bf16 v[112:115], v[174:177], v[182:185], v[112:115]
	v_mfma_f32_16x16x32_bf16 v[100:103], v[166:169], v[190:193], v[100:103]
	v_mfma_f32_16x16x32_bf16 v[96:99], v[174:177], v[190:193], v[96:99]
	v_mfma_f32_16x16x32_bf16 v[84:87], v[166:169], v[198:201], v[84:87]
	v_mfma_f32_16x16x32_bf16 v[80:83], v[174:177], v[198:201], v[80:83]
	v_mfma_f32_16x16x32_bf16 v[68:71], v[166:169], v[208:211], v[68:71]
	v_mfma_f32_16x16x32_bf16 v[64:67], v[174:177], v[208:211], v[64:67]
	s_barrier
	s_add_i32 s28, s52, s43
	s_mov_b32 m0, s28
	s_nop 0
	global_load_lds_dwordx4 v128, s[34:35]
	s_add_i32 m0, s28, 0x2000
	s_add_u32 s28, s34, 0x40000
	s_mov_b64 s[98:99], s[34:35]
	s_addc_u32 s29, s35, 0
	s_add_i32 s59, s53, s43
	global_load_lds_dwordx4 v130, s[34:35]
	s_mov_b32 m0, s59
	s_nop 0
	global_load_lds_dwordx4 v128, s[28:29]
	s_add_i32 m0, s59, 0x2000
	s_nop 0
	global_load_lds_dwordx4 v130, s[28:29]
	ds_read_b128 v[178:181], v149 offset:16384
	ds_read_b128 v[182:185], v149 offset:17408
	ds_read_b128 v[186:189], v149 offset:18432
	ds_read_b128 v[190:193], v149 offset:19456
	ds_read_b128 v[194:197], v149 offset:20480
	ds_read_b128 v[198:201], v149 offset:21504
	ds_read_b128 v[202:205], v149 offset:22528
	ds_read_b128 v[208:211], v149 offset:23552
	s_waitcnt vmcnt(6)
	s_waitcnt lgkmcnt(0)
	s_barrier
	s_waitcnt lgkmcnt(0)
	v_mfma_f32_16x16x32_bf16 v[60:63], v[140:143], v[178:181], v[60:63]
	v_mfma_f32_16x16x32_bf16 v[56:59], v[154:157], v[178:181], v[56:59]
	v_mfma_f32_16x16x32_bf16 v[44:47], v[140:143], v[186:189], v[44:47]
	v_mfma_f32_16x16x32_bf16 v[40:43], v[154:157], v[186:189], v[40:43]
	v_mfma_f32_16x16x32_bf16 v[28:31], v[140:143], v[194:197], v[28:31]
	v_mfma_f32_16x16x32_bf16 v[24:27], v[154:157], v[194:197], v[24:27]
	v_mfma_f32_16x16x32_bf16 v[12:15], v[140:143], v[202:205], v[12:15]
	v_mfma_f32_16x16x32_bf16 v[8:11], v[154:157], v[202:205], v[8:11]
	v_mfma_f32_16x16x32_bf16 v[60:63], v[150:153], v[182:185], v[60:63]
	v_mfma_f32_16x16x32_bf16 v[56:59], v[158:161], v[182:185], v[56:59]
	v_mfma_f32_16x16x32_bf16 v[44:47], v[150:153], v[190:193], v[44:47]
	v_mfma_f32_16x16x32_bf16 v[40:43], v[158:161], v[190:193], v[40:43]
	v_mfma_f32_16x16x32_bf16 v[28:31], v[150:153], v[198:201], v[28:31]
	v_mfma_f32_16x16x32_bf16 v[24:27], v[158:161], v[198:201], v[24:27]
	v_mfma_f32_16x16x32_bf16 v[12:15], v[150:153], v[208:211], v[12:15]
	v_mfma_f32_16x16x32_bf16 v[8:11], v[158:161], v[208:211], v[8:11]
	v_mfma_f32_16x16x32_bf16 v[52:55], v[162:165], v[178:181], v[52:55]
	v_mfma_f32_16x16x32_bf16 v[48:51], v[170:173], v[178:181], v[48:51]
	v_mfma_f32_16x16x32_bf16 v[36:39], v[162:165], v[186:189], v[36:39]
	v_mfma_f32_16x16x32_bf16 v[32:35], v[170:173], v[186:189], v[32:35]
	v_mfma_f32_16x16x32_bf16 v[20:23], v[162:165], v[194:197], v[20:23]
	v_mfma_f32_16x16x32_bf16 v[16:19], v[170:173], v[194:197], v[16:19]
	v_mfma_f32_16x16x32_bf16 v[4:7], v[162:165], v[202:205], v[4:7]
	v_mfma_f32_16x16x32_bf16 v[0:3], v[170:173], v[202:205], v[0:3]
	v_mfma_f32_16x16x32_bf16 v[52:55], v[166:169], v[182:185], v[52:55]
	v_mfma_f32_16x16x32_bf16 v[48:51], v[174:177], v[182:185], v[48:51]
	v_mfma_f32_16x16x32_bf16 v[36:39], v[166:169], v[190:193], v[36:39]
	v_mfma_f32_16x16x32_bf16 v[32:35], v[174:177], v[190:193], v[32:35]
	v_mfma_f32_16x16x32_bf16 v[20:23], v[166:169], v[198:201], v[20:23]
	v_mfma_f32_16x16x32_bf16 v[16:19], v[174:177], v[198:201], v[16:19]
	v_mfma_f32_16x16x32_bf16 v[4:7], v[166:169], v[208:211], v[4:7]
	v_mfma_f32_16x16x32_bf16 v[0:3], v[174:177], v[208:211], v[0:3]
	s_barrier
	s_mov_b32 m0, s44
	s_nop 0
	global_load_lds_dwordx4 v128, s[36:37]
	s_mov_b32 m0, s45
	s_nop 0
	global_load_lds_dwordx4 v130, s[36:37]
	s_add_i32 s59, 0, 0x18000
	s_add_i32 s60, 0, 0x1c000
	s_add_u32 s28, s36, 0x40000
	s_addc_u32 s29, s37, 0
	s_mov_b32 m0, s46
	s_nop 0
	global_load_lds_dwordx4 v128, s[28:29]
	s_mov_b32 m0, s47
	s_nop 0
	global_load_lds_dwordx4 v130, s[28:29]
	v_add_u32_e32 v158, s59, v145
	v_add_u32_e32 v174, s60, v145
	ds_read_b128 v[140:143], v158
	ds_read_b128 v[150:153], v158 offset:1024
	ds_read_b128 v[154:157], v158 offset:2048
	ds_read_b128 v[158:161], v158 offset:3072
	ds_read_b128 v[162:165], v174
	ds_read_b128 v[166:169], v174 offset:1024
	ds_read_b128 v[170:173], v174 offset:2048
	ds_read_b128 v[174:177], v174 offset:3072
	ds_read_b128 v[178:181], v149 offset:32768
	ds_read_b128 v[182:185], v149 offset:33792
	ds_read_b128 v[186:189], v149 offset:34816
	ds_read_b128 v[190:193], v149 offset:35840
	ds_read_b128 v[194:197], v149 offset:36864
	ds_read_b128 v[198:201], v149 offset:37888
	ds_read_b128 v[202:205], v149 offset:38912
	ds_read_b128 v[208:211], v149 offset:39936
	s_waitcnt vmcnt(8)
	s_waitcnt lgkmcnt(0)
	s_barrier
	s_waitcnt lgkmcnt(0)
	v_mfma_f32_16x16x32_bf16 v[124:127], v[140:143], v[178:181], v[124:127]
	v_mfma_f32_16x16x32_bf16 v[120:123], v[154:157], v[178:181], v[120:123]
	v_mfma_f32_16x16x32_bf16 v[108:111], v[140:143], v[186:189], v[108:111]
	v_mfma_f32_16x16x32_bf16 v[104:107], v[154:157], v[186:189], v[104:107]
	v_mfma_f32_16x16x32_bf16 v[92:95], v[140:143], v[194:197], v[92:95]
	v_mfma_f32_16x16x32_bf16 v[88:91], v[154:157], v[194:197], v[88:91]
	v_mfma_f32_16x16x32_bf16 v[76:79], v[140:143], v[202:205], v[76:79]
	v_mfma_f32_16x16x32_bf16 v[72:75], v[154:157], v[202:205], v[72:75]
	v_mfma_f32_16x16x32_bf16 v[124:127], v[150:153], v[182:185], v[124:127]
	v_mfma_f32_16x16x32_bf16 v[120:123], v[158:161], v[182:185], v[120:123]
	v_mfma_f32_16x16x32_bf16 v[108:111], v[150:153], v[190:193], v[108:111]
	v_mfma_f32_16x16x32_bf16 v[104:107], v[158:161], v[190:193], v[104:107]
	v_mfma_f32_16x16x32_bf16 v[92:95], v[150:153], v[198:201], v[92:95]
	v_mfma_f32_16x16x32_bf16 v[88:91], v[158:161], v[198:201], v[88:91]
	v_mfma_f32_16x16x32_bf16 v[76:79], v[150:153], v[208:211], v[76:79]
	v_mfma_f32_16x16x32_bf16 v[72:75], v[158:161], v[208:211], v[72:75]
	v_mfma_f32_16x16x32_bf16 v[116:119], v[162:165], v[178:181], v[116:119]
	v_mfma_f32_16x16x32_bf16 v[112:115], v[170:173], v[178:181], v[112:115]
	v_mfma_f32_16x16x32_bf16 v[100:103], v[162:165], v[186:189], v[100:103]
	v_mfma_f32_16x16x32_bf16 v[96:99], v[170:173], v[186:189], v[96:99]
	v_mfma_f32_16x16x32_bf16 v[84:87], v[162:165], v[194:197], v[84:87]
	v_mfma_f32_16x16x32_bf16 v[80:83], v[170:173], v[194:197], v[80:83]
	v_mfma_f32_16x16x32_bf16 v[68:71], v[162:165], v[202:205], v[68:71]
	v_mfma_f32_16x16x32_bf16 v[64:67], v[170:173], v[202:205], v[64:67]
	v_mfma_f32_16x16x32_bf16 v[116:119], v[166:169], v[182:185], v[116:119]
	v_mfma_f32_16x16x32_bf16 v[112:115], v[174:177], v[182:185], v[112:115]
	v_mfma_f32_16x16x32_bf16 v[100:103], v[166:169], v[190:193], v[100:103]
	v_mfma_f32_16x16x32_bf16 v[96:99], v[174:177], v[190:193], v[96:99]
	v_mfma_f32_16x16x32_bf16 v[84:87], v[166:169], v[198:201], v[84:87]
	v_mfma_f32_16x16x32_bf16 v[80:83], v[174:177], v[198:201], v[80:83]
	v_mfma_f32_16x16x32_bf16 v[68:71], v[166:169], v[208:211], v[68:71]
	v_mfma_f32_16x16x32_bf16 v[64:67], v[174:177], v[208:211], v[64:67]
	s_barrier
	s_add_i32 s28, s59, s43
	s_mov_b32 m0, s28
	s_nop 0
	global_load_lds_dwordx4 v212, s[34:35]
	s_add_i32 m0, s28, 0x2000
	s_add_u32 s28, s34, 0x40080
	s_addc_u32 s29, s35, 0
	s_add_i32 s34, s60, s43
	global_load_lds_dwordx4 v213, s[98:99]
	s_mov_b32 m0, s34
	s_nop 0
	global_load_lds_dwordx4 v128, s[28:29]
	s_add_i32 m0, s34, 0x2000
	s_nop 0
	global_load_lds_dwordx4 v130, s[28:29]
	s_cmp_lg_u32 s58, 12
	s_cbranch_scc1 .Lbal_last_20
	s_mov_b32 m0, s49
	s_nop 0
	global_load_lds_dwordx4 v212, s[36:37]
	s_mov_b32 m0, s50
	s_nop 0
	global_load_lds_dwordx4 v213, s[36:37]
.Lbal_last_20:
	ds_read_b128 v[178:181], v149 offset:49152
	ds_read_b128 v[182:185], v149 offset:50176
	ds_read_b128 v[186:189], v149 offset:51200
	ds_read_b128 v[190:193], v149 offset:52224
	ds_read_b128 v[194:197], v149 offset:53248
	ds_read_b128 v[198:201], v149 offset:54272
	ds_read_b128 v[202:205], v149 offset:55296
	ds_read_b128 v[208:211], v149 offset:56320
	s_waitcnt vmcnt(6)
	s_waitcnt lgkmcnt(0)
	s_barrier
	s_waitcnt lgkmcnt(0)
	v_mfma_f32_16x16x32_bf16 v[60:63], v[140:143], v[178:181], v[60:63]
	v_mfma_f32_16x16x32_bf16 v[56:59], v[154:157], v[178:181], v[56:59]
	v_mfma_f32_16x16x32_bf16 v[44:47], v[140:143], v[186:189], v[44:47]
	v_mfma_f32_16x16x32_bf16 v[40:43], v[154:157], v[186:189], v[40:43]
	v_mfma_f32_16x16x32_bf16 v[28:31], v[140:143], v[194:197], v[28:31]
	v_mfma_f32_16x16x32_bf16 v[24:27], v[154:157], v[194:197], v[24:27]
	v_mfma_f32_16x16x32_bf16 v[12:15], v[140:143], v[202:205], v[12:15]
	v_mfma_f32_16x16x32_bf16 v[8:11], v[154:157], v[202:205], v[8:11]
	v_mfma_f32_16x16x32_bf16 v[60:63], v[150:153], v[182:185], v[60:63]
	v_mfma_f32_16x16x32_bf16 v[56:59], v[158:161], v[182:185], v[56:59]
	v_mfma_f32_16x16x32_bf16 v[44:47], v[150:153], v[190:193], v[44:47]
	v_mfma_f32_16x16x32_bf16 v[40:43], v[158:161], v[190:193], v[40:43]
	v_mfma_f32_16x16x32_bf16 v[28:31], v[150:153], v[198:201], v[28:31]
	v_mfma_f32_16x16x32_bf16 v[24:27], v[158:161], v[198:201], v[24:27]
	v_mfma_f32_16x16x32_bf16 v[12:15], v[150:153], v[208:211], v[12:15]
	v_mfma_f32_16x16x32_bf16 v[8:11], v[158:161], v[208:211], v[8:11]
	v_mfma_f32_16x16x32_bf16 v[52:55], v[162:165], v[178:181], v[52:55]
	v_mfma_f32_16x16x32_bf16 v[48:51], v[170:173], v[178:181], v[48:51]
	v_mfma_f32_16x16x32_bf16 v[36:39], v[162:165], v[186:189], v[36:39]
	v_mfma_f32_16x16x32_bf16 v[32:35], v[170:173], v[186:189], v[32:35]
	v_mfma_f32_16x16x32_bf16 v[20:23], v[162:165], v[194:197], v[20:23]
	v_mfma_f32_16x16x32_bf16 v[16:19], v[170:173], v[194:197], v[16:19]
	v_mfma_f32_16x16x32_bf16 v[4:7], v[162:165], v[202:205], v[4:7]
	v_mfma_f32_16x16x32_bf16 v[0:3], v[170:173], v[202:205], v[0:3]
	v_mfma_f32_16x16x32_bf16 v[52:55], v[166:169], v[182:185], v[52:55]
	v_mfma_f32_16x16x32_bf16 v[48:51], v[174:177], v[182:185], v[48:51]
	v_mfma_f32_16x16x32_bf16 v[36:39], v[166:169], v[190:193], v[36:39]
	v_mfma_f32_16x16x32_bf16 v[32:35], v[174:177], v[190:193], v[32:35]
	v_mfma_f32_16x16x32_bf16 v[20:23], v[166:169], v[198:201], v[20:23]
	v_mfma_f32_16x16x32_bf16 v[16:19], v[174:177], v[198:201], v[16:19]
	v_mfma_f32_16x16x32_bf16 v[4:7], v[166:169], v[208:211], v[4:7]
	v_mfma_f32_16x16x32_bf16 v[0:3], v[174:177], v[208:211], v[0:3]
	s_barrier
	s_add_i32 s58, s58, 2
	s_add_u32 s56, s56, 0x100
	s_addc_u32 s57, s57, 0
	s_cmp_gt_u32 s58, 13
	s_mov_b64 s[28:29], s[30:31]
	s_cbranch_scc0 .LBB0_606
	s_setprio 0
	s_and_b64 vcc, exec, s[16:17]
	s_cbranch_vccz .LBB0_609
	s_barrier

.Lbal_first_19:
	s_add_u32 s28, s26, 0xfffc0080
	s_addc_u32 s29, s27, -1
	s_cmp_eq_u32 s53, 12
	s_cselect_b32 s31, s21, s29
	s_cselect_b32 s30, s49, s28
	s_cselect_b32 s29, s19, s52
	s_cselect_b32 s28, s50, s51
	s_add_i32 m0, s39, 0xc000
	s_nop 0
	global_load_lds_dwordx4 v138, s[26:27]
	s_add_i32 m0, s39, 0xe000
	s_nop 0
	global_load_lds_dwordx4 v136, s[26:27]
	ds_read_b128 v[144:147], v151
	ds_read_b128 v[156:159], v151 offset:1024
	ds_read_b128 v[160:163], v151 offset:2048
	ds_read_b128 v[164:167], v151 offset:3072
	ds_read_b128 v[168:171], v152
	ds_read_b128 v[172:175], v152 offset:1024
	ds_read_b128 v[176:179], v152 offset:2048
	ds_read_b128 v[180:183], v152 offset:3072
	ds_read_b128 v[184:187], v153
	ds_read_b128 v[188:191], v153 offset:1024
	ds_read_b128 v[192:195], v153 offset:2048
	ds_read_b128 v[196:199], v153 offset:3072
	ds_read_b128 v[200:203], v153 offset:4096
	ds_read_b128 v[208:211], v153 offset:5120
	ds_read_b128 v[212:215], v153 offset:6144
	ds_read_b128 v[216:219], v153 offset:7168
	s_waitcnt vmcnt(8)
	s_waitcnt lgkmcnt(0)
	s_barrier
	s_waitcnt lgkmcnt(0)
	v_mfma_f32_16x16x32_bf16 v[124:127], v[144:147], v[184:187], v[124:127]
	v_mfma_f32_16x16x32_bf16 v[120:123], v[160:163], v[184:187], v[120:123]
	v_mfma_f32_16x16x32_bf16 v[108:111], v[144:147], v[192:195], v[108:111]
	v_mfma_f32_16x16x32_bf16 v[104:107], v[160:163], v[192:195], v[104:107]
	v_mfma_f32_16x16x32_bf16 v[92:95], v[144:147], v[200:203], v[92:95]
	v_mfma_f32_16x16x32_bf16 v[88:91], v[160:163], v[200:203], v[88:91]
	v_mfma_f32_16x16x32_bf16 v[76:79], v[144:147], v[212:215], v[76:79]
	v_mfma_f32_16x16x32_bf16 v[72:75], v[160:163], v[212:215], v[72:75]
	v_mfma_f32_16x16x32_bf16 v[124:127], v[156:159], v[188:191], v[124:127]
	v_mfma_f32_16x16x32_bf16 v[120:123], v[164:167], v[188:191], v[120:123]
	v_mfma_f32_16x16x32_bf16 v[108:111], v[156:159], v[196:199], v[108:111]
	v_mfma_f32_16x16x32_bf16 v[104:107], v[164:167], v[196:199], v[104:107]
	v_mfma_f32_16x16x32_bf16 v[92:95], v[156:159], v[208:211], v[92:95]
	v_mfma_f32_16x16x32_bf16 v[88:91], v[164:167], v[208:211], v[88:91]
	v_mfma_f32_16x16x32_bf16 v[76:79], v[156:159], v[216:219], v[76:79]
	v_mfma_f32_16x16x32_bf16 v[72:75], v[164:167], v[216:219], v[72:75]
	v_mfma_f32_16x16x32_bf16 v[116:119], v[168:171], v[184:187], v[116:119]
	v_mfma_f32_16x16x32_bf16 v[112:115], v[176:179], v[184:187], v[112:115]
	v_mfma_f32_16x16x32_bf16 v[100:103], v[168:171], v[192:195], v[100:103]
	v_mfma_f32_16x16x32_bf16 v[96:99], v[176:179], v[192:195], v[96:99]
	v_mfma_f32_16x16x32_bf16 v[84:87], v[168:171], v[200:203], v[84:87]
	v_mfma_f32_16x16x32_bf16 v[80:83], v[176:179], v[200:203], v[80:83]
	v_mfma_f32_16x16x32_bf16 v[68:71], v[168:171], v[212:215], v[68:71]
	v_mfma_f32_16x16x32_bf16 v[64:67], v[176:179], v[212:215], v[64:67]
	v_mfma_f32_16x16x32_bf16 v[116:119], v[172:175], v[188:191], v[116:119]
	v_mfma_f32_16x16x32_bf16 v[112:115], v[180:183], v[188:191], v[112:115]
	v_mfma_f32_16x16x32_bf16 v[100:103], v[172:175], v[196:199], v[100:103]
	v_mfma_f32_16x16x32_bf16 v[96:99], v[180:183], v[196:199], v[96:99]
	v_mfma_f32_16x16x32_bf16 v[84:87], v[172:175], v[208:211], v[84:87]
	v_mfma_f32_16x16x32_bf16 v[80:83], v[180:183], v[208:211], v[80:83]
	v_mfma_f32_16x16x32_bf16 v[68:71], v[172:175], v[216:219], v[68:71]
	v_mfma_f32_16x16x32_bf16 v[64:67], v[180:183], v[216:219], v[64:67]
	s_barrier
	s_add_i32 s54, s46, s38
	s_mov_b32 m0, s54
	s_nop 0
	global_load_lds_dwordx4 v130, s[28:29]
	s_add_i32 m0, s54, 0x2000
	s_add_u32 s54, s28, 0x40000
	s_mov_b64 s[98:99], s[28:29]
	s_addc_u32 s55, s29, 0
	s_add_i32 s56, s47, s38
	global_load_lds_dwordx4 v134, s[28:29]
	s_mov_b32 m0, s56
	s_mov_b64 s[100:101], s[30:31]
	global_load_lds_dwordx4 v130, s[54:55]
	s_add_i32 m0, s56, 0x2000
	s_nop 0
	global_load_lds_dwordx4 v134, s[54:55]
	ds_read_b128 v[184:187], v153 offset:16384
	ds_read_b128 v[188:191], v153 offset:17408
	ds_read_b128 v[192:195], v153 offset:18432
	ds_read_b128 v[196:199], v153 offset:19456
	ds_read_b128 v[200:203], v153 offset:20480
	ds_read_b128 v[208:211], v153 offset:21504
	ds_read_b128 v[212:215], v153 offset:22528
	ds_read_b128 v[216:219], v153 offset:23552
	s_waitcnt vmcnt(6)
	s_waitcnt lgkmcnt(0)
	s_barrier
	s_waitcnt lgkmcnt(0)
	v_mfma_f32_16x16x32_bf16 v[60:63], v[144:147], v[184:187], v[60:63]
	v_mfma_f32_16x16x32_bf16 v[56:59], v[160:163], v[184:187], v[56:59]
	v_mfma_f32_16x16x32_bf16 v[44:47], v[144:147], v[192:195], v[44:47]
	v_mfma_f32_16x16x32_bf16 v[40:43], v[160:163], v[192:195], v[40:43]
	v_mfma_f32_16x16x32_bf16 v[28:31], v[144:147], v[200:203], v[28:31]
	v_mfma_f32_16x16x32_bf16 v[24:27], v[160:163], v[200:203], v[24:27]
	v_mfma_f32_16x16x32_bf16 v[12:15], v[144:147], v[212:215], v[12:15]
	v_mfma_f32_16x16x32_bf16 v[8:11], v[160:163], v[212:215], v[8:11]
	v_mfma_f32_16x16x32_bf16 v[60:63], v[156:159], v[188:191], v[60:63]
	v_mfma_f32_16x16x32_bf16 v[56:59], v[164:167], v[188:191], v[56:59]
	v_mfma_f32_16x16x32_bf16 v[44:47], v[156:159], v[196:199], v[44:47]
	v_mfma_f32_16x16x32_bf16 v[40:43], v[164:167], v[196:199], v[40:43]
	v_mfma_f32_16x16x32_bf16 v[28:31], v[156:159], v[208:211], v[28:31]
	v_mfma_f32_16x16x32_bf16 v[24:27], v[164:167], v[208:211], v[24:27]
	v_mfma_f32_16x16x32_bf16 v[12:15], v[156:159], v[216:219], v[12:15]
	v_mfma_f32_16x16x32_bf16 v[8:11], v[164:167], v[216:219], v[8:11]
	v_mfma_f32_16x16x32_bf16 v[52:55], v[168:171], v[184:187], v[52:55]
	v_mfma_f32_16x16x32_bf16 v[48:51], v[176:179], v[184:187], v[48:51]
	v_mfma_f32_16x16x32_bf16 v[36:39], v[168:171], v[192:195], v[36:39]
	v_mfma_f32_16x16x32_bf16 v[32:35], v[176:179], v[192:195], v[32:35]
	v_mfma_f32_16x16x32_bf16 v[20:23], v[168:171], v[200:203], v[20:23]
	v_mfma_f32_16x16x32_bf16 v[16:19], v[176:179], v[200:203], v[16:19]
	v_mfma_f32_16x16x32_bf16 v[4:7], v[168:171], v[212:215], v[4:7]
	v_mfma_f32_16x16x32_bf16 v[0:3], v[176:179], v[212:215], v[0:3]
	v_mfma_f32_16x16x32_bf16 v[52:55], v[172:175], v[188:191], v[52:55]
	v_mfma_f32_16x16x32_bf16 v[48:51], v[180:183], v[188:191], v[48:51]
	v_mfma_f32_16x16x32_bf16 v[36:39], v[172:175], v[196:199], v[36:39]
	v_mfma_f32_16x16x32_bf16 v[32:35], v[180:183], v[196:199], v[32:35]
	v_mfma_f32_16x16x32_bf16 v[20:23], v[172:175], v[208:211], v[20:23]
	v_mfma_f32_16x16x32_bf16 v[16:19], v[180:183], v[208:211], v[16:19]
	v_mfma_f32_16x16x32_bf16 v[4:7], v[172:175], v[216:219], v[4:7]
	v_mfma_f32_16x16x32_bf16 v[0:3], v[180:183], v[216:219], v[0:3]
	s_barrier
	s_mov_b32 m0, s39
	s_nop 0
	global_load_lds_dwordx4 v128, s[30:31]
	s_mov_b32 m0, s40
	s_nop 0
	global_load_lds_dwordx4 v132, s[30:31]
	s_add_i32 s54, 0, 0x18000
	s_add_i32 s55, 0, 0x1c000
	s_add_u32 s30, s30, 0x40000
	s_addc_u32 s31, s31, 0
	s_mov_b32 m0, s41
	s_nop 0
	global_load_lds_dwordx4 v128, s[30:31]
	s_mov_b32 m0, s42
	s_nop 0
	global_load_lds_dwordx4 v132, s[30:31]
	v_add_u32_e32 v155, s54, v149
	ds_read_b128 v[144:147], v155
	ds_read_b128 v[156:159], v155 offset:1024
	ds_read_b128 v[160:163], v155 offset:2048
	ds_read_b128 v[164:167], v155 offset:3072
	v_add_u32_e32 v155, s55, v149
	ds_read_b128 v[168:171], v155
	ds_read_b128 v[172:175], v155 offset:1024
	ds_read_b128 v[176:179], v155 offset:2048
	ds_read_b128 v[180:183], v155 offset:3072
	ds_read_b128 v[184:187], v153 offset:32768
	ds_read_b128 v[188:191], v153 offset:33792
	ds_read_b128 v[192:195], v153 offset:34816
	ds_read_b128 v[196:199], v153 offset:35840
	ds_read_b128 v[200:203], v153 offset:36864
	ds_read_b128 v[208:211], v153 offset:37888
	ds_read_b128 v[212:215], v153 offset:38912
	ds_read_b128 v[216:219], v153 offset:39936
	s_waitcnt vmcnt(8)
	s_waitcnt lgkmcnt(0)
	s_barrier
	s_waitcnt lgkmcnt(0)
	v_mfma_f32_16x16x32_bf16 v[124:127], v[144:147], v[184:187], v[124:127]
	v_mfma_f32_16x16x32_bf16 v[120:123], v[160:163], v[184:187], v[120:123]
	v_mfma_f32_16x16x32_bf16 v[108:111], v[144:147], v[192:195], v[108:111]
	v_mfma_f32_16x16x32_bf16 v[104:107], v[160:163], v[192:195], v[104:107]
	v_mfma_f32_16x16x32_bf16 v[92:95], v[144:147], v[200:203], v[92:95]
	v_mfma_f32_16x16x32_bf16 v[88:91], v[160:163], v[200:203], v[88:91]
	v_mfma_f32_16x16x32_bf16 v[76:79], v[144:147], v[212:215], v[76:79]
	v_mfma_f32_16x16x32_bf16 v[72:75], v[160:163], v[212:215], v[72:75]
	v_mfma_f32_16x16x32_bf16 v[124:127], v[156:159], v[188:191], v[124:127]
	v_mfma_f32_16x16x32_bf16 v[120:123], v[164:167], v[188:191], v[120:123]
	v_mfma_f32_16x16x32_bf16 v[108:111], v[156:159], v[196:199], v[108:111]
	v_mfma_f32_16x16x32_bf16 v[104:107], v[164:167], v[196:199], v[104:107]
	v_mfma_f32_16x16x32_bf16 v[92:95], v[156:159], v[208:211], v[92:95]
	v_mfma_f32_16x16x32_bf16 v[88:91], v[164:167], v[208:211], v[88:91]
	v_mfma_f32_16x16x32_bf16 v[76:79], v[156:159], v[216:219], v[76:79]
	v_mfma_f32_16x16x32_bf16 v[72:75], v[164:167], v[216:219], v[72:75]
	v_mfma_f32_16x16x32_bf16 v[116:119], v[168:171], v[184:187], v[116:119]
	v_mfma_f32_16x16x32_bf16 v[112:115], v[176:179], v[184:187], v[112:115]
	v_mfma_f32_16x16x32_bf16 v[100:103], v[168:171], v[192:195], v[100:103]
	v_mfma_f32_16x16x32_bf16 v[96:99], v[176:179], v[192:195], v[96:99]
	v_mfma_f32_16x16x32_bf16 v[84:87], v[168:171], v[200:203], v[84:87]
	v_mfma_f32_16x16x32_bf16 v[80:83], v[176:179], v[200:203], v[80:83]
	v_mfma_f32_16x16x32_bf16 v[68:71], v[168:171], v[212:215], v[68:71]
	v_mfma_f32_16x16x32_bf16 v[64:67], v[176:179], v[212:215], v[64:67]
	v_mfma_f32_16x16x32_bf16 v[116:119], v[172:175], v[188:191], v[116:119]
	v_mfma_f32_16x16x32_bf16 v[112:115], v[180:183], v[188:191], v[112:115]
	v_mfma_f32_16x16x32_bf16 v[100:103], v[172:175], v[196:199], v[100:103]
	v_mfma_f32_16x16x32_bf16 v[96:99], v[180:183], v[196:199], v[96:99]
	v_mfma_f32_16x16x32_bf16 v[84:87], v[172:175], v[208:211], v[84:87]
	v_mfma_f32_16x16x32_bf16 v[80:83], v[180:183], v[208:211], v[80:83]
	v_mfma_f32_16x16x32_bf16 v[68:71], v[172:175], v[216:219], v[68:71]
	v_mfma_f32_16x16x32_bf16 v[64:67], v[180:183], v[216:219], v[64:67]
	s_barrier
	s_add_i32 s30, s54, s38
	s_mov_b32 m0, s30
	s_nop 0
	global_load_lds_dwordx4 v205, s[28:29]
	s_add_i32 m0, s30, 0x2000
	s_add_u32 s28, s28, 0x40080
	s_addc_u32 s29, s29, 0
	s_add_i32 s30, s55, s38
	global_load_lds_dwordx4 v221, s[98:99]
	s_mov_b32 m0, s30
	s_nop 0
	global_load_lds_dwordx4 v130, s[28:29]
	s_add_i32 m0, s30, 0x2000
	s_nop 0
	global_load_lds_dwordx4 v134, s[28:29]
	s_cmp_lg_u32 s53, 12
	s_cbranch_scc1 .Lbal_last_19
	s_mov_b32 m0, s44
	s_nop 0
	global_load_lds_dwordx4 v204, s[100:101]
	s_mov_b32 m0, s45
	s_nop 0
	global_load_lds_dwordx4 v220, s[100:101]
.Lbal_last_19:
	ds_read_b128 v[184:187], v153 offset:49152
	ds_read_b128 v[188:191], v153 offset:50176
	ds_read_b128 v[192:195], v153 offset:51200
	ds_read_b128 v[196:199], v153 offset:52224
	ds_read_b128 v[200:203], v153 offset:53248
	ds_read_b128 v[208:211], v153 offset:54272
	ds_read_b128 v[212:215], v153 offset:55296
	ds_read_b128 v[216:219], v153 offset:56320
	s_waitcnt vmcnt(6)
	s_waitcnt lgkmcnt(0)
	s_barrier
	s_waitcnt lgkmcnt(0)
	v_mfma_f32_16x16x32_bf16 v[60:63], v[144:147], v[184:187], v[60:63]
	v_mfma_f32_16x16x32_bf16 v[56:59], v[160:163], v[184:187], v[56:59]
	v_mfma_f32_16x16x32_bf16 v[44:47], v[144:147], v[192:195], v[44:47]
	v_mfma_f32_16x16x32_bf16 v[40:43], v[160:163], v[192:195], v[40:43]
	v_mfma_f32_16x16x32_bf16 v[28:31], v[144:147], v[200:203], v[28:31]
	v_mfma_f32_16x16x32_bf16 v[24:27], v[160:163], v[200:203], v[24:27]
	v_mfma_f32_16x16x32_bf16 v[12:15], v[144:147], v[212:215], v[12:15]
	v_mfma_f32_16x16x32_bf16 v[8:11], v[160:163], v[212:215], v[8:11]
	v_mfma_f32_16x16x32_bf16 v[60:63], v[156:159], v[188:191], v[60:63]
	v_mfma_f32_16x16x32_bf16 v[56:59], v[164:167], v[188:191], v[56:59]
	v_mfma_f32_16x16x32_bf16 v[44:47], v[156:159], v[196:199], v[44:47]
	v_mfma_f32_16x16x32_bf16 v[40:43], v[164:167], v[196:199], v[40:43]
	v_mfma_f32_16x16x32_bf16 v[28:31], v[156:159], v[208:211], v[28:31]
	v_mfma_f32_16x16x32_bf16 v[24:27], v[164:167], v[208:211], v[24:27]
	v_mfma_f32_16x16x32_bf16 v[12:15], v[156:159], v[216:219], v[12:15]
	v_mfma_f32_16x16x32_bf16 v[8:11], v[164:167], v[216:219], v[8:11]
	v_mfma_f32_16x16x32_bf16 v[52:55], v[168:171], v[184:187], v[52:55]
	v_mfma_f32_16x16x32_bf16 v[48:51], v[176:179], v[184:187], v[48:51]
	v_mfma_f32_16x16x32_bf16 v[36:39], v[168:171], v[192:195], v[36:39]
	v_mfma_f32_16x16x32_bf16 v[32:35], v[176:179], v[192:195], v[32:35]
	v_mfma_f32_16x16x32_bf16 v[20:23], v[168:171], v[200:203], v[20:23]
	v_mfma_f32_16x16x32_bf16 v[16:19], v[176:179], v[200:203], v[16:19]
	v_mfma_f32_16x16x32_bf16 v[4:7], v[168:171], v[212:215], v[4:7]
	v_mfma_f32_16x16x32_bf16 v[0:3], v[176:179], v[212:215], v[0:3]
	v_mfma_f32_16x16x32_bf16 v[52:55], v[172:175], v[188:191], v[52:55]
	v_mfma_f32_16x16x32_bf16 v[48:51], v[180:183], v[188:191], v[48:51]
	v_mfma_f32_16x16x32_bf16 v[36:39], v[172:175], v[196:199], v[36:39]
	v_mfma_f32_16x16x32_bf16 v[32:35], v[180:183], v[196:199], v[32:35]
	v_mfma_f32_16x16x32_bf16 v[20:23], v[172:175], v[208:211], v[20:23]
	v_mfma_f32_16x16x32_bf16 v[16:19], v[180:183], v[208:211], v[16:19]
	v_mfma_f32_16x16x32_bf16 v[4:7], v[172:175], v[216:219], v[4:7]
	v_mfma_f32_16x16x32_bf16 v[0:3], v[180:183], v[216:219], v[0:3]
	s_barrier
	s_add_i32 s53, s53, 2
	s_add_u32 s51, s51, 0x100
	s_addc_u32 s52, s52, 0
	s_add_u32 s26, s26, 0x100
	s_addc_u32 s27, s27, 0
	s_cmp_gt_u32 s53, 13
	s_cbranch_scc0 .LBB0_699
	s_setprio 0
	s_and_b64 vcc, exec, s[16:17]
	s_cbranch_vccz .LBB0_702
	s_barrier

.Lbal_first_18:
	s_add_u32 s30, s28, 0x100
	s_addc_u32 s31, s29, 0
	s_cmp_eq_u32 s58, 60
	s_cselect_b32 s37, s21, s31
	s_cselect_b32 s36, s27, s30
	s_cselect_b32 s35, s19, s57
	s_cselect_b32 s34, s55, s56
	s_add_i32 m0, s44, 0xc000
	s_nop 0
	global_load_lds_dwordx4 v134, s[28:29]
	s_add_i32 m0, s44, 0xe000
	s_nop 0
	global_load_lds_dwordx4 v132, s[28:29]
	ds_read_b128 v[140:143], v147
	ds_read_b128 v[150:153], v147 offset:1024
	ds_read_b128 v[154:157], v147 offset:2048
	ds_read_b128 v[158:161], v147 offset:3072
	ds_read_b128 v[162:165], v148
	ds_read_b128 v[166:169], v148 offset:1024
	ds_read_b128 v[170:173], v148 offset:2048
	ds_read_b128 v[174:177], v148 offset:3072
	ds_read_b128 v[178:181], v149
	ds_read_b128 v[182:185], v149 offset:1024
	ds_read_b128 v[186:189], v149 offset:2048
	ds_read_b128 v[190:193], v149 offset:3072
	ds_read_b128 v[194:197], v149 offset:4096
	ds_read_b128 v[198:201], v149 offset:5120
	ds_read_b128 v[202:205], v149 offset:6144
	ds_read_b128 v[208:211], v149 offset:7168
	s_waitcnt vmcnt(8)
	s_waitcnt lgkmcnt(0)
	s_barrier
	s_waitcnt lgkmcnt(0)
	v_mfma_f32_16x16x32_bf16 v[124:127], v[140:143], v[178:181], v[124:127]
	v_mfma_f32_16x16x32_bf16 v[120:123], v[154:157], v[178:181], v[120:123]
	v_mfma_f32_16x16x32_bf16 v[108:111], v[140:143], v[186:189], v[108:111]
	v_mfma_f32_16x16x32_bf16 v[104:107], v[154:157], v[186:189], v[104:107]
	v_mfma_f32_16x16x32_bf16 v[92:95], v[140:143], v[194:197], v[92:95]
	v_mfma_f32_16x16x32_bf16 v[88:91], v[154:157], v[194:197], v[88:91]
	v_mfma_f32_16x16x32_bf16 v[76:79], v[140:143], v[202:205], v[76:79]
	v_mfma_f32_16x16x32_bf16 v[72:75], v[154:157], v[202:205], v[72:75]
	v_mfma_f32_16x16x32_bf16 v[124:127], v[150:153], v[182:185], v[124:127]
	v_mfma_f32_16x16x32_bf16 v[120:123], v[158:161], v[182:185], v[120:123]
	v_mfma_f32_16x16x32_bf16 v[108:111], v[150:153], v[190:193], v[108:111]
	v_mfma_f32_16x16x32_bf16 v[104:107], v[158:161], v[190:193], v[104:107]
	v_mfma_f32_16x16x32_bf16 v[92:95], v[150:153], v[198:201], v[92:95]
	v_mfma_f32_16x16x32_bf16 v[88:91], v[158:161], v[198:201], v[88:91]
	v_mfma_f32_16x16x32_bf16 v[76:79], v[150:153], v[208:211], v[76:79]
	v_mfma_f32_16x16x32_bf16 v[72:75], v[158:161], v[208:211], v[72:75]
	v_mfma_f32_16x16x32_bf16 v[116:119], v[162:165], v[178:181], v[116:119]
	v_mfma_f32_16x16x32_bf16 v[112:115], v[170:173], v[178:181], v[112:115]
	v_mfma_f32_16x16x32_bf16 v[100:103], v[162:165], v[186:189], v[100:103]
	v_mfma_f32_16x16x32_bf16 v[96:99], v[170:173], v[186:189], v[96:99]
	v_mfma_f32_16x16x32_bf16 v[84:87], v[162:165], v[194:197], v[84:87]
	v_mfma_f32_16x16x32_bf16 v[80:83], v[170:173], v[194:197], v[80:83]
	v_mfma_f32_16x16x32_bf16 v[68:71], v[162:165], v[202:205], v[68:71]
	v_mfma_f32_16x16x32_bf16 v[64:67], v[170:173], v[202:205], v[64:67]
	v_mfma_f32_16x16x32_bf16 v[116:119], v[166:169], v[182:185], v[116:119]
	v_mfma_f32_16x16x32_bf16 v[112:115], v[174:177], v[182:185], v[112:115]
	v_mfma_f32_16x16x32_bf16 v[100:103], v[166:169], v[190:193], v[100:103]
	v_mfma_f32_16x16x32_bf16 v[96:99], v[174:177], v[190:193], v[96:99]
	v_mfma_f32_16x16x32_bf16 v[84:87], v[166:169], v[198:201], v[84:87]
	v_mfma_f32_16x16x32_bf16 v[80:83], v[174:177], v[198:201], v[80:83]
	v_mfma_f32_16x16x32_bf16 v[68:71], v[166:169], v[208:211], v[68:71]
	v_mfma_f32_16x16x32_bf16 v[64:67], v[174:177], v[208:211], v[64:67]
	s_barrier
	s_add_i32 s28, s52, s43
	s_mov_b32 m0, s28
	s_nop 0
	global_load_lds_dwordx4 v128, s[34:35]
	s_add_i32 m0, s28, 0x2000
	s_add_u32 s28, s34, 0x100000
	s_mov_b64 s[98:99], s[34:35]
	s_addc_u32 s29, s35, 0
	s_add_i32 s59, s53, s43
	global_load_lds_dwordx4 v130, s[34:35]
	s_mov_b32 m0, s59
	s_nop 0
	global_load_lds_dwordx4 v128, s[28:29]
	s_add_i32 m0, s59, 0x2000
	s_nop 0
	global_load_lds_dwordx4 v130, s[28:29]
	ds_read_b128 v[178:181], v149 offset:16384
	ds_read_b128 v[182:185], v149 offset:17408
	ds_read_b128 v[186:189], v149 offset:18432
	ds_read_b128 v[190:193], v149 offset:19456
	ds_read_b128 v[194:197], v149 offset:20480
	ds_read_b128 v[198:201], v149 offset:21504
	ds_read_b128 v[202:205], v149 offset:22528
	ds_read_b128 v[208:211], v149 offset:23552
	s_waitcnt vmcnt(6)
	s_waitcnt lgkmcnt(0)
	s_barrier
	s_waitcnt lgkmcnt(0)
	v_mfma_f32_16x16x32_bf16 v[60:63], v[140:143], v[178:181], v[60:63]
	v_mfma_f32_16x16x32_bf16 v[56:59], v[154:157], v[178:181], v[56:59]
	v_mfma_f32_16x16x32_bf16 v[44:47], v[140:143], v[186:189], v[44:47]
	v_mfma_f32_16x16x32_bf16 v[40:43], v[154:157], v[186:189], v[40:43]
	v_mfma_f32_16x16x32_bf16 v[28:31], v[140:143], v[194:197], v[28:31]
	v_mfma_f32_16x16x32_bf16 v[24:27], v[154:157], v[194:197], v[24:27]
	v_mfma_f32_16x16x32_bf16 v[12:15], v[140:143], v[202:205], v[12:15]
	v_mfma_f32_16x16x32_bf16 v[8:11], v[154:157], v[202:205], v[8:11]
	v_mfma_f32_16x16x32_bf16 v[60:63], v[150:153], v[182:185], v[60:63]
	v_mfma_f32_16x16x32_bf16 v[56:59], v[158:161], v[182:185], v[56:59]
	v_mfma_f32_16x16x32_bf16 v[44:47], v[150:153], v[190:193], v[44:47]
	v_mfma_f32_16x16x32_bf16 v[40:43], v[158:161], v[190:193], v[40:43]
	v_mfma_f32_16x16x32_bf16 v[28:31], v[150:153], v[198:201], v[28:31]
	v_mfma_f32_16x16x32_bf16 v[24:27], v[158:161], v[198:201], v[24:27]
	v_mfma_f32_16x16x32_bf16 v[12:15], v[150:153], v[208:211], v[12:15]
	v_mfma_f32_16x16x32_bf16 v[8:11], v[158:161], v[208:211], v[8:11]
	v_mfma_f32_16x16x32_bf16 v[52:55], v[162:165], v[178:181], v[52:55]
	v_mfma_f32_16x16x32_bf16 v[48:51], v[170:173], v[178:181], v[48:51]
	v_mfma_f32_16x16x32_bf16 v[36:39], v[162:165], v[186:189], v[36:39]
	v_mfma_f32_16x16x32_bf16 v[32:35], v[170:173], v[186:189], v[32:35]
	v_mfma_f32_16x16x32_bf16 v[20:23], v[162:165], v[194:197], v[20:23]
	v_mfma_f32_16x16x32_bf16 v[16:19], v[170:173], v[194:197], v[16:19]
	v_mfma_f32_16x16x32_bf16 v[4:7], v[162:165], v[202:205], v[4:7]
	v_mfma_f32_16x16x32_bf16 v[0:3], v[170:173], v[202:205], v[0:3]
	v_mfma_f32_16x16x32_bf16 v[52:55], v[166:169], v[182:185], v[52:55]
	v_mfma_f32_16x16x32_bf16 v[48:51], v[174:177], v[182:185], v[48:51]
	v_mfma_f32_16x16x32_bf16 v[36:39], v[166:169], v[190:193], v[36:39]
	v_mfma_f32_16x16x32_bf16 v[32:35], v[174:177], v[190:193], v[32:35]
	v_mfma_f32_16x16x32_bf16 v[20:23], v[166:169], v[198:201], v[20:23]
	v_mfma_f32_16x16x32_bf16 v[16:19], v[174:177], v[198:201], v[16:19]
	v_mfma_f32_16x16x32_bf16 v[4:7], v[166:169], v[208:211], v[4:7]
	v_mfma_f32_16x16x32_bf16 v[0:3], v[174:177], v[208:211], v[0:3]
	s_barrier
	s_mov_b32 m0, s44
	s_nop 0
	global_load_lds_dwordx4 v128, s[36:37]
	s_mov_b32 m0, s45
	s_nop 0
	global_load_lds_dwordx4 v130, s[36:37]
	s_add_i32 s59, 0, 0x18000
	s_add_i32 s60, 0, 0x1c000
	s_add_u32 s28, s36, 0x100000
	s_addc_u32 s29, s37, 0
	s_mov_b32 m0, s46
	s_nop 0
	global_load_lds_dwordx4 v128, s[28:29]
	s_mov_b32 m0, s47
	s_nop 0
	global_load_lds_dwordx4 v130, s[28:29]
	v_add_u32_e32 v158, s59, v145
	v_add_u32_e32 v174, s60, v145
	ds_read_b128 v[140:143], v158
	ds_read_b128 v[150:153], v158 offset:1024
	ds_read_b128 v[154:157], v158 offset:2048
	ds_read_b128 v[158:161], v158 offset:3072
	ds_read_b128 v[162:165], v174
	ds_read_b128 v[166:169], v174 offset:1024
	ds_read_b128 v[170:173], v174 offset:2048
	ds_read_b128 v[174:177], v174 offset:3072
	ds_read_b128 v[178:181], v149 offset:32768
	ds_read_b128 v[182:185], v149 offset:33792
	ds_read_b128 v[186:189], v149 offset:34816
	ds_read_b128 v[190:193], v149 offset:35840
	ds_read_b128 v[194:197], v149 offset:36864
	ds_read_b128 v[198:201], v149 offset:37888
	ds_read_b128 v[202:205], v149 offset:38912
	ds_read_b128 v[208:211], v149 offset:39936
	s_waitcnt vmcnt(8)
	s_waitcnt lgkmcnt(0)
	s_barrier
	s_waitcnt lgkmcnt(0)
	v_mfma_f32_16x16x32_bf16 v[124:127], v[140:143], v[178:181], v[124:127]
	v_mfma_f32_16x16x32_bf16 v[120:123], v[154:157], v[178:181], v[120:123]
	v_mfma_f32_16x16x32_bf16 v[108:111], v[140:143], v[186:189], v[108:111]
	v_mfma_f32_16x16x32_bf16 v[104:107], v[154:157], v[186:189], v[104:107]
	v_mfma_f32_16x16x32_bf16 v[92:95], v[140:143], v[194:197], v[92:95]
	v_mfma_f32_16x16x32_bf16 v[88:91], v[154:157], v[194:197], v[88:91]
	v_mfma_f32_16x16x32_bf16 v[76:79], v[140:143], v[202:205], v[76:79]
	v_mfma_f32_16x16x32_bf16 v[72:75], v[154:157], v[202:205], v[72:75]
	v_mfma_f32_16x16x32_bf16 v[124:127], v[150:153], v[182:185], v[124:127]
	v_mfma_f32_16x16x32_bf16 v[120:123], v[158:161], v[182:185], v[120:123]
	v_mfma_f32_16x16x32_bf16 v[108:111], v[150:153], v[190:193], v[108:111]
	v_mfma_f32_16x16x32_bf16 v[104:107], v[158:161], v[190:193], v[104:107]
	v_mfma_f32_16x16x32_bf16 v[92:95], v[150:153], v[198:201], v[92:95]
	v_mfma_f32_16x16x32_bf16 v[88:91], v[158:161], v[198:201], v[88:91]
	v_mfma_f32_16x16x32_bf16 v[76:79], v[150:153], v[208:211], v[76:79]
	v_mfma_f32_16x16x32_bf16 v[72:75], v[158:161], v[208:211], v[72:75]
	v_mfma_f32_16x16x32_bf16 v[116:119], v[162:165], v[178:181], v[116:119]
	v_mfma_f32_16x16x32_bf16 v[112:115], v[170:173], v[178:181], v[112:115]
	v_mfma_f32_16x16x32_bf16 v[100:103], v[162:165], v[186:189], v[100:103]
	v_mfma_f32_16x16x32_bf16 v[96:99], v[170:173], v[186:189], v[96:99]
	v_mfma_f32_16x16x32_bf16 v[84:87], v[162:165], v[194:197], v[84:87]
	v_mfma_f32_16x16x32_bf16 v[80:83], v[170:173], v[194:197], v[80:83]
	v_mfma_f32_16x16x32_bf16 v[68:71], v[162:165], v[202:205], v[68:71]
	v_mfma_f32_16x16x32_bf16 v[64:67], v[170:173], v[202:205], v[64:67]
	v_mfma_f32_16x16x32_bf16 v[116:119], v[166:169], v[182:185], v[116:119]
	v_mfma_f32_16x16x32_bf16 v[112:115], v[174:177], v[182:185], v[112:115]
	v_mfma_f32_16x16x32_bf16 v[100:103], v[166:169], v[190:193], v[100:103]
	v_mfma_f32_16x16x32_bf16 v[96:99], v[174:177], v[190:193], v[96:99]
	v_mfma_f32_16x16x32_bf16 v[84:87], v[166:169], v[198:201], v[84:87]
	v_mfma_f32_16x16x32_bf16 v[80:83], v[174:177], v[198:201], v[80:83]
	v_mfma_f32_16x16x32_bf16 v[68:71], v[166:169], v[208:211], v[68:71]
	v_mfma_f32_16x16x32_bf16 v[64:67], v[174:177], v[208:211], v[64:67]
	s_barrier
	s_add_i32 s28, s59, s43
	s_mov_b32 m0, s28
	s_nop 0
	global_load_lds_dwordx4 v212, s[34:35]
	s_add_i32 m0, s28, 0x2000
	s_add_u32 s28, s34, 0x100080
	s_addc_u32 s29, s35, 0
	s_add_i32 s34, s60, s43
	global_load_lds_dwordx4 v213, s[98:99]
	s_mov_b32 m0, s34
	s_nop 0
	global_load_lds_dwordx4 v128, s[28:29]
	s_add_i32 m0, s34, 0x2000
	s_nop 0
	global_load_lds_dwordx4 v130, s[28:29]
	s_cmp_lg_u32 s58, 60
	s_cbranch_scc1 .Lbal_last_18
	s_mov_b32 m0, s49
	s_nop 0
	global_load_lds_dwordx4 v212, s[36:37]
	s_mov_b32 m0, s50
	s_nop 0
	global_load_lds_dwordx4 v213, s[36:37]
.Lbal_last_18:
	ds_read_b128 v[178:181], v149 offset:49152
	ds_read_b128 v[182:185], v149 offset:50176
	ds_read_b128 v[186:189], v149 offset:51200
	ds_read_b128 v[190:193], v149 offset:52224
	ds_read_b128 v[194:197], v149 offset:53248
	ds_read_b128 v[198:201], v149 offset:54272
	ds_read_b128 v[202:205], v149 offset:55296
	ds_read_b128 v[208:211], v149 offset:56320
	s_waitcnt vmcnt(6)
	s_waitcnt lgkmcnt(0)
	s_barrier
	s_waitcnt lgkmcnt(0)
	v_mfma_f32_16x16x32_bf16 v[60:63], v[140:143], v[178:181], v[60:63]
	v_mfma_f32_16x16x32_bf16 v[56:59], v[154:157], v[178:181], v[56:59]
	v_mfma_f32_16x16x32_bf16 v[44:47], v[140:143], v[186:189], v[44:47]
	v_mfma_f32_16x16x32_bf16 v[40:43], v[154:157], v[186:189], v[40:43]
	v_mfma_f32_16x16x32_bf16 v[28:31], v[140:143], v[194:197], v[28:31]
	v_mfma_f32_16x16x32_bf16 v[24:27], v[154:157], v[194:197], v[24:27]
	v_mfma_f32_16x16x32_bf16 v[12:15], v[140:143], v[202:205], v[12:15]
	v_mfma_f32_16x16x32_bf16 v[8:11], v[154:157], v[202:205], v[8:11]
	v_mfma_f32_16x16x32_bf16 v[60:63], v[150:153], v[182:185], v[60:63]
	v_mfma_f32_16x16x32_bf16 v[56:59], v[158:161], v[182:185], v[56:59]
	v_mfma_f32_16x16x32_bf16 v[44:47], v[150:153], v[190:193], v[44:47]
	v_mfma_f32_16x16x32_bf16 v[40:43], v[158:161], v[190:193], v[40:43]
	v_mfma_f32_16x16x32_bf16 v[28:31], v[150:153], v[198:201], v[28:31]
	v_mfma_f32_16x16x32_bf16 v[24:27], v[158:161], v[198:201], v[24:27]
	v_mfma_f32_16x16x32_bf16 v[12:15], v[150:153], v[208:211], v[12:15]
	v_mfma_f32_16x16x32_bf16 v[8:11], v[158:161], v[208:211], v[8:11]
	v_mfma_f32_16x16x32_bf16 v[52:55], v[162:165], v[178:181], v[52:55]
	v_mfma_f32_16x16x32_bf16 v[48:51], v[170:173], v[178:181], v[48:51]
	v_mfma_f32_16x16x32_bf16 v[36:39], v[162:165], v[186:189], v[36:39]
	v_mfma_f32_16x16x32_bf16 v[32:35], v[170:173], v[186:189], v[32:35]
	v_mfma_f32_16x16x32_bf16 v[20:23], v[162:165], v[194:197], v[20:23]
	v_mfma_f32_16x16x32_bf16 v[16:19], v[170:173], v[194:197], v[16:19]
	v_mfma_f32_16x16x32_bf16 v[4:7], v[162:165], v[202:205], v[4:7]
	v_mfma_f32_16x16x32_bf16 v[0:3], v[170:173], v[202:205], v[0:3]
	v_mfma_f32_16x16x32_bf16 v[52:55], v[166:169], v[182:185], v[52:55]
	v_mfma_f32_16x16x32_bf16 v[48:51], v[174:177], v[182:185], v[48:51]
	v_mfma_f32_16x16x32_bf16 v[36:39], v[166:169], v[190:193], v[36:39]
	v_mfma_f32_16x16x32_bf16 v[32:35], v[174:177], v[190:193], v[32:35]
	v_mfma_f32_16x16x32_bf16 v[20:23], v[166:169], v[198:201], v[20:23]
	v_mfma_f32_16x16x32_bf16 v[16:19], v[174:177], v[198:201], v[16:19]
	v_mfma_f32_16x16x32_bf16 v[4:7], v[166:169], v[208:211], v[4:7]
	v_mfma_f32_16x16x32_bf16 v[0:3], v[174:177], v[208:211], v[0:3]
	s_barrier
	s_add_i32 s58, s58, 2
	s_add_u32 s56, s56, 0x100
	s_addc_u32 s57, s57, 0
	s_cmp_gt_u32 s58, 61
	s_mov_b64 s[28:29], s[30:31]
	s_cbranch_scc0 .LBB0_778
	s_setprio 0
	s_and_b64 vcc, exec, s[16:17]
	s_cbranch_vccz .LBB0_781
	s_barrier

.Lbal_first_17:
	s_add_u32 s38, s36, 0xfffc0080
	s_addc_u32 s39, s37, -1
	s_cmp_eq_u32 s61, 12
	s_cselect_b32 s41, s3, s39
	s_cselect_b32 s40, s29, s38
	s_cselect_b32 s39, s27, s60
	s_cselect_b32 s38, s58, s59
	s_add_i32 m0, s46, 0xc000
	s_nop 0
	global_load_lds_dwordx4 v134, s[36:37]
	s_add_i32 m0, s46, 0xe000
	s_nop 0
	global_load_lds_dwordx4 v132, s[36:37]
	ds_read_b128 v[140:143], v153
	ds_read_b128 v[144:147], v153 offset:1024
	ds_read_b128 v[158:161], v153 offset:2048
	ds_read_b128 v[162:165], v153 offset:3072
	ds_read_b128 v[166:169], v154
	ds_read_b128 v[170:173], v154 offset:1024
	ds_read_b128 v[174:177], v154 offset:2048
	ds_read_b128 v[178:181], v154 offset:3072
	ds_read_b128 v[182:185], v155
	ds_read_b128 v[186:189], v155 offset:1024
	ds_read_b128 v[190:193], v155 offset:2048
	ds_read_b128 v[194:197], v155 offset:3072
	ds_read_b128 v[198:201], v155 offset:4096
	ds_read_b128 v[202:205], v155 offset:5120
	ds_read_b128 v[208:211], v155 offset:6144
	ds_read_b128 v[212:215], v155 offset:7168
	s_waitcnt vmcnt(8)
	s_waitcnt lgkmcnt(0)
	s_barrier
	s_waitcnt lgkmcnt(0)
	v_mfma_f32_16x16x32_bf16 v[124:127], v[140:143], v[182:185], v[124:127]
	v_mfma_f32_16x16x32_bf16 v[120:123], v[158:161], v[182:185], v[120:123]
	v_mfma_f32_16x16x32_bf16 v[108:111], v[140:143], v[190:193], v[108:111]
	v_mfma_f32_16x16x32_bf16 v[104:107], v[158:161], v[190:193], v[104:107]
	v_mfma_f32_16x16x32_bf16 v[92:95], v[140:143], v[198:201], v[92:95]
	v_mfma_f32_16x16x32_bf16 v[88:91], v[158:161], v[198:201], v[88:91]
	v_mfma_f32_16x16x32_bf16 v[76:79], v[140:143], v[208:211], v[76:79]
	v_mfma_f32_16x16x32_bf16 v[72:75], v[158:161], v[208:211], v[72:75]
	v_mfma_f32_16x16x32_bf16 v[124:127], v[144:147], v[186:189], v[124:127]
	v_mfma_f32_16x16x32_bf16 v[120:123], v[162:165], v[186:189], v[120:123]
	v_mfma_f32_16x16x32_bf16 v[108:111], v[144:147], v[194:197], v[108:111]
	v_mfma_f32_16x16x32_bf16 v[104:107], v[162:165], v[194:197], v[104:107]
	v_mfma_f32_16x16x32_bf16 v[92:95], v[144:147], v[202:205], v[92:95]
	v_mfma_f32_16x16x32_bf16 v[88:91], v[162:165], v[202:205], v[88:91]
	v_mfma_f32_16x16x32_bf16 v[76:79], v[144:147], v[212:215], v[76:79]
	v_mfma_f32_16x16x32_bf16 v[72:75], v[162:165], v[212:215], v[72:75]
	v_mfma_f32_16x16x32_bf16 v[116:119], v[166:169], v[182:185], v[116:119]
	v_mfma_f32_16x16x32_bf16 v[112:115], v[174:177], v[182:185], v[112:115]
	v_mfma_f32_16x16x32_bf16 v[100:103], v[166:169], v[190:193], v[100:103]
	v_mfma_f32_16x16x32_bf16 v[96:99], v[174:177], v[190:193], v[96:99]
	v_mfma_f32_16x16x32_bf16 v[84:87], v[166:169], v[198:201], v[84:87]
	v_mfma_f32_16x16x32_bf16 v[80:83], v[174:177], v[198:201], v[80:83]
	v_mfma_f32_16x16x32_bf16 v[68:71], v[166:169], v[208:211], v[68:71]
	v_mfma_f32_16x16x32_bf16 v[64:67], v[174:177], v[208:211], v[64:67]
	v_mfma_f32_16x16x32_bf16 v[116:119], v[170:173], v[186:189], v[116:119]
	v_mfma_f32_16x16x32_bf16 v[112:115], v[178:181], v[186:189], v[112:115]
	v_mfma_f32_16x16x32_bf16 v[100:103], v[170:173], v[194:197], v[100:103]
	v_mfma_f32_16x16x32_bf16 v[96:99], v[178:181], v[194:197], v[96:99]
	v_mfma_f32_16x16x32_bf16 v[84:87], v[170:173], v[202:205], v[84:87]
	v_mfma_f32_16x16x32_bf16 v[80:83], v[178:181], v[202:205], v[80:83]
	v_mfma_f32_16x16x32_bf16 v[68:71], v[170:173], v[212:215], v[68:71]
	v_mfma_f32_16x16x32_bf16 v[64:67], v[178:181], v[212:215], v[64:67]
	s_barrier
	s_add_i32 s62, s54, s45
	s_mov_b32 m0, s62
	s_nop 0
	global_load_lds_dwordx4 v128, s[38:39]
	s_add_i32 m0, s62, 0x2000
	s_add_u32 s62, s38, 0x40000
	s_mov_b64 s[98:99], s[38:39]
	s_addc_u32 s63, s39, 0
	s_add_i32 s64, s55, s45
	global_load_lds_dwordx4 v130, s[38:39]
	s_mov_b32 m0, s64
	s_mov_b64 s[100:101], s[40:41]
	global_load_lds_dwordx4 v128, s[62:63]
	s_add_i32 m0, s64, 0x2000
	s_nop 0
	global_load_lds_dwordx4 v130, s[62:63]
	ds_read_b128 v[182:185], v155 offset:16384
	ds_read_b128 v[186:189], v155 offset:17408
	ds_read_b128 v[190:193], v155 offset:18432
	ds_read_b128 v[194:197], v155 offset:19456
	ds_read_b128 v[198:201], v155 offset:20480
	ds_read_b128 v[202:205], v155 offset:21504
	ds_read_b128 v[208:211], v155 offset:22528
	ds_read_b128 v[212:215], v155 offset:23552
	s_waitcnt vmcnt(6)
	s_waitcnt lgkmcnt(0)
	s_barrier
	s_waitcnt lgkmcnt(0)
	v_mfma_f32_16x16x32_bf16 v[60:63], v[140:143], v[182:185], v[60:63]
	v_mfma_f32_16x16x32_bf16 v[56:59], v[158:161], v[182:185], v[56:59]
	v_mfma_f32_16x16x32_bf16 v[44:47], v[140:143], v[190:193], v[44:47]
	v_mfma_f32_16x16x32_bf16 v[40:43], v[158:161], v[190:193], v[40:43]
	v_mfma_f32_16x16x32_bf16 v[28:31], v[140:143], v[198:201], v[28:31]
	v_mfma_f32_16x16x32_bf16 v[24:27], v[158:161], v[198:201], v[24:27]
	v_mfma_f32_16x16x32_bf16 v[12:15], v[140:143], v[208:211], v[12:15]
	v_mfma_f32_16x16x32_bf16 v[8:11], v[158:161], v[208:211], v[8:11]
	v_mfma_f32_16x16x32_bf16 v[60:63], v[144:147], v[186:189], v[60:63]
	v_mfma_f32_16x16x32_bf16 v[56:59], v[162:165], v[186:189], v[56:59]
	v_mfma_f32_16x16x32_bf16 v[44:47], v[144:147], v[194:197], v[44:47]
	v_mfma_f32_16x16x32_bf16 v[40:43], v[162:165], v[194:197], v[40:43]
	v_mfma_f32_16x16x32_bf16 v[28:31], v[144:147], v[202:205], v[28:31]
	v_mfma_f32_16x16x32_bf16 v[24:27], v[162:165], v[202:205], v[24:27]
	v_mfma_f32_16x16x32_bf16 v[12:15], v[144:147], v[212:215], v[12:15]
	v_mfma_f32_16x16x32_bf16 v[8:11], v[162:165], v[212:215], v[8:11]
	v_mfma_f32_16x16x32_bf16 v[52:55], v[166:169], v[182:185], v[52:55]
	v_mfma_f32_16x16x32_bf16 v[48:51], v[174:177], v[182:185], v[48:51]
	v_mfma_f32_16x16x32_bf16 v[36:39], v[166:169], v[190:193], v[36:39]
	v_mfma_f32_16x16x32_bf16 v[32:35], v[174:177], v[190:193], v[32:35]
	v_mfma_f32_16x16x32_bf16 v[20:23], v[166:169], v[198:201], v[20:23]
	v_mfma_f32_16x16x32_bf16 v[16:19], v[174:177], v[198:201], v[16:19]
	v_mfma_f32_16x16x32_bf16 v[4:7], v[166:169], v[208:211], v[4:7]
	v_mfma_f32_16x16x32_bf16 v[0:3], v[174:177], v[208:211], v[0:3]
	v_mfma_f32_16x16x32_bf16 v[52:55], v[170:173], v[186:189], v[52:55]
	v_mfma_f32_16x16x32_bf16 v[48:51], v[178:181], v[186:189], v[48:51]
	v_mfma_f32_16x16x32_bf16 v[36:39], v[170:173], v[194:197], v[36:39]
	v_mfma_f32_16x16x32_bf16 v[32:35], v[178:181], v[194:197], v[32:35]
	v_mfma_f32_16x16x32_bf16 v[20:23], v[170:173], v[202:205], v[20:23]
	v_mfma_f32_16x16x32_bf16 v[16:19], v[178:181], v[202:205], v[16:19]
	v_mfma_f32_16x16x32_bf16 v[4:7], v[170:173], v[212:215], v[4:7]
	v_mfma_f32_16x16x32_bf16 v[0:3], v[178:181], v[212:215], v[0:3]
	s_barrier
	s_mov_b32 m0, s46
	s_nop 0
	global_load_lds_dwordx4 v128, s[40:41]
	s_mov_b32 m0, s47
	s_nop 0
	global_load_lds_dwordx4 v130, s[40:41]
	s_add_i32 s62, 0, 0x18000
	s_add_i32 s63, 0, 0x1c000
	s_add_u32 s40, s40, 0x40000
	s_addc_u32 s41, s41, 0
	s_mov_b32 m0, s48
	s_nop 0
	global_load_lds_dwordx4 v128, s[40:41]
	s_mov_b32 m0, s49
	s_nop 0
	global_load_lds_dwordx4 v130, s[40:41]
	v_add_u32_e32 v157, s62, v151
	ds_read_b128 v[140:143], v157
	ds_read_b128 v[144:147], v157 offset:1024
	ds_read_b128 v[158:161], v157 offset:2048
	ds_read_b128 v[162:165], v157 offset:3072
	v_add_u32_e32 v157, s63, v151
	ds_read_b128 v[166:169], v157
	ds_read_b128 v[170:173], v157 offset:1024
	ds_read_b128 v[174:177], v157 offset:2048
	ds_read_b128 v[178:181], v157 offset:3072
	ds_read_b128 v[182:185], v155 offset:32768
	ds_read_b128 v[186:189], v155 offset:33792
	ds_read_b128 v[190:193], v155 offset:34816
	ds_read_b128 v[194:197], v155 offset:35840
	ds_read_b128 v[198:201], v155 offset:36864
	ds_read_b128 v[202:205], v155 offset:37888
	ds_read_b128 v[208:211], v155 offset:38912
	ds_read_b128 v[212:215], v155 offset:39936
	s_waitcnt vmcnt(8)
	s_waitcnt lgkmcnt(0)
	s_barrier
	s_waitcnt lgkmcnt(0)
	v_mfma_f32_16x16x32_bf16 v[124:127], v[140:143], v[182:185], v[124:127]
	v_mfma_f32_16x16x32_bf16 v[120:123], v[158:161], v[182:185], v[120:123]
	v_mfma_f32_16x16x32_bf16 v[108:111], v[140:143], v[190:193], v[108:111]
	v_mfma_f32_16x16x32_bf16 v[104:107], v[158:161], v[190:193], v[104:107]
	v_mfma_f32_16x16x32_bf16 v[92:95], v[140:143], v[198:201], v[92:95]
	v_mfma_f32_16x16x32_bf16 v[88:91], v[158:161], v[198:201], v[88:91]
	v_mfma_f32_16x16x32_bf16 v[76:79], v[140:143], v[208:211], v[76:79]
	v_mfma_f32_16x16x32_bf16 v[72:75], v[158:161], v[208:211], v[72:75]
	v_mfma_f32_16x16x32_bf16 v[124:127], v[144:147], v[186:189], v[124:127]
	v_mfma_f32_16x16x32_bf16 v[120:123], v[162:165], v[186:189], v[120:123]
	v_mfma_f32_16x16x32_bf16 v[108:111], v[144:147], v[194:197], v[108:111]
	v_mfma_f32_16x16x32_bf16 v[104:107], v[162:165], v[194:197], v[104:107]
	v_mfma_f32_16x16x32_bf16 v[92:95], v[144:147], v[202:205], v[92:95]
	v_mfma_f32_16x16x32_bf16 v[88:91], v[162:165], v[202:205], v[88:91]
	v_mfma_f32_16x16x32_bf16 v[76:79], v[144:147], v[212:215], v[76:79]
	v_mfma_f32_16x16x32_bf16 v[72:75], v[162:165], v[212:215], v[72:75]
	v_mfma_f32_16x16x32_bf16 v[116:119], v[166:169], v[182:185], v[116:119]
	v_mfma_f32_16x16x32_bf16 v[112:115], v[174:177], v[182:185], v[112:115]
	v_mfma_f32_16x16x32_bf16 v[100:103], v[166:169], v[190:193], v[100:103]
	v_mfma_f32_16x16x32_bf16 v[96:99], v[174:177], v[190:193], v[96:99]
	v_mfma_f32_16x16x32_bf16 v[84:87], v[166:169], v[198:201], v[84:87]
	v_mfma_f32_16x16x32_bf16 v[80:83], v[174:177], v[198:201], v[80:83]
	v_mfma_f32_16x16x32_bf16 v[68:71], v[166:169], v[208:211], v[68:71]
	v_mfma_f32_16x16x32_bf16 v[64:67], v[174:177], v[208:211], v[64:67]
	v_mfma_f32_16x16x32_bf16 v[116:119], v[170:173], v[186:189], v[116:119]
	v_mfma_f32_16x16x32_bf16 v[112:115], v[178:181], v[186:189], v[112:115]
	v_mfma_f32_16x16x32_bf16 v[100:103], v[170:173], v[194:197], v[100:103]
	v_mfma_f32_16x16x32_bf16 v[96:99], v[178:181], v[194:197], v[96:99]
	v_mfma_f32_16x16x32_bf16 v[84:87], v[170:173], v[202:205], v[84:87]
	v_mfma_f32_16x16x32_bf16 v[80:83], v[178:181], v[202:205], v[80:83]
	v_mfma_f32_16x16x32_bf16 v[68:71], v[170:173], v[212:215], v[68:71]
	v_mfma_f32_16x16x32_bf16 v[64:67], v[178:181], v[212:215], v[64:67]
	s_barrier
	s_add_i32 s40, s62, s45
	s_mov_b32 m0, s40
	s_nop 0
	global_load_lds_dwordx4 v148, s[38:39]
	s_add_i32 m0, s40, 0x2000
	s_add_u32 s38, s38, 0x40080
	s_addc_u32 s39, s39, 0
	s_add_i32 s40, s63, s45
	global_load_lds_dwordx4 v149, s[98:99]
	s_mov_b32 m0, s40
	s_nop 0
	global_load_lds_dwordx4 v128, s[38:39]
	s_add_i32 m0, s40, 0x2000
	s_nop 0
	global_load_lds_dwordx4 v130, s[38:39]
	s_cmp_lg_u32 s61, 12
	s_cbranch_scc1 .Lbal_last_17
	s_mov_b32 m0, s51
	s_nop 0
	global_load_lds_dwordx4 v148, s[100:101]
	s_mov_b32 m0, s52
	s_nop 0
	global_load_lds_dwordx4 v149, s[100:101]
.Lbal_last_17:
	ds_read_b128 v[182:185], v155 offset:49152
	ds_read_b128 v[186:189], v155 offset:50176
	ds_read_b128 v[190:193], v155 offset:51200
	ds_read_b128 v[194:197], v155 offset:52224
	ds_read_b128 v[198:201], v155 offset:53248
	ds_read_b128 v[202:205], v155 offset:54272
	ds_read_b128 v[208:211], v155 offset:55296
	ds_read_b128 v[212:215], v155 offset:56320
	s_waitcnt vmcnt(6)
	s_waitcnt lgkmcnt(0)
	s_barrier
	s_waitcnt lgkmcnt(0)
	v_mfma_f32_16x16x32_bf16 v[60:63], v[140:143], v[182:185], v[60:63]
	v_mfma_f32_16x16x32_bf16 v[56:59], v[158:161], v[182:185], v[56:59]
	v_mfma_f32_16x16x32_bf16 v[44:47], v[140:143], v[190:193], v[44:47]
	v_mfma_f32_16x16x32_bf16 v[40:43], v[158:161], v[190:193], v[40:43]
	v_mfma_f32_16x16x32_bf16 v[28:31], v[140:143], v[198:201], v[28:31]
	v_mfma_f32_16x16x32_bf16 v[24:27], v[158:161], v[198:201], v[24:27]
	v_mfma_f32_16x16x32_bf16 v[12:15], v[140:143], v[208:211], v[12:15]
	v_mfma_f32_16x16x32_bf16 v[8:11], v[158:161], v[208:211], v[8:11]
	v_mfma_f32_16x16x32_bf16 v[60:63], v[144:147], v[186:189], v[60:63]
	v_mfma_f32_16x16x32_bf16 v[56:59], v[162:165], v[186:189], v[56:59]
	v_mfma_f32_16x16x32_bf16 v[44:47], v[144:147], v[194:197], v[44:47]
	v_mfma_f32_16x16x32_bf16 v[40:43], v[162:165], v[194:197], v[40:43]
	v_mfma_f32_16x16x32_bf16 v[28:31], v[144:147], v[202:205], v[28:31]
	v_mfma_f32_16x16x32_bf16 v[24:27], v[162:165], v[202:205], v[24:27]
	v_mfma_f32_16x16x32_bf16 v[12:15], v[144:147], v[212:215], v[12:15]
	v_mfma_f32_16x16x32_bf16 v[8:11], v[162:165], v[212:215], v[8:11]
	v_mfma_f32_16x16x32_bf16 v[52:55], v[166:169], v[182:185], v[52:55]
	v_mfma_f32_16x16x32_bf16 v[48:51], v[174:177], v[182:185], v[48:51]
	v_mfma_f32_16x16x32_bf16 v[36:39], v[166:169], v[190:193], v[36:39]
	v_mfma_f32_16x16x32_bf16 v[32:35], v[174:177], v[190:193], v[32:35]
	v_mfma_f32_16x16x32_bf16 v[20:23], v[166:169], v[198:201], v[20:23]
	v_mfma_f32_16x16x32_bf16 v[16:19], v[174:177], v[198:201], v[16:19]
	v_mfma_f32_16x16x32_bf16 v[4:7], v[166:169], v[208:211], v[4:7]
	v_mfma_f32_16x16x32_bf16 v[0:3], v[174:177], v[208:211], v[0:3]
	v_mfma_f32_16x16x32_bf16 v[52:55], v[170:173], v[186:189], v[52:55]
	v_mfma_f32_16x16x32_bf16 v[48:51], v[178:181], v[186:189], v[48:51]
	v_mfma_f32_16x16x32_bf16 v[36:39], v[170:173], v[194:197], v[36:39]
	v_mfma_f32_16x16x32_bf16 v[32:35], v[178:181], v[194:197], v[32:35]
	v_mfma_f32_16x16x32_bf16 v[20:23], v[170:173], v[202:205], v[20:23]
	v_mfma_f32_16x16x32_bf16 v[16:19], v[178:181], v[202:205], v[16:19]
	v_mfma_f32_16x16x32_bf16 v[4:7], v[170:173], v[212:215], v[4:7]
	v_mfma_f32_16x16x32_bf16 v[0:3], v[178:181], v[212:215], v[0:3]
	s_barrier
	s_add_i32 s61, s61, 2
	s_add_u32 s59, s59, 0x100
	s_addc_u32 s60, s60, 0
	s_add_u32 s36, s36, 0x100
	s_addc_u32 s37, s37, 0
	s_cmp_gt_u32 s61, 13
	s_cbranch_scc0 .LBB0_895
	s_setprio 0
	s_and_b64 vcc, exec, s[24:25]
	s_cbranch_vccz .LBB0_898
	s_barrier

.Lbal_first_16:
	s_add_u32 s26, s6, 0xfffc0080
	s_addc_u32 s27, s7, -1
	s_cmp_eq_u32 s53, 12
	s_cselect_b32 s29, s19, s27
	s_cselect_b32 s28, s49, s26
	s_cselect_b32 s27, s17, s52
	s_cselect_b32 s26, s50, s51
	s_add_i32 m0, s25, 0xc000
	s_nop 0
	global_load_lds_dwordx4 v138, s[6:7]
	s_add_i32 m0, s25, 0xe000
	s_nop 0
	global_load_lds_dwordx4 v136, s[6:7]
	ds_read_b128 v[144:147], v151
	ds_read_b128 v[156:159], v151 offset:1024
	ds_read_b128 v[160:163], v151 offset:2048
	ds_read_b128 v[164:167], v151 offset:3072
	ds_read_b128 v[168:171], v152
	ds_read_b128 v[172:175], v152 offset:1024
	ds_read_b128 v[176:179], v152 offset:2048
	ds_read_b128 v[180:183], v152 offset:3072
	ds_read_b128 v[184:187], v153
	ds_read_b128 v[188:191], v153 offset:1024
	ds_read_b128 v[192:195], v153 offset:2048
	ds_read_b128 v[196:199], v153 offset:3072
	ds_read_b128 v[200:203], v153 offset:4096
	ds_read_b128 v[208:211], v153 offset:5120
	ds_read_b128 v[212:215], v153 offset:6144
	ds_read_b128 v[216:219], v153 offset:7168
	s_waitcnt vmcnt(8)
	s_waitcnt lgkmcnt(0)
	s_barrier
	s_waitcnt lgkmcnt(0)
	v_mfma_f32_16x16x32_bf16 v[124:127], v[144:147], v[184:187], v[124:127]
	v_mfma_f32_16x16x32_bf16 v[120:123], v[160:163], v[184:187], v[120:123]
	v_mfma_f32_16x16x32_bf16 v[108:111], v[144:147], v[192:195], v[108:111]
	v_mfma_f32_16x16x32_bf16 v[104:107], v[160:163], v[192:195], v[104:107]
	v_mfma_f32_16x16x32_bf16 v[92:95], v[144:147], v[200:203], v[92:95]
	v_mfma_f32_16x16x32_bf16 v[88:91], v[160:163], v[200:203], v[88:91]
	v_mfma_f32_16x16x32_bf16 v[76:79], v[144:147], v[212:215], v[76:79]
	v_mfma_f32_16x16x32_bf16 v[72:75], v[160:163], v[212:215], v[72:75]
	v_mfma_f32_16x16x32_bf16 v[124:127], v[156:159], v[188:191], v[124:127]
	v_mfma_f32_16x16x32_bf16 v[120:123], v[164:167], v[188:191], v[120:123]
	v_mfma_f32_16x16x32_bf16 v[108:111], v[156:159], v[196:199], v[108:111]
	v_mfma_f32_16x16x32_bf16 v[104:107], v[164:167], v[196:199], v[104:107]
	v_mfma_f32_16x16x32_bf16 v[92:95], v[156:159], v[208:211], v[92:95]
	v_mfma_f32_16x16x32_bf16 v[88:91], v[164:167], v[208:211], v[88:91]
	v_mfma_f32_16x16x32_bf16 v[76:79], v[156:159], v[216:219], v[76:79]
	v_mfma_f32_16x16x32_bf16 v[72:75], v[164:167], v[216:219], v[72:75]
	v_mfma_f32_16x16x32_bf16 v[116:119], v[168:171], v[184:187], v[116:119]
	v_mfma_f32_16x16x32_bf16 v[112:115], v[176:179], v[184:187], v[112:115]
	v_mfma_f32_16x16x32_bf16 v[100:103], v[168:171], v[192:195], v[100:103]
	v_mfma_f32_16x16x32_bf16 v[96:99], v[176:179], v[192:195], v[96:99]
	v_mfma_f32_16x16x32_bf16 v[84:87], v[168:171], v[200:203], v[84:87]
	v_mfma_f32_16x16x32_bf16 v[80:83], v[176:179], v[200:203], v[80:83]
	v_mfma_f32_16x16x32_bf16 v[68:71], v[168:171], v[212:215], v[68:71]
	v_mfma_f32_16x16x32_bf16 v[64:67], v[176:179], v[212:215], v[64:67]
	v_mfma_f32_16x16x32_bf16 v[116:119], v[172:175], v[188:191], v[116:119]
	v_mfma_f32_16x16x32_bf16 v[112:115], v[180:183], v[188:191], v[112:115]
	v_mfma_f32_16x16x32_bf16 v[100:103], v[172:175], v[196:199], v[100:103]
	v_mfma_f32_16x16x32_bf16 v[96:99], v[180:183], v[196:199], v[96:99]
	v_mfma_f32_16x16x32_bf16 v[84:87], v[172:175], v[208:211], v[84:87]
	v_mfma_f32_16x16x32_bf16 v[80:83], v[180:183], v[208:211], v[80:83]
	v_mfma_f32_16x16x32_bf16 v[68:71], v[172:175], v[216:219], v[68:71]
	v_mfma_f32_16x16x32_bf16 v[64:67], v[180:183], v[216:219], v[64:67]
	s_barrier
	s_add_i32 s54, s45, s38
	s_mov_b32 m0, s54
	s_nop 0
	global_load_lds_dwordx4 v130, s[26:27]
	s_add_i32 m0, s54, 0x2000
	s_add_u32 s54, s26, 0x40000
	s_mov_b64 s[98:99], s[26:27]
	s_addc_u32 s55, s27, 0
	s_add_i32 s56, s46, s38
	global_load_lds_dwordx4 v134, s[26:27]
	s_mov_b32 m0, s56
	s_mov_b64 s[100:101], s[28:29]
	global_load_lds_dwordx4 v130, s[54:55]
	s_add_i32 m0, s56, 0x2000
	s_nop 0
	global_load_lds_dwordx4 v134, s[54:55]
	ds_read_b128 v[184:187], v153 offset:16384
	ds_read_b128 v[188:191], v153 offset:17408
	ds_read_b128 v[192:195], v153 offset:18432
	ds_read_b128 v[196:199], v153 offset:19456
	ds_read_b128 v[200:203], v153 offset:20480
	ds_read_b128 v[208:211], v153 offset:21504
	ds_read_b128 v[212:215], v153 offset:22528
	ds_read_b128 v[216:219], v153 offset:23552
	s_waitcnt vmcnt(6)
	s_waitcnt lgkmcnt(0)
	s_barrier
	s_waitcnt lgkmcnt(0)
	v_mfma_f32_16x16x32_bf16 v[60:63], v[144:147], v[184:187], v[60:63]
	v_mfma_f32_16x16x32_bf16 v[56:59], v[160:163], v[184:187], v[56:59]
	v_mfma_f32_16x16x32_bf16 v[44:47], v[144:147], v[192:195], v[44:47]
	v_mfma_f32_16x16x32_bf16 v[40:43], v[160:163], v[192:195], v[40:43]
	v_mfma_f32_16x16x32_bf16 v[28:31], v[144:147], v[200:203], v[28:31]
	v_mfma_f32_16x16x32_bf16 v[24:27], v[160:163], v[200:203], v[24:27]
	v_mfma_f32_16x16x32_bf16 v[12:15], v[144:147], v[212:215], v[12:15]
	v_mfma_f32_16x16x32_bf16 v[8:11], v[160:163], v[212:215], v[8:11]
	v_mfma_f32_16x16x32_bf16 v[60:63], v[156:159], v[188:191], v[60:63]
	v_mfma_f32_16x16x32_bf16 v[56:59], v[164:167], v[188:191], v[56:59]
	v_mfma_f32_16x16x32_bf16 v[44:47], v[156:159], v[196:199], v[44:47]
	v_mfma_f32_16x16x32_bf16 v[40:43], v[164:167], v[196:199], v[40:43]
	v_mfma_f32_16x16x32_bf16 v[28:31], v[156:159], v[208:211], v[28:31]
	v_mfma_f32_16x16x32_bf16 v[24:27], v[164:167], v[208:211], v[24:27]
	v_mfma_f32_16x16x32_bf16 v[12:15], v[156:159], v[216:219], v[12:15]
	v_mfma_f32_16x16x32_bf16 v[8:11], v[164:167], v[216:219], v[8:11]
	v_mfma_f32_16x16x32_bf16 v[52:55], v[168:171], v[184:187], v[52:55]
	v_mfma_f32_16x16x32_bf16 v[48:51], v[176:179], v[184:187], v[48:51]
	v_mfma_f32_16x16x32_bf16 v[36:39], v[168:171], v[192:195], v[36:39]
	v_mfma_f32_16x16x32_bf16 v[32:35], v[176:179], v[192:195], v[32:35]
	v_mfma_f32_16x16x32_bf16 v[20:23], v[168:171], v[200:203], v[20:23]
	v_mfma_f32_16x16x32_bf16 v[16:19], v[176:179], v[200:203], v[16:19]
	v_mfma_f32_16x16x32_bf16 v[4:7], v[168:171], v[212:215], v[4:7]
	v_mfma_f32_16x16x32_bf16 v[0:3], v[176:179], v[212:215], v[0:3]
	v_mfma_f32_16x16x32_bf16 v[52:55], v[172:175], v[188:191], v[52:55]
	v_mfma_f32_16x16x32_bf16 v[48:51], v[180:183], v[188:191], v[48:51]
	v_mfma_f32_16x16x32_bf16 v[36:39], v[172:175], v[196:199], v[36:39]
	v_mfma_f32_16x16x32_bf16 v[32:35], v[180:183], v[196:199], v[32:35]
	v_mfma_f32_16x16x32_bf16 v[20:23], v[172:175], v[208:211], v[20:23]
	v_mfma_f32_16x16x32_bf16 v[16:19], v[180:183], v[208:211], v[16:19]
	v_mfma_f32_16x16x32_bf16 v[4:7], v[172:175], v[216:219], v[4:7]
	v_mfma_f32_16x16x32_bf16 v[0:3], v[180:183], v[216:219], v[0:3]
	s_barrier
	s_mov_b32 m0, s25
	s_nop 0
	global_load_lds_dwordx4 v128, s[28:29]
	s_mov_b32 m0, s39
	s_nop 0
	global_load_lds_dwordx4 v132, s[28:29]
	s_add_i32 s54, 0, 0x18000
	s_add_i32 s55, 0, 0x1c000
	s_add_u32 s28, s28, 0x40000
	s_addc_u32 s29, s29, 0
	s_mov_b32 m0, s40
	s_nop 0
	global_load_lds_dwordx4 v128, s[28:29]
	s_mov_b32 m0, s41
	s_nop 0
	global_load_lds_dwordx4 v132, s[28:29]
	v_add_u32_e32 v155, s54, v149
	ds_read_b128 v[144:147], v155
	ds_read_b128 v[156:159], v155 offset:1024
	ds_read_b128 v[160:163], v155 offset:2048
	ds_read_b128 v[164:167], v155 offset:3072
	v_add_u32_e32 v155, s55, v149
	ds_read_b128 v[168:171], v155
	ds_read_b128 v[172:175], v155 offset:1024
	ds_read_b128 v[176:179], v155 offset:2048
	ds_read_b128 v[180:183], v155 offset:3072
	ds_read_b128 v[184:187], v153 offset:32768
	ds_read_b128 v[188:191], v153 offset:33792
	ds_read_b128 v[192:195], v153 offset:34816
	ds_read_b128 v[196:199], v153 offset:35840
	ds_read_b128 v[200:203], v153 offset:36864
	ds_read_b128 v[208:211], v153 offset:37888
	ds_read_b128 v[212:215], v153 offset:38912
	ds_read_b128 v[216:219], v153 offset:39936
	s_waitcnt vmcnt(8)
	s_waitcnt lgkmcnt(0)
	s_barrier
	s_waitcnt lgkmcnt(0)
	v_mfma_f32_16x16x32_bf16 v[124:127], v[144:147], v[184:187], v[124:127]
	v_mfma_f32_16x16x32_bf16 v[120:123], v[160:163], v[184:187], v[120:123]
	v_mfma_f32_16x16x32_bf16 v[108:111], v[144:147], v[192:195], v[108:111]
	v_mfma_f32_16x16x32_bf16 v[104:107], v[160:163], v[192:195], v[104:107]
	v_mfma_f32_16x16x32_bf16 v[92:95], v[144:147], v[200:203], v[92:95]
	v_mfma_f32_16x16x32_bf16 v[88:91], v[160:163], v[200:203], v[88:91]
	v_mfma_f32_16x16x32_bf16 v[76:79], v[144:147], v[212:215], v[76:79]
	v_mfma_f32_16x16x32_bf16 v[72:75], v[160:163], v[212:215], v[72:75]
	v_mfma_f32_16x16x32_bf16 v[124:127], v[156:159], v[188:191], v[124:127]
	v_mfma_f32_16x16x32_bf16 v[120:123], v[164:167], v[188:191], v[120:123]
	v_mfma_f32_16x16x32_bf16 v[108:111], v[156:159], v[196:199], v[108:111]
	v_mfma_f32_16x16x32_bf16 v[104:107], v[164:167], v[196:199], v[104:107]
	v_mfma_f32_16x16x32_bf16 v[92:95], v[156:159], v[208:211], v[92:95]
	v_mfma_f32_16x16x32_bf16 v[88:91], v[164:167], v[208:211], v[88:91]
	v_mfma_f32_16x16x32_bf16 v[76:79], v[156:159], v[216:219], v[76:79]
	v_mfma_f32_16x16x32_bf16 v[72:75], v[164:167], v[216:219], v[72:75]
	v_mfma_f32_16x16x32_bf16 v[116:119], v[168:171], v[184:187], v[116:119]
	v_mfma_f32_16x16x32_bf16 v[112:115], v[176:179], v[184:187], v[112:115]
	v_mfma_f32_16x16x32_bf16 v[100:103], v[168:171], v[192:195], v[100:103]
	v_mfma_f32_16x16x32_bf16 v[96:99], v[176:179], v[192:195], v[96:99]
	v_mfma_f32_16x16x32_bf16 v[84:87], v[168:171], v[200:203], v[84:87]
	v_mfma_f32_16x16x32_bf16 v[80:83], v[176:179], v[200:203], v[80:83]
	v_mfma_f32_16x16x32_bf16 v[68:71], v[168:171], v[212:215], v[68:71]
	v_mfma_f32_16x16x32_bf16 v[64:67], v[176:179], v[212:215], v[64:67]
	v_mfma_f32_16x16x32_bf16 v[116:119], v[172:175], v[188:191], v[116:119]
	v_mfma_f32_16x16x32_bf16 v[112:115], v[180:183], v[188:191], v[112:115]
	v_mfma_f32_16x16x32_bf16 v[100:103], v[172:175], v[196:199], v[100:103]
	v_mfma_f32_16x16x32_bf16 v[96:99], v[180:183], v[196:199], v[96:99]
	v_mfma_f32_16x16x32_bf16 v[84:87], v[172:175], v[208:211], v[84:87]
	v_mfma_f32_16x16x32_bf16 v[80:83], v[180:183], v[208:211], v[80:83]
	v_mfma_f32_16x16x32_bf16 v[68:71], v[172:175], v[216:219], v[68:71]
	v_mfma_f32_16x16x32_bf16 v[64:67], v[180:183], v[216:219], v[64:67]
	s_barrier
	s_add_i32 s28, s54, s38
	s_mov_b32 m0, s28
	s_nop 0
	global_load_lds_dwordx4 v205, s[26:27]
	s_add_i32 m0, s28, 0x2000
	s_add_u32 s26, s26, 0x40080
	s_addc_u32 s27, s27, 0
	s_add_i32 s28, s55, s38
	global_load_lds_dwordx4 v221, s[98:99]
	s_mov_b32 m0, s28
	s_nop 0
	global_load_lds_dwordx4 v130, s[26:27]
	s_add_i32 m0, s28, 0x2000
	s_nop 0
	global_load_lds_dwordx4 v134, s[26:27]
	s_cmp_lg_u32 s53, 12
	s_cbranch_scc1 .Lbal_last_16
	s_mov_b32 m0, s43
	s_nop 0
	global_load_lds_dwordx4 v204, s[100:101]
	s_mov_b32 m0, s44
	s_nop 0
	global_load_lds_dwordx4 v220, s[100:101]
.Lbal_last_16:
	ds_read_b128 v[184:187], v153 offset:49152
	ds_read_b128 v[188:191], v153 offset:50176
	ds_read_b128 v[192:195], v153 offset:51200
	ds_read_b128 v[196:199], v153 offset:52224
	ds_read_b128 v[200:203], v153 offset:53248
	ds_read_b128 v[208:211], v153 offset:54272
	ds_read_b128 v[212:215], v153 offset:55296
	ds_read_b128 v[216:219], v153 offset:56320
	s_waitcnt vmcnt(6)
	s_waitcnt lgkmcnt(0)
	s_barrier
	s_waitcnt lgkmcnt(0)
	v_mfma_f32_16x16x32_bf16 v[60:63], v[144:147], v[184:187], v[60:63]
	v_mfma_f32_16x16x32_bf16 v[56:59], v[160:163], v[184:187], v[56:59]
	v_mfma_f32_16x16x32_bf16 v[44:47], v[144:147], v[192:195], v[44:47]
	v_mfma_f32_16x16x32_bf16 v[40:43], v[160:163], v[192:195], v[40:43]
	v_mfma_f32_16x16x32_bf16 v[28:31], v[144:147], v[200:203], v[28:31]
	v_mfma_f32_16x16x32_bf16 v[24:27], v[160:163], v[200:203], v[24:27]
	v_mfma_f32_16x16x32_bf16 v[12:15], v[144:147], v[212:215], v[12:15]
	v_mfma_f32_16x16x32_bf16 v[8:11], v[160:163], v[212:215], v[8:11]
	v_mfma_f32_16x16x32_bf16 v[60:63], v[156:159], v[188:191], v[60:63]
	v_mfma_f32_16x16x32_bf16 v[56:59], v[164:167], v[188:191], v[56:59]
	v_mfma_f32_16x16x32_bf16 v[44:47], v[156:159], v[196:199], v[44:47]
	v_mfma_f32_16x16x32_bf16 v[40:43], v[164:167], v[196:199], v[40:43]
	v_mfma_f32_16x16x32_bf16 v[28:31], v[156:159], v[208:211], v[28:31]
	v_mfma_f32_16x16x32_bf16 v[24:27], v[164:167], v[208:211], v[24:27]
	v_mfma_f32_16x16x32_bf16 v[12:15], v[156:159], v[216:219], v[12:15]
	v_mfma_f32_16x16x32_bf16 v[8:11], v[164:167], v[216:219], v[8:11]
	v_mfma_f32_16x16x32_bf16 v[52:55], v[168:171], v[184:187], v[52:55]
	v_mfma_f32_16x16x32_bf16 v[48:51], v[176:179], v[184:187], v[48:51]
	v_mfma_f32_16x16x32_bf16 v[36:39], v[168:171], v[192:195], v[36:39]
	v_mfma_f32_16x16x32_bf16 v[32:35], v[176:179], v[192:195], v[32:35]
	v_mfma_f32_16x16x32_bf16 v[20:23], v[168:171], v[200:203], v[20:23]
	v_mfma_f32_16x16x32_bf16 v[16:19], v[176:179], v[200:203], v[16:19]
	v_mfma_f32_16x16x32_bf16 v[4:7], v[168:171], v[212:215], v[4:7]
	v_mfma_f32_16x16x32_bf16 v[0:3], v[176:179], v[212:215], v[0:3]
	v_mfma_f32_16x16x32_bf16 v[52:55], v[172:175], v[188:191], v[52:55]
	v_mfma_f32_16x16x32_bf16 v[48:51], v[180:183], v[188:191], v[48:51]
	v_mfma_f32_16x16x32_bf16 v[36:39], v[172:175], v[196:199], v[36:39]
	v_mfma_f32_16x16x32_bf16 v[32:35], v[180:183], v[196:199], v[32:35]
	v_mfma_f32_16x16x32_bf16 v[20:23], v[172:175], v[208:211], v[20:23]
	v_mfma_f32_16x16x32_bf16 v[16:19], v[180:183], v[208:211], v[16:19]
	v_mfma_f32_16x16x32_bf16 v[4:7], v[172:175], v[216:219], v[4:7]
	v_mfma_f32_16x16x32_bf16 v[0:3], v[180:183], v[216:219], v[0:3]
	s_barrier
	s_add_i32 s53, s53, 2
	s_add_u32 s51, s51, 0x100
	s_addc_u32 s52, s52, 0
	s_add_u32 s6, s6, 0x100
	s_addc_u32 s7, s7, 0
	s_cmp_gt_u32 s53, 13
	s_cbranch_scc0 .LBB0_988
	s_setprio 0
	s_and_b64 vcc, exec, s[14:15]
	s_cbranch_vccz .LBB0_991
	s_barrier

.Lbal_first_15:
	s_add_u32 s26, s24, 0xfffe0080
	s_addc_u32 s27, s25, -1
	s_cmp_eq_u32 s50, 4
	s_cselect_b32 s29, s17, s27
	s_cselect_b32 s28, s46, s26
	s_cselect_b32 s27, s15, s49
	s_cselect_b32 s26, s47, s48
	s_add_i32 m0, s23, 0xc000
	s_nop 0
	global_load_lds_dwordx4 v138, s[24:25]
	s_add_i32 m0, s23, 0xe000
	s_nop 0
	global_load_lds_dwordx4 v136, s[24:25]
	ds_read_b128 v[144:147], v151
	ds_read_b128 v[154:157], v151 offset:1024
	ds_read_b128 v[158:161], v151 offset:2048
	ds_read_b128 v[162:165], v151 offset:3072
	ds_read_b128 v[166:169], v152
	ds_read_b128 v[170:173], v152 offset:1024
	ds_read_b128 v[174:177], v152 offset:2048
	ds_read_b128 v[178:181], v152 offset:3072
	ds_read_b128 v[182:185], v153
	ds_read_b128 v[186:189], v153 offset:1024
	ds_read_b128 v[190:193], v153 offset:2048
	ds_read_b128 v[194:197], v153 offset:3072
	ds_read_b128 v[198:201], v153 offset:4096
	ds_read_b128 v[202:205], v153 offset:5120
	ds_read_b128 v[208:211], v153 offset:6144
	ds_read_b128 v[212:215], v153 offset:7168
	s_waitcnt vmcnt(8)
	s_waitcnt lgkmcnt(0)
	s_barrier
	s_waitcnt lgkmcnt(0)
	v_mfma_f32_16x16x32_bf16 v[124:127], v[144:147], v[182:185], v[124:127]
	v_mfma_f32_16x16x32_bf16 v[120:123], v[158:161], v[182:185], v[120:123]
	v_mfma_f32_16x16x32_bf16 v[108:111], v[144:147], v[190:193], v[108:111]
	v_mfma_f32_16x16x32_bf16 v[104:107], v[158:161], v[190:193], v[104:107]
	v_mfma_f32_16x16x32_bf16 v[92:95], v[144:147], v[198:201], v[92:95]
	v_mfma_f32_16x16x32_bf16 v[88:91], v[158:161], v[198:201], v[88:91]
	v_mfma_f32_16x16x32_bf16 v[76:79], v[144:147], v[208:211], v[76:79]
	v_mfma_f32_16x16x32_bf16 v[72:75], v[158:161], v[208:211], v[72:75]
	v_mfma_f32_16x16x32_bf16 v[124:127], v[154:157], v[186:189], v[124:127]
	v_mfma_f32_16x16x32_bf16 v[120:123], v[162:165], v[186:189], v[120:123]
	v_mfma_f32_16x16x32_bf16 v[108:111], v[154:157], v[194:197], v[108:111]
	v_mfma_f32_16x16x32_bf16 v[104:107], v[162:165], v[194:197], v[104:107]
	v_mfma_f32_16x16x32_bf16 v[92:95], v[154:157], v[202:205], v[92:95]
	v_mfma_f32_16x16x32_bf16 v[88:91], v[162:165], v[202:205], v[88:91]
	v_mfma_f32_16x16x32_bf16 v[76:79], v[154:157], v[212:215], v[76:79]
	v_mfma_f32_16x16x32_bf16 v[72:75], v[162:165], v[212:215], v[72:75]
	v_mfma_f32_16x16x32_bf16 v[116:119], v[166:169], v[182:185], v[116:119]
	v_mfma_f32_16x16x32_bf16 v[112:115], v[174:177], v[182:185], v[112:115]
	v_mfma_f32_16x16x32_bf16 v[100:103], v[166:169], v[190:193], v[100:103]
	v_mfma_f32_16x16x32_bf16 v[96:99], v[174:177], v[190:193], v[96:99]
	v_mfma_f32_16x16x32_bf16 v[84:87], v[166:169], v[198:201], v[84:87]
	v_mfma_f32_16x16x32_bf16 v[80:83], v[174:177], v[198:201], v[80:83]
	v_mfma_f32_16x16x32_bf16 v[68:71], v[166:169], v[208:211], v[68:71]
	v_mfma_f32_16x16x32_bf16 v[64:67], v[174:177], v[208:211], v[64:67]
	v_mfma_f32_16x16x32_bf16 v[116:119], v[170:173], v[186:189], v[116:119]
	v_mfma_f32_16x16x32_bf16 v[112:115], v[178:181], v[186:189], v[112:115]
	v_mfma_f32_16x16x32_bf16 v[100:103], v[170:173], v[194:197], v[100:103]
	v_mfma_f32_16x16x32_bf16 v[96:99], v[178:181], v[194:197], v[96:99]
	v_mfma_f32_16x16x32_bf16 v[84:87], v[170:173], v[202:205], v[84:87]
	v_mfma_f32_16x16x32_bf16 v[80:83], v[178:181], v[202:205], v[80:83]
	v_mfma_f32_16x16x32_bf16 v[68:71], v[170:173], v[212:215], v[68:71]
	v_mfma_f32_16x16x32_bf16 v[64:67], v[178:181], v[212:215], v[64:67]
	s_barrier
	s_add_i32 s51, s43, s36
	s_mov_b32 m0, s51
	s_nop 0
	global_load_lds_dwordx4 v130, s[26:27]
	s_add_i32 m0, s51, 0x2000
	s_add_u32 s52, s26, 0x20000
	s_mov_b64 s[98:99], s[26:27]
	s_addc_u32 s53, s27, 0
	s_add_i32 s51, s44, s36
	global_load_lds_dwordx4 v134, s[26:27]
	s_mov_b32 m0, s51
	s_mov_b64 s[100:101], s[28:29]
	global_load_lds_dwordx4 v130, s[52:53]
	s_add_i32 m0, s51, 0x2000
	s_nop 0
	global_load_lds_dwordx4 v134, s[52:53]
	ds_read_b128 v[182:185], v153 offset:16384
	ds_read_b128 v[186:189], v153 offset:17408
	ds_read_b128 v[190:193], v153 offset:18432
	ds_read_b128 v[194:197], v153 offset:19456
	ds_read_b128 v[198:201], v153 offset:20480
	ds_read_b128 v[202:205], v153 offset:21504
	ds_read_b128 v[208:211], v153 offset:22528
	ds_read_b128 v[212:215], v153 offset:23552
	s_waitcnt vmcnt(6)
	s_waitcnt lgkmcnt(0)
	s_barrier
	s_waitcnt lgkmcnt(0)
	v_mfma_f32_16x16x32_bf16 v[60:63], v[144:147], v[182:185], v[60:63]
	v_mfma_f32_16x16x32_bf16 v[56:59], v[158:161], v[182:185], v[56:59]
	v_mfma_f32_16x16x32_bf16 v[44:47], v[144:147], v[190:193], v[44:47]
	v_mfma_f32_16x16x32_bf16 v[40:43], v[158:161], v[190:193], v[40:43]
	v_mfma_f32_16x16x32_bf16 v[28:31], v[144:147], v[198:201], v[28:31]
	v_mfma_f32_16x16x32_bf16 v[24:27], v[158:161], v[198:201], v[24:27]
	v_mfma_f32_16x16x32_bf16 v[12:15], v[144:147], v[208:211], v[12:15]
	v_mfma_f32_16x16x32_bf16 v[8:11], v[158:161], v[208:211], v[8:11]
	v_mfma_f32_16x16x32_bf16 v[60:63], v[154:157], v[186:189], v[60:63]
	v_mfma_f32_16x16x32_bf16 v[56:59], v[162:165], v[186:189], v[56:59]
	v_mfma_f32_16x16x32_bf16 v[44:47], v[154:157], v[194:197], v[44:47]
	v_mfma_f32_16x16x32_bf16 v[40:43], v[162:165], v[194:197], v[40:43]
	v_mfma_f32_16x16x32_bf16 v[28:31], v[154:157], v[202:205], v[28:31]
	v_mfma_f32_16x16x32_bf16 v[24:27], v[162:165], v[202:205], v[24:27]
	v_mfma_f32_16x16x32_bf16 v[12:15], v[154:157], v[212:215], v[12:15]
	v_mfma_f32_16x16x32_bf16 v[8:11], v[162:165], v[212:215], v[8:11]
	v_mfma_f32_16x16x32_bf16 v[52:55], v[166:169], v[182:185], v[52:55]
	v_mfma_f32_16x16x32_bf16 v[48:51], v[174:177], v[182:185], v[48:51]
	v_mfma_f32_16x16x32_bf16 v[36:39], v[166:169], v[190:193], v[36:39]
	v_mfma_f32_16x16x32_bf16 v[32:35], v[174:177], v[190:193], v[32:35]
	v_mfma_f32_16x16x32_bf16 v[20:23], v[166:169], v[198:201], v[20:23]
	v_mfma_f32_16x16x32_bf16 v[16:19], v[174:177], v[198:201], v[16:19]
	v_mfma_f32_16x16x32_bf16 v[4:7], v[166:169], v[208:211], v[4:7]
	v_mfma_f32_16x16x32_bf16 v[0:3], v[174:177], v[208:211], v[0:3]
	v_mfma_f32_16x16x32_bf16 v[52:55], v[170:173], v[186:189], v[52:55]
	v_mfma_f32_16x16x32_bf16 v[48:51], v[178:181], v[186:189], v[48:51]
	v_mfma_f32_16x16x32_bf16 v[36:39], v[170:173], v[194:197], v[36:39]
	v_mfma_f32_16x16x32_bf16 v[32:35], v[178:181], v[194:197], v[32:35]
	v_mfma_f32_16x16x32_bf16 v[20:23], v[170:173], v[202:205], v[20:23]
	v_mfma_f32_16x16x32_bf16 v[16:19], v[178:181], v[202:205], v[16:19]
	v_mfma_f32_16x16x32_bf16 v[4:7], v[170:173], v[212:215], v[4:7]
	v_mfma_f32_16x16x32_bf16 v[0:3], v[178:181], v[212:215], v[0:3]
	s_barrier
	s_mov_b32 m0, s23
	s_nop 0
	global_load_lds_dwordx4 v128, s[28:29]
	s_mov_b32 m0, s37
	s_nop 0
	global_load_lds_dwordx4 v132, s[28:29]
	s_add_i32 s51, 0, 0x18000
	s_add_i32 s52, 0, 0x1c000
	s_add_u32 s28, s28, 0x20000
	s_addc_u32 s29, s29, 0
	s_mov_b32 m0, s38
	s_nop 0
	global_load_lds_dwordx4 v128, s[28:29]
	s_mov_b32 m0, s39
	s_nop 0
	global_load_lds_dwordx4 v132, s[28:29]
	v_add_u32_e32 v162, s51, v149
	v_add_u32_e32 v178, s52, v149
	ds_read_b128 v[144:147], v162
	ds_read_b128 v[154:157], v162 offset:1024
	ds_read_b128 v[158:161], v162 offset:2048
	ds_read_b128 v[162:165], v162 offset:3072
	ds_read_b128 v[166:169], v178
	ds_read_b128 v[170:173], v178 offset:1024
	ds_read_b128 v[174:177], v178 offset:2048
	ds_read_b128 v[178:181], v178 offset:3072
	ds_read_b128 v[182:185], v153 offset:32768
	ds_read_b128 v[186:189], v153 offset:33792
	ds_read_b128 v[190:193], v153 offset:34816
	ds_read_b128 v[194:197], v153 offset:35840
	ds_read_b128 v[198:201], v153 offset:36864
	ds_read_b128 v[202:205], v153 offset:37888
	ds_read_b128 v[208:211], v153 offset:38912
	ds_read_b128 v[212:215], v153 offset:39936
	s_waitcnt vmcnt(8)
	s_waitcnt lgkmcnt(0)
	s_barrier
	s_waitcnt lgkmcnt(0)
	v_mfma_f32_16x16x32_bf16 v[124:127], v[144:147], v[182:185], v[124:127]
	v_mfma_f32_16x16x32_bf16 v[120:123], v[158:161], v[182:185], v[120:123]
	v_mfma_f32_16x16x32_bf16 v[108:111], v[144:147], v[190:193], v[108:111]
	v_mfma_f32_16x16x32_bf16 v[104:107], v[158:161], v[190:193], v[104:107]
	v_mfma_f32_16x16x32_bf16 v[92:95], v[144:147], v[198:201], v[92:95]
	v_mfma_f32_16x16x32_bf16 v[88:91], v[158:161], v[198:201], v[88:91]
	v_mfma_f32_16x16x32_bf16 v[76:79], v[144:147], v[208:211], v[76:79]
	v_mfma_f32_16x16x32_bf16 v[72:75], v[158:161], v[208:211], v[72:75]
	v_mfma_f32_16x16x32_bf16 v[124:127], v[154:157], v[186:189], v[124:127]
	v_mfma_f32_16x16x32_bf16 v[120:123], v[162:165], v[186:189], v[120:123]
	v_mfma_f32_16x16x32_bf16 v[108:111], v[154:157], v[194:197], v[108:111]
	v_mfma_f32_16x16x32_bf16 v[104:107], v[162:165], v[194:197], v[104:107]
	v_mfma_f32_16x16x32_bf16 v[92:95], v[154:157], v[202:205], v[92:95]
	v_mfma_f32_16x16x32_bf16 v[88:91], v[162:165], v[202:205], v[88:91]
	v_mfma_f32_16x16x32_bf16 v[76:79], v[154:157], v[212:215], v[76:79]
	v_mfma_f32_16x16x32_bf16 v[72:75], v[162:165], v[212:215], v[72:75]
	v_mfma_f32_16x16x32_bf16 v[116:119], v[166:169], v[182:185], v[116:119]
	v_mfma_f32_16x16x32_bf16 v[112:115], v[174:177], v[182:185], v[112:115]
	v_mfma_f32_16x16x32_bf16 v[100:103], v[166:169], v[190:193], v[100:103]
	v_mfma_f32_16x16x32_bf16 v[96:99], v[174:177], v[190:193], v[96:99]
	v_mfma_f32_16x16x32_bf16 v[84:87], v[166:169], v[198:201], v[84:87]
	v_mfma_f32_16x16x32_bf16 v[80:83], v[174:177], v[198:201], v[80:83]
	v_mfma_f32_16x16x32_bf16 v[68:71], v[166:169], v[208:211], v[68:71]
	v_mfma_f32_16x16x32_bf16 v[64:67], v[174:177], v[208:211], v[64:67]
	v_mfma_f32_16x16x32_bf16 v[116:119], v[170:173], v[186:189], v[116:119]
	v_mfma_f32_16x16x32_bf16 v[112:115], v[178:181], v[186:189], v[112:115]
	v_mfma_f32_16x16x32_bf16 v[100:103], v[170:173], v[194:197], v[100:103]
	v_mfma_f32_16x16x32_bf16 v[96:99], v[178:181], v[194:197], v[96:99]
	v_mfma_f32_16x16x32_bf16 v[84:87], v[170:173], v[202:205], v[84:87]
	v_mfma_f32_16x16x32_bf16 v[80:83], v[178:181], v[202:205], v[80:83]
	v_mfma_f32_16x16x32_bf16 v[68:71], v[170:173], v[212:215], v[68:71]
	v_mfma_f32_16x16x32_bf16 v[64:67], v[178:181], v[212:215], v[64:67]
	s_barrier
	s_add_i32 s28, s51, s36
	s_mov_b32 m0, s28
	s_nop 0
	global_load_lds_dwordx4 v217, s[26:27]
	s_add_i32 m0, s28, 0x2000
	s_add_u32 s26, s26, 0x20080
	s_addc_u32 s27, s27, 0
	s_add_i32 s28, s52, s36
	global_load_lds_dwordx4 v219, s[98:99]
	s_mov_b32 m0, s28
	s_nop 0
	global_load_lds_dwordx4 v130, s[26:27]
	s_add_i32 m0, s28, 0x2000
	s_nop 0
	global_load_lds_dwordx4 v134, s[26:27]
	s_cmp_lg_u32 s50, 4
	s_cbranch_scc1 .Lbal_last_15
	s_mov_b32 m0, s41
	s_nop 0
	global_load_lds_dwordx4 v216, s[100:101]
	s_mov_b32 m0, s42
	s_nop 0
	global_load_lds_dwordx4 v218, s[100:101]
.Lbal_last_15:
	ds_read_b128 v[182:185], v153 offset:49152
	ds_read_b128 v[186:189], v153 offset:50176
	ds_read_b128 v[190:193], v153 offset:51200
	ds_read_b128 v[194:197], v153 offset:52224
	ds_read_b128 v[198:201], v153 offset:53248
	ds_read_b128 v[202:205], v153 offset:54272
	ds_read_b128 v[208:211], v153 offset:55296
	ds_read_b128 v[212:215], v153 offset:56320
	s_waitcnt vmcnt(6)
	s_waitcnt lgkmcnt(0)
	s_barrier
	s_waitcnt lgkmcnt(0)
	v_mfma_f32_16x16x32_bf16 v[60:63], v[144:147], v[182:185], v[60:63]
	v_mfma_f32_16x16x32_bf16 v[56:59], v[158:161], v[182:185], v[56:59]
	v_mfma_f32_16x16x32_bf16 v[44:47], v[144:147], v[190:193], v[44:47]
	v_mfma_f32_16x16x32_bf16 v[40:43], v[158:161], v[190:193], v[40:43]
	v_mfma_f32_16x16x32_bf16 v[28:31], v[144:147], v[198:201], v[28:31]
	v_mfma_f32_16x16x32_bf16 v[24:27], v[158:161], v[198:201], v[24:27]
	v_mfma_f32_16x16x32_bf16 v[12:15], v[144:147], v[208:211], v[12:15]
	v_mfma_f32_16x16x32_bf16 v[8:11], v[158:161], v[208:211], v[8:11]
	v_mfma_f32_16x16x32_bf16 v[60:63], v[154:157], v[186:189], v[60:63]
	v_mfma_f32_16x16x32_bf16 v[56:59], v[162:165], v[186:189], v[56:59]
	v_mfma_f32_16x16x32_bf16 v[44:47], v[154:157], v[194:197], v[44:47]
	v_mfma_f32_16x16x32_bf16 v[40:43], v[162:165], v[194:197], v[40:43]
	v_mfma_f32_16x16x32_bf16 v[28:31], v[154:157], v[202:205], v[28:31]
	v_mfma_f32_16x16x32_bf16 v[24:27], v[162:165], v[202:205], v[24:27]
	v_mfma_f32_16x16x32_bf16 v[12:15], v[154:157], v[212:215], v[12:15]
	v_mfma_f32_16x16x32_bf16 v[8:11], v[162:165], v[212:215], v[8:11]
	v_mfma_f32_16x16x32_bf16 v[52:55], v[166:169], v[182:185], v[52:55]
	v_mfma_f32_16x16x32_bf16 v[48:51], v[174:177], v[182:185], v[48:51]
	v_mfma_f32_16x16x32_bf16 v[36:39], v[166:169], v[190:193], v[36:39]
	v_mfma_f32_16x16x32_bf16 v[32:35], v[174:177], v[190:193], v[32:35]
	v_mfma_f32_16x16x32_bf16 v[20:23], v[166:169], v[198:201], v[20:23]
	v_mfma_f32_16x16x32_bf16 v[16:19], v[174:177], v[198:201], v[16:19]
	v_mfma_f32_16x16x32_bf16 v[4:7], v[166:169], v[208:211], v[4:7]
	v_mfma_f32_16x16x32_bf16 v[0:3], v[174:177], v[208:211], v[0:3]
	v_mfma_f32_16x16x32_bf16 v[52:55], v[170:173], v[186:189], v[52:55]
	v_mfma_f32_16x16x32_bf16 v[48:51], v[178:181], v[186:189], v[48:51]
	v_mfma_f32_16x16x32_bf16 v[36:39], v[170:173], v[194:197], v[36:39]
	v_mfma_f32_16x16x32_bf16 v[32:35], v[178:181], v[194:197], v[32:35]
	v_mfma_f32_16x16x32_bf16 v[20:23], v[170:173], v[202:205], v[20:23]
	v_mfma_f32_16x16x32_bf16 v[16:19], v[178:181], v[202:205], v[16:19]
	v_mfma_f32_16x16x32_bf16 v[4:7], v[170:173], v[212:215], v[4:7]
	v_mfma_f32_16x16x32_bf16 v[0:3], v[178:181], v[212:215], v[0:3]
	s_barrier
	s_add_i32 s50, s50, 2
	s_add_u32 s48, s48, 0x100
	s_addc_u32 s49, s49, 0
	s_add_u32 s24, s24, 0x100
	s_addc_u32 s25, s25, 0
	s_cmp_gt_u32 s50, 5
	s_cbranch_scc0 .LBB0_1193
	s_setprio 0
	s_and_b64 vcc, exec, s[12:13]
	s_cbranch_vccz .LBB0_1196
	s_barrier

.Lbal_first_13:
	s_add_u32 s26, s24, 0xfffc0080
	s_addc_u32 s27, s25, -1
	s_cmp_eq_u32 s53, 12
	s_cselect_b32 s29, s19, s27
	s_cselect_b32 s28, s49, s26
	s_cselect_b32 s27, s17, s52
	s_cselect_b32 s26, s50, s51
	s_add_i32 m0, s39, 0xc000
	s_nop 0
	global_load_lds_dwordx4 v138, s[24:25]
	s_add_i32 m0, s39, 0xe000
	s_nop 0
	global_load_lds_dwordx4 v136, s[24:25]
	ds_read_b128 v[144:147], v151
	ds_read_b128 v[156:159], v151 offset:1024
	ds_read_b128 v[160:163], v151 offset:2048
	ds_read_b128 v[164:167], v151 offset:3072
	ds_read_b128 v[168:171], v152
	ds_read_b128 v[172:175], v152 offset:1024
	ds_read_b128 v[176:179], v152 offset:2048
	ds_read_b128 v[180:183], v152 offset:3072
	ds_read_b128 v[184:187], v153
	ds_read_b128 v[188:191], v153 offset:1024
	ds_read_b128 v[192:195], v153 offset:2048
	ds_read_b128 v[196:199], v153 offset:3072
	ds_read_b128 v[200:203], v153 offset:4096
	ds_read_b128 v[208:211], v153 offset:5120
	ds_read_b128 v[212:215], v153 offset:6144
	ds_read_b128 v[216:219], v153 offset:7168
	s_waitcnt vmcnt(8)
	s_waitcnt lgkmcnt(0)
	s_barrier
	s_waitcnt lgkmcnt(0)
	v_mfma_f32_16x16x32_bf16 v[124:127], v[144:147], v[184:187], v[124:127]
	v_mfma_f32_16x16x32_bf16 v[120:123], v[160:163], v[184:187], v[120:123]
	v_mfma_f32_16x16x32_bf16 v[108:111], v[144:147], v[192:195], v[108:111]
	v_mfma_f32_16x16x32_bf16 v[104:107], v[160:163], v[192:195], v[104:107]
	v_mfma_f32_16x16x32_bf16 v[92:95], v[144:147], v[200:203], v[92:95]
	v_mfma_f32_16x16x32_bf16 v[88:91], v[160:163], v[200:203], v[88:91]
	v_mfma_f32_16x16x32_bf16 v[76:79], v[144:147], v[212:215], v[76:79]
	v_mfma_f32_16x16x32_bf16 v[72:75], v[160:163], v[212:215], v[72:75]
	v_mfma_f32_16x16x32_bf16 v[124:127], v[156:159], v[188:191], v[124:127]
	v_mfma_f32_16x16x32_bf16 v[120:123], v[164:167], v[188:191], v[120:123]
	v_mfma_f32_16x16x32_bf16 v[108:111], v[156:159], v[196:199], v[108:111]
	v_mfma_f32_16x16x32_bf16 v[104:107], v[164:167], v[196:199], v[104:107]
	v_mfma_f32_16x16x32_bf16 v[92:95], v[156:159], v[208:211], v[92:95]
	v_mfma_f32_16x16x32_bf16 v[88:91], v[164:167], v[208:211], v[88:91]
	v_mfma_f32_16x16x32_bf16 v[76:79], v[156:159], v[216:219], v[76:79]
	v_mfma_f32_16x16x32_bf16 v[72:75], v[164:167], v[216:219], v[72:75]
	v_mfma_f32_16x16x32_bf16 v[116:119], v[168:171], v[184:187], v[116:119]
	v_mfma_f32_16x16x32_bf16 v[112:115], v[176:179], v[184:187], v[112:115]
	v_mfma_f32_16x16x32_bf16 v[100:103], v[168:171], v[192:195], v[100:103]
	v_mfma_f32_16x16x32_bf16 v[96:99], v[176:179], v[192:195], v[96:99]
	v_mfma_f32_16x16x32_bf16 v[84:87], v[168:171], v[200:203], v[84:87]
	v_mfma_f32_16x16x32_bf16 v[80:83], v[176:179], v[200:203], v[80:83]
	v_mfma_f32_16x16x32_bf16 v[68:71], v[168:171], v[212:215], v[68:71]
	v_mfma_f32_16x16x32_bf16 v[64:67], v[176:179], v[212:215], v[64:67]
	v_mfma_f32_16x16x32_bf16 v[116:119], v[172:175], v[188:191], v[116:119]
	v_mfma_f32_16x16x32_bf16 v[112:115], v[180:183], v[188:191], v[112:115]
	v_mfma_f32_16x16x32_bf16 v[100:103], v[172:175], v[196:199], v[100:103]
	v_mfma_f32_16x16x32_bf16 v[96:99], v[180:183], v[196:199], v[96:99]
	v_mfma_f32_16x16x32_bf16 v[84:87], v[172:175], v[208:211], v[84:87]
	v_mfma_f32_16x16x32_bf16 v[80:83], v[180:183], v[208:211], v[80:83]
	v_mfma_f32_16x16x32_bf16 v[68:71], v[172:175], v[216:219], v[68:71]
	v_mfma_f32_16x16x32_bf16 v[64:67], v[180:183], v[216:219], v[64:67]
	s_barrier
	s_add_i32 s54, s46, s38
	s_mov_b32 m0, s54
	s_nop 0
	global_load_lds_dwordx4 v130, s[26:27]
	s_add_i32 m0, s54, 0x2000
	s_add_u32 s54, s26, 0x40000
	s_mov_b64 s[98:99], s[26:27]
	s_addc_u32 s55, s27, 0
	s_add_i32 s56, s47, s38
	global_load_lds_dwordx4 v134, s[26:27]
	s_mov_b32 m0, s56
	s_mov_b64 s[100:101], s[28:29]
	global_load_lds_dwordx4 v130, s[54:55]
	s_add_i32 m0, s56, 0x2000
	s_nop 0
	global_load_lds_dwordx4 v134, s[54:55]
	ds_read_b128 v[184:187], v153 offset:16384
	ds_read_b128 v[188:191], v153 offset:17408
	ds_read_b128 v[192:195], v153 offset:18432
	ds_read_b128 v[196:199], v153 offset:19456
	ds_read_b128 v[200:203], v153 offset:20480
	ds_read_b128 v[208:211], v153 offset:21504
	ds_read_b128 v[212:215], v153 offset:22528
	ds_read_b128 v[216:219], v153 offset:23552
	s_waitcnt vmcnt(6)
	s_waitcnt lgkmcnt(0)
	s_barrier
	s_waitcnt lgkmcnt(0)
	v_mfma_f32_16x16x32_bf16 v[60:63], v[144:147], v[184:187], v[60:63]
	v_mfma_f32_16x16x32_bf16 v[56:59], v[160:163], v[184:187], v[56:59]
	v_mfma_f32_16x16x32_bf16 v[44:47], v[144:147], v[192:195], v[44:47]
	v_mfma_f32_16x16x32_bf16 v[40:43], v[160:163], v[192:195], v[40:43]
	v_mfma_f32_16x16x32_bf16 v[28:31], v[144:147], v[200:203], v[28:31]
	v_mfma_f32_16x16x32_bf16 v[24:27], v[160:163], v[200:203], v[24:27]
	v_mfma_f32_16x16x32_bf16 v[12:15], v[144:147], v[212:215], v[12:15]
	v_mfma_f32_16x16x32_bf16 v[8:11], v[160:163], v[212:215], v[8:11]
	v_mfma_f32_16x16x32_bf16 v[60:63], v[156:159], v[188:191], v[60:63]
	v_mfma_f32_16x16x32_bf16 v[56:59], v[164:167], v[188:191], v[56:59]
	v_mfma_f32_16x16x32_bf16 v[44:47], v[156:159], v[196:199], v[44:47]
	v_mfma_f32_16x16x32_bf16 v[40:43], v[164:167], v[196:199], v[40:43]
	v_mfma_f32_16x16x32_bf16 v[28:31], v[156:159], v[208:211], v[28:31]
	v_mfma_f32_16x16x32_bf16 v[24:27], v[164:167], v[208:211], v[24:27]
	v_mfma_f32_16x16x32_bf16 v[12:15], v[156:159], v[216:219], v[12:15]
	v_mfma_f32_16x16x32_bf16 v[8:11], v[164:167], v[216:219], v[8:11]
	v_mfma_f32_16x16x32_bf16 v[52:55], v[168:171], v[184:187], v[52:55]
	v_mfma_f32_16x16x32_bf16 v[48:51], v[176:179], v[184:187], v[48:51]
	v_mfma_f32_16x16x32_bf16 v[36:39], v[168:171], v[192:195], v[36:39]
	v_mfma_f32_16x16x32_bf16 v[32:35], v[176:179], v[192:195], v[32:35]
	v_mfma_f32_16x16x32_bf16 v[20:23], v[168:171], v[200:203], v[20:23]
	v_mfma_f32_16x16x32_bf16 v[16:19], v[176:179], v[200:203], v[16:19]
	v_mfma_f32_16x16x32_bf16 v[4:7], v[168:171], v[212:215], v[4:7]
	v_mfma_f32_16x16x32_bf16 v[0:3], v[176:179], v[212:215], v[0:3]
	v_mfma_f32_16x16x32_bf16 v[52:55], v[172:175], v[188:191], v[52:55]
	v_mfma_f32_16x16x32_bf16 v[48:51], v[180:183], v[188:191], v[48:51]
	v_mfma_f32_16x16x32_bf16 v[36:39], v[172:175], v[196:199], v[36:39]
	v_mfma_f32_16x16x32_bf16 v[32:35], v[180:183], v[196:199], v[32:35]
	v_mfma_f32_16x16x32_bf16 v[20:23], v[172:175], v[208:211], v[20:23]
	v_mfma_f32_16x16x32_bf16 v[16:19], v[180:183], v[208:211], v[16:19]
	v_mfma_f32_16x16x32_bf16 v[4:7], v[172:175], v[216:219], v[4:7]
	v_mfma_f32_16x16x32_bf16 v[0:3], v[180:183], v[216:219], v[0:3]
	s_barrier
	s_mov_b32 m0, s39
	s_nop 0
	global_load_lds_dwordx4 v128, s[28:29]
	s_mov_b32 m0, s40
	s_nop 0
	global_load_lds_dwordx4 v132, s[28:29]
	s_add_i32 s54, 0, 0x18000
	s_add_i32 s55, 0, 0x1c000
	s_add_u32 s28, s28, 0x40000
	s_addc_u32 s29, s29, 0
	s_mov_b32 m0, s41
	s_nop 0
	global_load_lds_dwordx4 v128, s[28:29]
	s_mov_b32 m0, s42
	s_nop 0
	global_load_lds_dwordx4 v132, s[28:29]
	v_add_u32_e32 v155, s54, v149
	ds_read_b128 v[144:147], v155
	ds_read_b128 v[156:159], v155 offset:1024
	ds_read_b128 v[160:163], v155 offset:2048
	ds_read_b128 v[164:167], v155 offset:3072
	v_add_u32_e32 v155, s55, v149
	ds_read_b128 v[168:171], v155
	ds_read_b128 v[172:175], v155 offset:1024
	ds_read_b128 v[176:179], v155 offset:2048
	ds_read_b128 v[180:183], v155 offset:3072
	ds_read_b128 v[184:187], v153 offset:32768
	ds_read_b128 v[188:191], v153 offset:33792
	ds_read_b128 v[192:195], v153 offset:34816
	ds_read_b128 v[196:199], v153 offset:35840
	ds_read_b128 v[200:203], v153 offset:36864
	ds_read_b128 v[208:211], v153 offset:37888
	ds_read_b128 v[212:215], v153 offset:38912
	ds_read_b128 v[216:219], v153 offset:39936
	s_waitcnt vmcnt(8)
	s_waitcnt lgkmcnt(0)
	s_barrier
	s_waitcnt lgkmcnt(0)
	v_mfma_f32_16x16x32_bf16 v[124:127], v[144:147], v[184:187], v[124:127]
	v_mfma_f32_16x16x32_bf16 v[120:123], v[160:163], v[184:187], v[120:123]
	v_mfma_f32_16x16x32_bf16 v[108:111], v[144:147], v[192:195], v[108:111]
	v_mfma_f32_16x16x32_bf16 v[104:107], v[160:163], v[192:195], v[104:107]
	v_mfma_f32_16x16x32_bf16 v[92:95], v[144:147], v[200:203], v[92:95]
	v_mfma_f32_16x16x32_bf16 v[88:91], v[160:163], v[200:203], v[88:91]
	v_mfma_f32_16x16x32_bf16 v[76:79], v[144:147], v[212:215], v[76:79]
	v_mfma_f32_16x16x32_bf16 v[72:75], v[160:163], v[212:215], v[72:75]
	v_mfma_f32_16x16x32_bf16 v[124:127], v[156:159], v[188:191], v[124:127]
	v_mfma_f32_16x16x32_bf16 v[120:123], v[164:167], v[188:191], v[120:123]
	v_mfma_f32_16x16x32_bf16 v[108:111], v[156:159], v[196:199], v[108:111]
	v_mfma_f32_16x16x32_bf16 v[104:107], v[164:167], v[196:199], v[104:107]
	v_mfma_f32_16x16x32_bf16 v[92:95], v[156:159], v[208:211], v[92:95]
	v_mfma_f32_16x16x32_bf16 v[88:91], v[164:167], v[208:211], v[88:91]
	v_mfma_f32_16x16x32_bf16 v[76:79], v[156:159], v[216:219], v[76:79]
	v_mfma_f32_16x16x32_bf16 v[72:75], v[164:167], v[216:219], v[72:75]
	v_mfma_f32_16x16x32_bf16 v[116:119], v[168:171], v[184:187], v[116:119]
	v_mfma_f32_16x16x32_bf16 v[112:115], v[176:179], v[184:187], v[112:115]
	v_mfma_f32_16x16x32_bf16 v[100:103], v[168:171], v[192:195], v[100:103]
	v_mfma_f32_16x16x32_bf16 v[96:99], v[176:179], v[192:195], v[96:99]
	v_mfma_f32_16x16x32_bf16 v[84:87], v[168:171], v[200:203], v[84:87]
	v_mfma_f32_16x16x32_bf16 v[80:83], v[176:179], v[200:203], v[80:83]
	v_mfma_f32_16x16x32_bf16 v[68:71], v[168:171], v[212:215], v[68:71]
	v_mfma_f32_16x16x32_bf16 v[64:67], v[176:179], v[212:215], v[64:67]
	v_mfma_f32_16x16x32_bf16 v[116:119], v[172:175], v[188:191], v[116:119]
	v_mfma_f32_16x16x32_bf16 v[112:115], v[180:183], v[188:191], v[112:115]
	v_mfma_f32_16x16x32_bf16 v[100:103], v[172:175], v[196:199], v[100:103]
	v_mfma_f32_16x16x32_bf16 v[96:99], v[180:183], v[196:199], v[96:99]
	v_mfma_f32_16x16x32_bf16 v[84:87], v[172:175], v[208:211], v[84:87]
	v_mfma_f32_16x16x32_bf16 v[80:83], v[180:183], v[208:211], v[80:83]
	v_mfma_f32_16x16x32_bf16 v[68:71], v[172:175], v[216:219], v[68:71]
	v_mfma_f32_16x16x32_bf16 v[64:67], v[180:183], v[216:219], v[64:67]
	s_barrier
	s_add_i32 s28, s54, s38
	s_mov_b32 m0, s28
	s_nop 0
	global_load_lds_dwordx4 v205, s[26:27]
	s_add_i32 m0, s28, 0x2000
	s_add_u32 s26, s26, 0x40080
	s_addc_u32 s27, s27, 0
	s_add_i32 s28, s55, s38
	global_load_lds_dwordx4 v221, s[98:99]
	s_mov_b32 m0, s28
	s_nop 0
	global_load_lds_dwordx4 v130, s[26:27]
	s_add_i32 m0, s28, 0x2000
	s_nop 0
	global_load_lds_dwordx4 v134, s[26:27]
	s_cmp_lg_u32 s53, 12
	s_cbranch_scc1 .Lbal_last_13
	s_mov_b32 m0, s44
	s_nop 0
	global_load_lds_dwordx4 v204, s[100:101]
	s_mov_b32 m0, s45
	s_nop 0
	global_load_lds_dwordx4 v220, s[100:101]
.Lbal_last_13:
	ds_read_b128 v[184:187], v153 offset:49152
	ds_read_b128 v[188:191], v153 offset:50176
	ds_read_b128 v[192:195], v153 offset:51200
	ds_read_b128 v[196:199], v153 offset:52224
	ds_read_b128 v[200:203], v153 offset:53248
	ds_read_b128 v[208:211], v153 offset:54272
	ds_read_b128 v[212:215], v153 offset:55296
	ds_read_b128 v[216:219], v153 offset:56320
	s_waitcnt vmcnt(6)
	s_waitcnt lgkmcnt(0)
	s_barrier
	s_waitcnt lgkmcnt(0)
	v_mfma_f32_16x16x32_bf16 v[60:63], v[144:147], v[184:187], v[60:63]
	v_mfma_f32_16x16x32_bf16 v[56:59], v[160:163], v[184:187], v[56:59]
	v_mfma_f32_16x16x32_bf16 v[44:47], v[144:147], v[192:195], v[44:47]
	v_mfma_f32_16x16x32_bf16 v[40:43], v[160:163], v[192:195], v[40:43]
	v_mfma_f32_16x16x32_bf16 v[28:31], v[144:147], v[200:203], v[28:31]
	v_mfma_f32_16x16x32_bf16 v[24:27], v[160:163], v[200:203], v[24:27]
	v_mfma_f32_16x16x32_bf16 v[12:15], v[144:147], v[212:215], v[12:15]
	v_mfma_f32_16x16x32_bf16 v[8:11], v[160:163], v[212:215], v[8:11]
	v_mfma_f32_16x16x32_bf16 v[60:63], v[156:159], v[188:191], v[60:63]
	v_mfma_f32_16x16x32_bf16 v[56:59], v[164:167], v[188:191], v[56:59]
	v_mfma_f32_16x16x32_bf16 v[44:47], v[156:159], v[196:199], v[44:47]
	v_mfma_f32_16x16x32_bf16 v[40:43], v[164:167], v[196:199], v[40:43]
	v_mfma_f32_16x16x32_bf16 v[28:31], v[156:159], v[208:211], v[28:31]
	v_mfma_f32_16x16x32_bf16 v[24:27], v[164:167], v[208:211], v[24:27]
	v_mfma_f32_16x16x32_bf16 v[12:15], v[156:159], v[216:219], v[12:15]
	v_mfma_f32_16x16x32_bf16 v[8:11], v[164:167], v[216:219], v[8:11]
	v_mfma_f32_16x16x32_bf16 v[52:55], v[168:171], v[184:187], v[52:55]
	v_mfma_f32_16x16x32_bf16 v[48:51], v[176:179], v[184:187], v[48:51]
	v_mfma_f32_16x16x32_bf16 v[36:39], v[168:171], v[192:195], v[36:39]
	v_mfma_f32_16x16x32_bf16 v[32:35], v[176:179], v[192:195], v[32:35]
	v_mfma_f32_16x16x32_bf16 v[20:23], v[168:171], v[200:203], v[20:23]
	v_mfma_f32_16x16x32_bf16 v[16:19], v[176:179], v[200:203], v[16:19]
	v_mfma_f32_16x16x32_bf16 v[4:7], v[168:171], v[212:215], v[4:7]
	v_mfma_f32_16x16x32_bf16 v[0:3], v[176:179], v[212:215], v[0:3]
	v_mfma_f32_16x16x32_bf16 v[52:55], v[172:175], v[188:191], v[52:55]
	v_mfma_f32_16x16x32_bf16 v[48:51], v[180:183], v[188:191], v[48:51]
	v_mfma_f32_16x16x32_bf16 v[36:39], v[172:175], v[196:199], v[36:39]
	v_mfma_f32_16x16x32_bf16 v[32:35], v[180:183], v[196:199], v[32:35]
	v_mfma_f32_16x16x32_bf16 v[20:23], v[172:175], v[208:211], v[20:23]
	v_mfma_f32_16x16x32_bf16 v[16:19], v[180:183], v[208:211], v[16:19]
	v_mfma_f32_16x16x32_bf16 v[4:7], v[172:175], v[216:219], v[4:7]
	v_mfma_f32_16x16x32_bf16 v[0:3], v[180:183], v[216:219], v[0:3]
	s_barrier
	s_add_i32 s53, s53, 2
	s_add_u32 s51, s51, 0x100
	s_addc_u32 s52, s52, 0
	s_add_u32 s24, s24, 0x100
	s_addc_u32 s25, s25, 0
	s_cmp_gt_u32 s53, 13
	s_cbranch_scc0 .LBB0_1365
	s_setprio 0
	s_and_b64 vcc, exec, s[14:15]
	s_cbranch_vccz .LBB0_1368
	s_barrier

.Lbal_first_11:
	s_add_u32 s38, s36, 0xfffc0080
	s_addc_u32 s39, s37, -1
	s_cmp_eq_u32 s61, 12
	s_cselect_b32 s41, s3, s39
	s_cselect_b32 s40, s29, s38
	s_cselect_b32 s39, s27, s60
	s_cselect_b32 s38, s58, s59
	s_add_i32 m0, s46, 0xc000
	s_nop 0
	global_load_lds_dwordx4 v134, s[36:37]
	s_add_i32 m0, s46, 0xe000
	s_nop 0
	global_load_lds_dwordx4 v132, s[36:37]
	ds_read_b128 v[140:143], v151
	ds_read_b128 v[144:147], v151 offset:1024
	ds_read_b128 v[156:159], v151 offset:2048
	ds_read_b128 v[160:163], v151 offset:3072
	ds_read_b128 v[164:167], v152
	ds_read_b128 v[168:171], v152 offset:1024
	ds_read_b128 v[172:175], v152 offset:2048
	ds_read_b128 v[176:179], v152 offset:3072
	ds_read_b128 v[180:183], v153
	ds_read_b128 v[184:187], v153 offset:1024
	ds_read_b128 v[188:191], v153 offset:2048
	ds_read_b128 v[192:195], v153 offset:3072
	ds_read_b128 v[196:199], v153 offset:4096
	ds_read_b128 v[200:203], v153 offset:5120
	ds_read_b128 v[208:211], v153 offset:6144
	ds_read_b128 v[212:215], v153 offset:7168
	s_waitcnt vmcnt(8)
	s_waitcnt lgkmcnt(0)
	s_barrier
	s_waitcnt lgkmcnt(0)
	v_mfma_f32_16x16x32_bf16 v[124:127], v[140:143], v[180:183], v[124:127]
	v_mfma_f32_16x16x32_bf16 v[120:123], v[156:159], v[180:183], v[120:123]
	v_mfma_f32_16x16x32_bf16 v[108:111], v[140:143], v[188:191], v[108:111]
	v_mfma_f32_16x16x32_bf16 v[104:107], v[156:159], v[188:191], v[104:107]
	v_mfma_f32_16x16x32_bf16 v[92:95], v[140:143], v[196:199], v[92:95]
	v_mfma_f32_16x16x32_bf16 v[88:91], v[156:159], v[196:199], v[88:91]
	v_mfma_f32_16x16x32_bf16 v[76:79], v[140:143], v[208:211], v[76:79]
	v_mfma_f32_16x16x32_bf16 v[72:75], v[156:159], v[208:211], v[72:75]
	v_mfma_f32_16x16x32_bf16 v[124:127], v[144:147], v[184:187], v[124:127]
	v_mfma_f32_16x16x32_bf16 v[120:123], v[160:163], v[184:187], v[120:123]
	v_mfma_f32_16x16x32_bf16 v[108:111], v[144:147], v[192:195], v[108:111]
	v_mfma_f32_16x16x32_bf16 v[104:107], v[160:163], v[192:195], v[104:107]
	v_mfma_f32_16x16x32_bf16 v[92:95], v[144:147], v[200:203], v[92:95]
	v_mfma_f32_16x16x32_bf16 v[88:91], v[160:163], v[200:203], v[88:91]
	v_mfma_f32_16x16x32_bf16 v[76:79], v[144:147], v[212:215], v[76:79]
	v_mfma_f32_16x16x32_bf16 v[72:75], v[160:163], v[212:215], v[72:75]
	v_mfma_f32_16x16x32_bf16 v[116:119], v[164:167], v[180:183], v[116:119]
	v_mfma_f32_16x16x32_bf16 v[112:115], v[172:175], v[180:183], v[112:115]
	v_mfma_f32_16x16x32_bf16 v[100:103], v[164:167], v[188:191], v[100:103]
	v_mfma_f32_16x16x32_bf16 v[96:99], v[172:175], v[188:191], v[96:99]
	v_mfma_f32_16x16x32_bf16 v[84:87], v[164:167], v[196:199], v[84:87]
	v_mfma_f32_16x16x32_bf16 v[80:83], v[172:175], v[196:199], v[80:83]
	v_mfma_f32_16x16x32_bf16 v[68:71], v[164:167], v[208:211], v[68:71]
	v_mfma_f32_16x16x32_bf16 v[64:67], v[172:175], v[208:211], v[64:67]
	v_mfma_f32_16x16x32_bf16 v[116:119], v[168:171], v[184:187], v[116:119]
	v_mfma_f32_16x16x32_bf16 v[112:115], v[176:179], v[184:187], v[112:115]
	v_mfma_f32_16x16x32_bf16 v[100:103], v[168:171], v[192:195], v[100:103]
	v_mfma_f32_16x16x32_bf16 v[96:99], v[176:179], v[192:195], v[96:99]
	v_mfma_f32_16x16x32_bf16 v[84:87], v[168:171], v[200:203], v[84:87]
	v_mfma_f32_16x16x32_bf16 v[80:83], v[176:179], v[200:203], v[80:83]
	v_mfma_f32_16x16x32_bf16 v[68:71], v[168:171], v[212:215], v[68:71]
	v_mfma_f32_16x16x32_bf16 v[64:67], v[176:179], v[212:215], v[64:67]
	s_barrier
	s_add_i32 s62, s54, s45
	s_mov_b32 m0, s62
	s_nop 0
	global_load_lds_dwordx4 v128, s[38:39]
	s_add_i32 m0, s62, 0x2000
	s_add_u32 s62, s38, 0x40000
	s_mov_b64 s[98:99], s[38:39]
	s_addc_u32 s63, s39, 0
	s_add_i32 s64, s55, s45
	global_load_lds_dwordx4 v130, s[38:39]
	s_mov_b32 m0, s64
	s_mov_b64 s[100:101], s[40:41]
	global_load_lds_dwordx4 v128, s[62:63]
	s_add_i32 m0, s64, 0x2000
	s_nop 0
	global_load_lds_dwordx4 v130, s[62:63]
	ds_read_b128 v[180:183], v153 offset:16384
	ds_read_b128 v[184:187], v153 offset:17408
	ds_read_b128 v[188:191], v153 offset:18432
	ds_read_b128 v[192:195], v153 offset:19456
	ds_read_b128 v[196:199], v153 offset:20480
	ds_read_b128 v[200:203], v153 offset:21504
	ds_read_b128 v[208:211], v153 offset:22528
	ds_read_b128 v[212:215], v153 offset:23552
	s_waitcnt vmcnt(6)
	s_waitcnt lgkmcnt(0)
	s_barrier
	s_waitcnt lgkmcnt(0)
	v_mfma_f32_16x16x32_bf16 v[60:63], v[140:143], v[180:183], v[60:63]
	v_mfma_f32_16x16x32_bf16 v[56:59], v[156:159], v[180:183], v[56:59]
	v_mfma_f32_16x16x32_bf16 v[44:47], v[140:143], v[188:191], v[44:47]
	v_mfma_f32_16x16x32_bf16 v[40:43], v[156:159], v[188:191], v[40:43]
	v_mfma_f32_16x16x32_bf16 v[28:31], v[140:143], v[196:199], v[28:31]
	v_mfma_f32_16x16x32_bf16 v[24:27], v[156:159], v[196:199], v[24:27]
	v_mfma_f32_16x16x32_bf16 v[12:15], v[140:143], v[208:211], v[12:15]
	v_mfma_f32_16x16x32_bf16 v[8:11], v[156:159], v[208:211], v[8:11]
	v_mfma_f32_16x16x32_bf16 v[60:63], v[144:147], v[184:187], v[60:63]
	v_mfma_f32_16x16x32_bf16 v[56:59], v[160:163], v[184:187], v[56:59]
	v_mfma_f32_16x16x32_bf16 v[44:47], v[144:147], v[192:195], v[44:47]
	v_mfma_f32_16x16x32_bf16 v[40:43], v[160:163], v[192:195], v[40:43]
	v_mfma_f32_16x16x32_bf16 v[28:31], v[144:147], v[200:203], v[28:31]
	v_mfma_f32_16x16x32_bf16 v[24:27], v[160:163], v[200:203], v[24:27]
	v_mfma_f32_16x16x32_bf16 v[12:15], v[144:147], v[212:215], v[12:15]
	v_mfma_f32_16x16x32_bf16 v[8:11], v[160:163], v[212:215], v[8:11]
	v_mfma_f32_16x16x32_bf16 v[52:55], v[164:167], v[180:183], v[52:55]
	v_mfma_f32_16x16x32_bf16 v[48:51], v[172:175], v[180:183], v[48:51]
	v_mfma_f32_16x16x32_bf16 v[36:39], v[164:167], v[188:191], v[36:39]
	v_mfma_f32_16x16x32_bf16 v[32:35], v[172:175], v[188:191], v[32:35]
	v_mfma_f32_16x16x32_bf16 v[20:23], v[164:167], v[196:199], v[20:23]
	v_mfma_f32_16x16x32_bf16 v[16:19], v[172:175], v[196:199], v[16:19]
	v_mfma_f32_16x16x32_bf16 v[4:7], v[164:167], v[208:211], v[4:7]
	v_mfma_f32_16x16x32_bf16 v[0:3], v[172:175], v[208:211], v[0:3]
	v_mfma_f32_16x16x32_bf16 v[52:55], v[168:171], v[184:187], v[52:55]
	v_mfma_f32_16x16x32_bf16 v[48:51], v[176:179], v[184:187], v[48:51]
	v_mfma_f32_16x16x32_bf16 v[36:39], v[168:171], v[192:195], v[36:39]
	v_mfma_f32_16x16x32_bf16 v[32:35], v[176:179], v[192:195], v[32:35]
	v_mfma_f32_16x16x32_bf16 v[20:23], v[168:171], v[200:203], v[20:23]
	v_mfma_f32_16x16x32_bf16 v[16:19], v[176:179], v[200:203], v[16:19]
	v_mfma_f32_16x16x32_bf16 v[4:7], v[168:171], v[212:215], v[4:7]
	v_mfma_f32_16x16x32_bf16 v[0:3], v[176:179], v[212:215], v[0:3]
	s_barrier
	s_mov_b32 m0, s46
	s_nop 0
	global_load_lds_dwordx4 v128, s[40:41]
	s_mov_b32 m0, s47
	s_nop 0
	global_load_lds_dwordx4 v130, s[40:41]
	s_add_i32 s62, 0, 0x18000
	s_add_i32 s63, 0, 0x1c000
	s_add_u32 s40, s40, 0x40000
	s_addc_u32 s41, s41, 0
	s_mov_b32 m0, s48
	s_nop 0
	global_load_lds_dwordx4 v128, s[40:41]
	s_mov_b32 m0, s49
	s_nop 0
	global_load_lds_dwordx4 v130, s[40:41]
	v_add_u32_e32 v155, s62, v149
	ds_read_b128 v[140:143], v155
	ds_read_b128 v[144:147], v155 offset:1024
	ds_read_b128 v[156:159], v155 offset:2048
	ds_read_b128 v[160:163], v155 offset:3072
	v_add_u32_e32 v155, s63, v149
	ds_read_b128 v[164:167], v155
	ds_read_b128 v[168:171], v155 offset:1024
	ds_read_b128 v[172:175], v155 offset:2048
	ds_read_b128 v[176:179], v155 offset:3072
	ds_read_b128 v[180:183], v153 offset:32768
	ds_read_b128 v[184:187], v153 offset:33792
	ds_read_b128 v[188:191], v153 offset:34816
	ds_read_b128 v[192:195], v153 offset:35840
	ds_read_b128 v[196:199], v153 offset:36864
	ds_read_b128 v[200:203], v153 offset:37888
	ds_read_b128 v[208:211], v153 offset:38912
	ds_read_b128 v[212:215], v153 offset:39936
	s_waitcnt vmcnt(8)
	s_waitcnt lgkmcnt(0)
	s_barrier
	s_waitcnt lgkmcnt(0)
	v_mfma_f32_16x16x32_bf16 v[124:127], v[140:143], v[180:183], v[124:127]
	v_mfma_f32_16x16x32_bf16 v[120:123], v[156:159], v[180:183], v[120:123]
	v_mfma_f32_16x16x32_bf16 v[108:111], v[140:143], v[188:191], v[108:111]
	v_mfma_f32_16x16x32_bf16 v[104:107], v[156:159], v[188:191], v[104:107]
	v_mfma_f32_16x16x32_bf16 v[92:95], v[140:143], v[196:199], v[92:95]
	v_mfma_f32_16x16x32_bf16 v[88:91], v[156:159], v[196:199], v[88:91]
	v_mfma_f32_16x16x32_bf16 v[76:79], v[140:143], v[208:211], v[76:79]
	v_mfma_f32_16x16x32_bf16 v[72:75], v[156:159], v[208:211], v[72:75]
	v_mfma_f32_16x16x32_bf16 v[124:127], v[144:147], v[184:187], v[124:127]
	v_mfma_f32_16x16x32_bf16 v[120:123], v[160:163], v[184:187], v[120:123]
	v_mfma_f32_16x16x32_bf16 v[108:111], v[144:147], v[192:195], v[108:111]
	v_mfma_f32_16x16x32_bf16 v[104:107], v[160:163], v[192:195], v[104:107]
	v_mfma_f32_16x16x32_bf16 v[92:95], v[144:147], v[200:203], v[92:95]
	v_mfma_f32_16x16x32_bf16 v[88:91], v[160:163], v[200:203], v[88:91]
	v_mfma_f32_16x16x32_bf16 v[76:79], v[144:147], v[212:215], v[76:79]
	v_mfma_f32_16x16x32_bf16 v[72:75], v[160:163], v[212:215], v[72:75]
	v_mfma_f32_16x16x32_bf16 v[116:119], v[164:167], v[180:183], v[116:119]
	v_mfma_f32_16x16x32_bf16 v[112:115], v[172:175], v[180:183], v[112:115]
	v_mfma_f32_16x16x32_bf16 v[100:103], v[164:167], v[188:191], v[100:103]
	v_mfma_f32_16x16x32_bf16 v[96:99], v[172:175], v[188:191], v[96:99]
	v_mfma_f32_16x16x32_bf16 v[84:87], v[164:167], v[196:199], v[84:87]
	v_mfma_f32_16x16x32_bf16 v[80:83], v[172:175], v[196:199], v[80:83]
	v_mfma_f32_16x16x32_bf16 v[68:71], v[164:167], v[208:211], v[68:71]
	v_mfma_f32_16x16x32_bf16 v[64:67], v[172:175], v[208:211], v[64:67]
	v_mfma_f32_16x16x32_bf16 v[116:119], v[168:171], v[184:187], v[116:119]
	v_mfma_f32_16x16x32_bf16 v[112:115], v[176:179], v[184:187], v[112:115]
	v_mfma_f32_16x16x32_bf16 v[100:103], v[168:171], v[192:195], v[100:103]
	v_mfma_f32_16x16x32_bf16 v[96:99], v[176:179], v[192:195], v[96:99]
	v_mfma_f32_16x16x32_bf16 v[84:87], v[168:171], v[200:203], v[84:87]
	v_mfma_f32_16x16x32_bf16 v[80:83], v[176:179], v[200:203], v[80:83]
	v_mfma_f32_16x16x32_bf16 v[68:71], v[168:171], v[212:215], v[68:71]
	v_mfma_f32_16x16x32_bf16 v[64:67], v[176:179], v[212:215], v[64:67]
	s_barrier
	s_add_i32 s40, s62, s45
	s_mov_b32 m0, s40
	s_nop 0
	global_load_lds_dwordx4 v204, s[38:39]
	s_add_i32 m0, s40, 0x2000
	s_add_u32 s38, s38, 0x40080
	s_addc_u32 s39, s39, 0
	s_add_i32 s40, s63, s45
	global_load_lds_dwordx4 v205, s[98:99]
	s_mov_b32 m0, s40
	s_nop 0
	global_load_lds_dwordx4 v128, s[38:39]
	s_add_i32 m0, s40, 0x2000
	s_nop 0
	global_load_lds_dwordx4 v130, s[38:39]
	s_cmp_lg_u32 s61, 12
	s_cbranch_scc1 .Lbal_last_11
	s_mov_b32 m0, s51
	s_nop 0
	global_load_lds_dwordx4 v204, s[100:101]
	s_mov_b32 m0, s52
	s_nop 0
	global_load_lds_dwordx4 v205, s[100:101]
.Lbal_last_11:
	ds_read_b128 v[180:183], v153 offset:49152
	ds_read_b128 v[184:187], v153 offset:50176
	ds_read_b128 v[188:191], v153 offset:51200
	ds_read_b128 v[192:195], v153 offset:52224
	ds_read_b128 v[196:199], v153 offset:53248
	ds_read_b128 v[200:203], v153 offset:54272
	ds_read_b128 v[208:211], v153 offset:55296
	ds_read_b128 v[212:215], v153 offset:56320
	s_waitcnt vmcnt(6)
	s_waitcnt lgkmcnt(0)
	s_barrier
	s_waitcnt lgkmcnt(0)
	v_mfma_f32_16x16x32_bf16 v[60:63], v[140:143], v[180:183], v[60:63]
	v_mfma_f32_16x16x32_bf16 v[56:59], v[156:159], v[180:183], v[56:59]
	v_mfma_f32_16x16x32_bf16 v[44:47], v[140:143], v[188:191], v[44:47]
	v_mfma_f32_16x16x32_bf16 v[40:43], v[156:159], v[188:191], v[40:43]
	v_mfma_f32_16x16x32_bf16 v[28:31], v[140:143], v[196:199], v[28:31]
	v_mfma_f32_16x16x32_bf16 v[24:27], v[156:159], v[196:199], v[24:27]
	v_mfma_f32_16x16x32_bf16 v[12:15], v[140:143], v[208:211], v[12:15]
	v_mfma_f32_16x16x32_bf16 v[8:11], v[156:159], v[208:211], v[8:11]
	v_mfma_f32_16x16x32_bf16 v[60:63], v[144:147], v[184:187], v[60:63]
	v_mfma_f32_16x16x32_bf16 v[56:59], v[160:163], v[184:187], v[56:59]
	v_mfma_f32_16x16x32_bf16 v[44:47], v[144:147], v[192:195], v[44:47]
	v_mfma_f32_16x16x32_bf16 v[40:43], v[160:163], v[192:195], v[40:43]
	v_mfma_f32_16x16x32_bf16 v[28:31], v[144:147], v[200:203], v[28:31]
	v_mfma_f32_16x16x32_bf16 v[24:27], v[160:163], v[200:203], v[24:27]
	v_mfma_f32_16x16x32_bf16 v[12:15], v[144:147], v[212:215], v[12:15]
	v_mfma_f32_16x16x32_bf16 v[8:11], v[160:163], v[212:215], v[8:11]
	v_mfma_f32_16x16x32_bf16 v[52:55], v[164:167], v[180:183], v[52:55]
	v_mfma_f32_16x16x32_bf16 v[48:51], v[172:175], v[180:183], v[48:51]
	v_mfma_f32_16x16x32_bf16 v[36:39], v[164:167], v[188:191], v[36:39]
	v_mfma_f32_16x16x32_bf16 v[32:35], v[172:175], v[188:191], v[32:35]
	v_mfma_f32_16x16x32_bf16 v[20:23], v[164:167], v[196:199], v[20:23]
	v_mfma_f32_16x16x32_bf16 v[16:19], v[172:175], v[196:199], v[16:19]
	v_mfma_f32_16x16x32_bf16 v[4:7], v[164:167], v[208:211], v[4:7]
	v_mfma_f32_16x16x32_bf16 v[0:3], v[172:175], v[208:211], v[0:3]
	v_mfma_f32_16x16x32_bf16 v[52:55], v[168:171], v[184:187], v[52:55]
	v_mfma_f32_16x16x32_bf16 v[48:51], v[176:179], v[184:187], v[48:51]
	v_mfma_f32_16x16x32_bf16 v[36:39], v[168:171], v[192:195], v[36:39]
	v_mfma_f32_16x16x32_bf16 v[32:35], v[176:179], v[192:195], v[32:35]
	v_mfma_f32_16x16x32_bf16 v[20:23], v[168:171], v[200:203], v[20:23]
	v_mfma_f32_16x16x32_bf16 v[16:19], v[176:179], v[200:203], v[16:19]
	v_mfma_f32_16x16x32_bf16 v[4:7], v[168:171], v[212:215], v[4:7]
	v_mfma_f32_16x16x32_bf16 v[0:3], v[176:179], v[212:215], v[0:3]
	s_barrier
	s_add_i32 s61, s61, 2
	s_add_u32 s59, s59, 0x100
	s_addc_u32 s60, s60, 0
	s_add_u32 s36, s36, 0x100
	s_addc_u32 s37, s37, 0
	s_cmp_gt_u32 s61, 13
	s_cbranch_scc0 .LBB0_1561
	s_setprio 0
	s_and_b64 vcc, exec, s[24:25]
	s_cbranch_vccz .LBB0_1564
	s_barrier

.Lbal_first_10:
	s_add_u32 s26, s24, 0xfffc0080
	s_addc_u32 s27, s25, -1
	s_cmp_eq_u32 s54, 12
	s_cselect_b32 s29, s19, s27
	s_cselect_b32 s28, s50, s26
	s_cselect_b32 s27, s17, s53
	s_cselect_b32 s26, s51, s52
	s_add_i32 m0, s38, 0xc000
	s_nop 0
	global_load_lds_dwordx4 v138, s[24:25]
	s_add_i32 m0, s38, 0xe000
	s_nop 0
	global_load_lds_dwordx4 v136, s[24:25]
	ds_read_b128 v[144:147], v151
	ds_read_b128 v[156:159], v151 offset:1024
	ds_read_b128 v[160:163], v151 offset:2048
	ds_read_b128 v[164:167], v151 offset:3072
	ds_read_b128 v[168:171], v152
	ds_read_b128 v[172:175], v152 offset:1024
	ds_read_b128 v[176:179], v152 offset:2048
	ds_read_b128 v[180:183], v152 offset:3072
	ds_read_b128 v[184:187], v153
	ds_read_b128 v[188:191], v153 offset:1024
	ds_read_b128 v[192:195], v153 offset:2048
	ds_read_b128 v[196:199], v153 offset:3072
	ds_read_b128 v[200:203], v153 offset:4096
	ds_read_b128 v[208:211], v153 offset:5120
	ds_read_b128 v[212:215], v153 offset:6144
	ds_read_b128 v[216:219], v153 offset:7168
	s_waitcnt vmcnt(8)
	s_waitcnt lgkmcnt(0)
	s_barrier
	s_waitcnt lgkmcnt(0)
	v_mfma_f32_16x16x32_bf16 v[124:127], v[144:147], v[184:187], v[124:127]
	v_mfma_f32_16x16x32_bf16 v[120:123], v[160:163], v[184:187], v[120:123]
	v_mfma_f32_16x16x32_bf16 v[108:111], v[144:147], v[192:195], v[108:111]
	v_mfma_f32_16x16x32_bf16 v[104:107], v[160:163], v[192:195], v[104:107]
	v_mfma_f32_16x16x32_bf16 v[92:95], v[144:147], v[200:203], v[92:95]
	v_mfma_f32_16x16x32_bf16 v[88:91], v[160:163], v[200:203], v[88:91]
	v_mfma_f32_16x16x32_bf16 v[76:79], v[144:147], v[212:215], v[76:79]
	v_mfma_f32_16x16x32_bf16 v[72:75], v[160:163], v[212:215], v[72:75]
	v_mfma_f32_16x16x32_bf16 v[124:127], v[156:159], v[188:191], v[124:127]
	v_mfma_f32_16x16x32_bf16 v[120:123], v[164:167], v[188:191], v[120:123]
	v_mfma_f32_16x16x32_bf16 v[108:111], v[156:159], v[196:199], v[108:111]
	v_mfma_f32_16x16x32_bf16 v[104:107], v[164:167], v[196:199], v[104:107]
	v_mfma_f32_16x16x32_bf16 v[92:95], v[156:159], v[208:211], v[92:95]
	v_mfma_f32_16x16x32_bf16 v[88:91], v[164:167], v[208:211], v[88:91]
	v_mfma_f32_16x16x32_bf16 v[76:79], v[156:159], v[216:219], v[76:79]
	v_mfma_f32_16x16x32_bf16 v[72:75], v[164:167], v[216:219], v[72:75]
	v_mfma_f32_16x16x32_bf16 v[116:119], v[168:171], v[184:187], v[116:119]
	v_mfma_f32_16x16x32_bf16 v[112:115], v[176:179], v[184:187], v[112:115]
	v_mfma_f32_16x16x32_bf16 v[100:103], v[168:171], v[192:195], v[100:103]
	v_mfma_f32_16x16x32_bf16 v[96:99], v[176:179], v[192:195], v[96:99]
	v_mfma_f32_16x16x32_bf16 v[84:87], v[168:171], v[200:203], v[84:87]
	v_mfma_f32_16x16x32_bf16 v[80:83], v[176:179], v[200:203], v[80:83]
	v_mfma_f32_16x16x32_bf16 v[68:71], v[168:171], v[212:215], v[68:71]
	v_mfma_f32_16x16x32_bf16 v[64:67], v[176:179], v[212:215], v[64:67]
	v_mfma_f32_16x16x32_bf16 v[116:119], v[172:175], v[188:191], v[116:119]
	v_mfma_f32_16x16x32_bf16 v[112:115], v[180:183], v[188:191], v[112:115]
	v_mfma_f32_16x16x32_bf16 v[100:103], v[172:175], v[196:199], v[100:103]
	v_mfma_f32_16x16x32_bf16 v[96:99], v[180:183], v[196:199], v[96:99]
	v_mfma_f32_16x16x32_bf16 v[84:87], v[172:175], v[208:211], v[84:87]
	v_mfma_f32_16x16x32_bf16 v[80:83], v[180:183], v[208:211], v[80:83]
	v_mfma_f32_16x16x32_bf16 v[68:71], v[172:175], v[216:219], v[68:71]
	v_mfma_f32_16x16x32_bf16 v[64:67], v[180:183], v[216:219], v[64:67]
	s_barrier
	s_add_i32 s55, s47, s35
	s_mov_b32 m0, s55
	s_nop 0
	global_load_lds_dwordx4 v132, s[26:27]
	s_add_i32 m0, s55, 0x2000
	s_add_u32 s56, s26, 0x40000
	s_mov_b64 s[98:99], s[26:27]
	s_addc_u32 s57, s27, 0
	s_add_i32 s55, s48, s35
	global_load_lds_dwordx4 v128, s[26:27]
	s_mov_b32 m0, s55
	s_mov_b64 s[100:101], s[28:29]
	global_load_lds_dwordx4 v132, s[56:57]
	s_add_i32 m0, s55, 0x2000
	s_nop 0
	global_load_lds_dwordx4 v128, s[56:57]
	ds_read_b128 v[184:187], v153 offset:16384
	ds_read_b128 v[188:191], v153 offset:17408
	ds_read_b128 v[192:195], v153 offset:18432
	ds_read_b128 v[196:199], v153 offset:19456
	ds_read_b128 v[200:203], v153 offset:20480
	ds_read_b128 v[208:211], v153 offset:21504
	ds_read_b128 v[212:215], v153 offset:22528
	ds_read_b128 v[216:219], v153 offset:23552
	s_waitcnt vmcnt(6)
	s_waitcnt lgkmcnt(0)
	s_barrier
	s_waitcnt lgkmcnt(0)
	v_mfma_f32_16x16x32_bf16 v[60:63], v[144:147], v[184:187], v[60:63]
	v_mfma_f32_16x16x32_bf16 v[56:59], v[160:163], v[184:187], v[56:59]
	v_mfma_f32_16x16x32_bf16 v[44:47], v[144:147], v[192:195], v[44:47]
	v_mfma_f32_16x16x32_bf16 v[40:43], v[160:163], v[192:195], v[40:43]
	v_mfma_f32_16x16x32_bf16 v[28:31], v[144:147], v[200:203], v[28:31]
	v_mfma_f32_16x16x32_bf16 v[24:27], v[160:163], v[200:203], v[24:27]
	v_mfma_f32_16x16x32_bf16 v[12:15], v[144:147], v[212:215], v[12:15]
	v_mfma_f32_16x16x32_bf16 v[8:11], v[160:163], v[212:215], v[8:11]
	v_mfma_f32_16x16x32_bf16 v[60:63], v[156:159], v[188:191], v[60:63]
	v_mfma_f32_16x16x32_bf16 v[56:59], v[164:167], v[188:191], v[56:59]
	v_mfma_f32_16x16x32_bf16 v[44:47], v[156:159], v[196:199], v[44:47]
	v_mfma_f32_16x16x32_bf16 v[40:43], v[164:167], v[196:199], v[40:43]
	v_mfma_f32_16x16x32_bf16 v[28:31], v[156:159], v[208:211], v[28:31]
	v_mfma_f32_16x16x32_bf16 v[24:27], v[164:167], v[208:211], v[24:27]
	v_mfma_f32_16x16x32_bf16 v[12:15], v[156:159], v[216:219], v[12:15]
	v_mfma_f32_16x16x32_bf16 v[8:11], v[164:167], v[216:219], v[8:11]
	v_mfma_f32_16x16x32_bf16 v[52:55], v[168:171], v[184:187], v[52:55]
	v_mfma_f32_16x16x32_bf16 v[48:51], v[176:179], v[184:187], v[48:51]
	v_mfma_f32_16x16x32_bf16 v[36:39], v[168:171], v[192:195], v[36:39]
	v_mfma_f32_16x16x32_bf16 v[32:35], v[176:179], v[192:195], v[32:35]
	v_mfma_f32_16x16x32_bf16 v[20:23], v[168:171], v[200:203], v[20:23]
	v_mfma_f32_16x16x32_bf16 v[16:19], v[176:179], v[200:203], v[16:19]
	v_mfma_f32_16x16x32_bf16 v[4:7], v[168:171], v[212:215], v[4:7]
	v_mfma_f32_16x16x32_bf16 v[0:3], v[176:179], v[212:215], v[0:3]
	v_mfma_f32_16x16x32_bf16 v[52:55], v[172:175], v[188:191], v[52:55]
	v_mfma_f32_16x16x32_bf16 v[48:51], v[180:183], v[188:191], v[48:51]
	v_mfma_f32_16x16x32_bf16 v[36:39], v[172:175], v[196:199], v[36:39]
	v_mfma_f32_16x16x32_bf16 v[32:35], v[180:183], v[196:199], v[32:35]
	v_mfma_f32_16x16x32_bf16 v[20:23], v[172:175], v[208:211], v[20:23]
	v_mfma_f32_16x16x32_bf16 v[16:19], v[180:183], v[208:211], v[16:19]
	v_mfma_f32_16x16x32_bf16 v[4:7], v[172:175], v[216:219], v[4:7]
	v_mfma_f32_16x16x32_bf16 v[0:3], v[180:183], v[216:219], v[0:3]
	s_barrier
	s_mov_b32 m0, s38
	s_nop 0
	global_load_lds_dwordx4 v134, s[28:29]
	s_mov_b32 m0, s39
	s_nop 0
	global_load_lds_dwordx4 v130, s[28:29]
	s_add_i32 s55, 0, 0x18000
	s_add_i32 s56, 0, 0x1c000
	s_add_u32 s28, s28, 0x40000
	s_addc_u32 s29, s29, 0
	s_mov_b32 m0, s40
	s_nop 0
	global_load_lds_dwordx4 v134, s[28:29]
	s_mov_b32 m0, s41
	s_nop 0
	global_load_lds_dwordx4 v130, s[28:29]
	v_add_u32_e32 v164, s55, v149
	v_add_u32_e32 v180, s56, v149
	ds_read_b128 v[144:147], v164
	ds_read_b128 v[156:159], v164 offset:1024
	ds_read_b128 v[160:163], v164 offset:2048
	ds_read_b128 v[164:167], v164 offset:3072
	ds_read_b128 v[168:171], v180
	ds_read_b128 v[172:175], v180 offset:1024
	ds_read_b128 v[176:179], v180 offset:2048
	ds_read_b128 v[180:183], v180 offset:3072
	ds_read_b128 v[184:187], v153 offset:32768
	ds_read_b128 v[188:191], v153 offset:33792
	ds_read_b128 v[192:195], v153 offset:34816
	ds_read_b128 v[196:199], v153 offset:35840
	ds_read_b128 v[200:203], v153 offset:36864
	ds_read_b128 v[208:211], v153 offset:37888
	ds_read_b128 v[212:215], v153 offset:38912
	ds_read_b128 v[216:219], v153 offset:39936
	s_waitcnt vmcnt(8)
	s_waitcnt lgkmcnt(0)
	s_barrier
	s_waitcnt lgkmcnt(0)
	v_mfma_f32_16x16x32_bf16 v[124:127], v[144:147], v[184:187], v[124:127]
	v_mfma_f32_16x16x32_bf16 v[120:123], v[160:163], v[184:187], v[120:123]
	v_mfma_f32_16x16x32_bf16 v[108:111], v[144:147], v[192:195], v[108:111]
	v_mfma_f32_16x16x32_bf16 v[104:107], v[160:163], v[192:195], v[104:107]
	v_mfma_f32_16x16x32_bf16 v[92:95], v[144:147], v[200:203], v[92:95]
	v_mfma_f32_16x16x32_bf16 v[88:91], v[160:163], v[200:203], v[88:91]
	v_mfma_f32_16x16x32_bf16 v[76:79], v[144:147], v[212:215], v[76:79]
	v_mfma_f32_16x16x32_bf16 v[72:75], v[160:163], v[212:215], v[72:75]
	v_mfma_f32_16x16x32_bf16 v[124:127], v[156:159], v[188:191], v[124:127]
	v_mfma_f32_16x16x32_bf16 v[120:123], v[164:167], v[188:191], v[120:123]
	v_mfma_f32_16x16x32_bf16 v[108:111], v[156:159], v[196:199], v[108:111]
	v_mfma_f32_16x16x32_bf16 v[104:107], v[164:167], v[196:199], v[104:107]
	v_mfma_f32_16x16x32_bf16 v[92:95], v[156:159], v[208:211], v[92:95]
	v_mfma_f32_16x16x32_bf16 v[88:91], v[164:167], v[208:211], v[88:91]
	v_mfma_f32_16x16x32_bf16 v[76:79], v[156:159], v[216:219], v[76:79]
	v_mfma_f32_16x16x32_bf16 v[72:75], v[164:167], v[216:219], v[72:75]
	v_mfma_f32_16x16x32_bf16 v[116:119], v[168:171], v[184:187], v[116:119]
	v_mfma_f32_16x16x32_bf16 v[112:115], v[176:179], v[184:187], v[112:115]
	v_mfma_f32_16x16x32_bf16 v[100:103], v[168:171], v[192:195], v[100:103]
	v_mfma_f32_16x16x32_bf16 v[96:99], v[176:179], v[192:195], v[96:99]
	v_mfma_f32_16x16x32_bf16 v[84:87], v[168:171], v[200:203], v[84:87]
	v_mfma_f32_16x16x32_bf16 v[80:83], v[176:179], v[200:203], v[80:83]
	v_mfma_f32_16x16x32_bf16 v[68:71], v[168:171], v[212:215], v[68:71]
	v_mfma_f32_16x16x32_bf16 v[64:67], v[176:179], v[212:215], v[64:67]
	v_mfma_f32_16x16x32_bf16 v[116:119], v[172:175], v[188:191], v[116:119]
	v_mfma_f32_16x16x32_bf16 v[112:115], v[180:183], v[188:191], v[112:115]
	v_mfma_f32_16x16x32_bf16 v[100:103], v[172:175], v[196:199], v[100:103]
	v_mfma_f32_16x16x32_bf16 v[96:99], v[180:183], v[196:199], v[96:99]
	v_mfma_f32_16x16x32_bf16 v[84:87], v[172:175], v[208:211], v[84:87]
	v_mfma_f32_16x16x32_bf16 v[80:83], v[180:183], v[208:211], v[80:83]
	v_mfma_f32_16x16x32_bf16 v[68:71], v[172:175], v[216:219], v[68:71]
	v_mfma_f32_16x16x32_bf16 v[64:67], v[180:183], v[216:219], v[64:67]
	s_barrier
	s_add_i32 s28, s55, s35
	s_mov_b32 m0, s28
	s_nop 0
	global_load_lds_dwordx4 v220, s[26:27]
	s_add_i32 m0, s28, 0x2000
	s_add_u32 s26, s26, 0x40080
	s_addc_u32 s27, s27, 0
	s_add_i32 s28, s56, s35
	global_load_lds_dwordx4 v204, s[98:99]
	s_mov_b32 m0, s28
	s_nop 0
	global_load_lds_dwordx4 v132, s[26:27]
	s_add_i32 m0, s28, 0x2000
	s_nop 0
	global_load_lds_dwordx4 v128, s[26:27]
	s_cmp_lg_u32 s54, 12
	s_cbranch_scc1 .Lbal_last_10
	s_mov_b32 m0, s45
	s_nop 0
	global_load_lds_dwordx4 v221, s[100:101]
	s_mov_b32 m0, s46
	s_nop 0
	global_load_lds_dwordx4 v205, s[100:101]
.Lbal_last_10:
	ds_read_b128 v[184:187], v153 offset:49152
	ds_read_b128 v[188:191], v153 offset:50176
	ds_read_b128 v[192:195], v153 offset:51200
	ds_read_b128 v[196:199], v153 offset:52224
	ds_read_b128 v[200:203], v153 offset:53248
	ds_read_b128 v[208:211], v153 offset:54272
	ds_read_b128 v[212:215], v153 offset:55296
	ds_read_b128 v[216:219], v153 offset:56320
	s_waitcnt vmcnt(6)
	s_waitcnt lgkmcnt(0)
	s_barrier
	s_waitcnt lgkmcnt(0)
	v_mfma_f32_16x16x32_bf16 v[60:63], v[144:147], v[184:187], v[60:63]
	v_mfma_f32_16x16x32_bf16 v[56:59], v[160:163], v[184:187], v[56:59]
	v_mfma_f32_16x16x32_bf16 v[44:47], v[144:147], v[192:195], v[44:47]
	v_mfma_f32_16x16x32_bf16 v[40:43], v[160:163], v[192:195], v[40:43]
	v_mfma_f32_16x16x32_bf16 v[28:31], v[144:147], v[200:203], v[28:31]
	v_mfma_f32_16x16x32_bf16 v[24:27], v[160:163], v[200:203], v[24:27]
	v_mfma_f32_16x16x32_bf16 v[12:15], v[144:147], v[212:215], v[12:15]
	v_mfma_f32_16x16x32_bf16 v[8:11], v[160:163], v[212:215], v[8:11]
	v_mfma_f32_16x16x32_bf16 v[60:63], v[156:159], v[188:191], v[60:63]
	v_mfma_f32_16x16x32_bf16 v[56:59], v[164:167], v[188:191], v[56:59]
	v_mfma_f32_16x16x32_bf16 v[44:47], v[156:159], v[196:199], v[44:47]
	v_mfma_f32_16x16x32_bf16 v[40:43], v[164:167], v[196:199], v[40:43]
	v_mfma_f32_16x16x32_bf16 v[28:31], v[156:159], v[208:211], v[28:31]
	v_mfma_f32_16x16x32_bf16 v[24:27], v[164:167], v[208:211], v[24:27]
	v_mfma_f32_16x16x32_bf16 v[12:15], v[156:159], v[216:219], v[12:15]
	v_mfma_f32_16x16x32_bf16 v[8:11], v[164:167], v[216:219], v[8:11]
	v_mfma_f32_16x16x32_bf16 v[52:55], v[168:171], v[184:187], v[52:55]
	v_mfma_f32_16x16x32_bf16 v[48:51], v[176:179], v[184:187], v[48:51]
	v_mfma_f32_16x16x32_bf16 v[36:39], v[168:171], v[192:195], v[36:39]
	v_mfma_f32_16x16x32_bf16 v[32:35], v[176:179], v[192:195], v[32:35]
	v_mfma_f32_16x16x32_bf16 v[20:23], v[168:171], v[200:203], v[20:23]
	v_mfma_f32_16x16x32_bf16 v[16:19], v[176:179], v[200:203], v[16:19]
	v_mfma_f32_16x16x32_bf16 v[4:7], v[168:171], v[212:215], v[4:7]
	v_mfma_f32_16x16x32_bf16 v[0:3], v[176:179], v[212:215], v[0:3]
	v_mfma_f32_16x16x32_bf16 v[52:55], v[172:175], v[188:191], v[52:55]
	v_mfma_f32_16x16x32_bf16 v[48:51], v[180:183], v[188:191], v[48:51]
	v_mfma_f32_16x16x32_bf16 v[36:39], v[172:175], v[196:199], v[36:39]
	v_mfma_f32_16x16x32_bf16 v[32:35], v[180:183], v[196:199], v[32:35]
	v_mfma_f32_16x16x32_bf16 v[20:23], v[172:175], v[208:211], v[20:23]
	v_mfma_f32_16x16x32_bf16 v[16:19], v[180:183], v[208:211], v[16:19]
	v_mfma_f32_16x16x32_bf16 v[4:7], v[172:175], v[216:219], v[4:7]
	v_mfma_f32_16x16x32_bf16 v[0:3], v[180:183], v[216:219], v[0:3]
	s_barrier
	s_add_i32 s54, s54, 2
	s_add_u32 s52, s52, 0x100
	s_addc_u32 s53, s53, 0
	s_add_u32 s24, s24, 0x100
	s_addc_u32 s25, s25, 0
	s_cmp_gt_u32 s54, 13
	s_cbranch_scc0 .LBB0_1646
	s_setprio 0
	s_and_b64 vcc, exec, s[14:15]
	s_cbranch_vccz .LBB0_1649
	s_barrier
